# toeplitz: filter rows copied to LDS with 9 loads in flight instead of load-wait-write per 16B; next-group data wait moved to end of K trip
# baseline (speedup 1.0000x reference)
;   DI int item(int i) const { const int li = j + i * nxb; if (li >= per) return -1; const int lin = xcd * per + li; return lin < total ? lin : -1; }
; template <int MODE, int TB>
; DI void toeplitz_task(const Params& P, int layer, int set, int cg, int chunk, char* smem) {
;     ...
;   const h16* krg = (const h16*)(P.ws + (set ? WS_KRC : WS_KRL)) + (size_t)(MODE * 512 + cg * 8) * KLEN;
;   h16* krs = (h16*)smem;
;   char* stg = smem + 8 * KLEN_L * 2;
;   for (int i = tid; i < KLEN; i += 512) *(half8*)(krs + i * 8) = *(const half8*)(krg + i * 8);
;   __syncthreads();
; template <int MODE>
; DI void phase_toeplitz(const Params& P, int layer, char* smem) {
;     ...
;   for (int item = blockIdx.x; item < total; item += gridDim.x) {
;     if (item < 256) {
;       const int xj = item >> 3;
;       toeplitz_task<MODE, 4>(P, layer, 0, (item & 7) + 8 * (xj >> 2), xj & 3, smem);
.LBB0_399:
	s_and_b64 vcc, exec, s[2:3]
	s_cbranch_vccz .LBB0_393
	s_lshr_b32 s3, s45, 2
	s_and_b32 s2, s45, 7
	s_and_b32 s3, s3, 0x1ffffff8
	s_or_b32 s2, s3, s2
	v_mov_b32_e32 v157, v208
	s_lshl_b32 s38, s2, 3
	s_movk_i32 s2, 0x1100
	s_nop 0
	v_cmp_gt_i32_e32 vcc, s2, v157
	s_and_saveexec_b64 s[2:3], vcc
	s_cbranch_execz .LBB0_403
	s_add_i32 s24, s38, 0x200
	s_mul_hi_i32 s25, s24, 0x2200
	s_mulk_i32 s24, 0x2200
	v_readlane_b32 s33, v253, 47
	s_add_u32 s40, s33, s24
	v_readlane_b32 s24, v253, 48
	s_addc_u32 s41, s24, s25
	v_add_u32_e32 v2, 0xfffffe00, v157
	v_lshl_add_u32 v3, v157, 4, 0
	v_lshlrev_b32_e32 v0, 3, v157
	s_mov_b64 s[42:43], 0x2000
	v_ashrrev_i32_e32 v1, 31, v0
	v_lshl_add_u64 v[4:5], v[0:1], 1, s[40:41]
	global_load_dwordx4 v[12:15], v[4:5], off
	v_lshl_add_u64 v[4:5], v[4:5], 0, s[42:43]
	global_load_dwordx4 v[16:19], v[4:5], off
	v_lshl_add_u64 v[4:5], v[4:5], 0, s[42:43]
	global_load_dwordx4 v[20:23], v[4:5], off
	v_lshl_add_u64 v[4:5], v[4:5], 0, s[42:43]
	global_load_dwordx4 v[24:27], v[4:5], off
	v_lshl_add_u64 v[4:5], v[4:5], 0, s[42:43]
	global_load_dwordx4 v[28:31], v[4:5], off
	v_lshl_add_u64 v[4:5], v[4:5], 0, s[42:43]
	global_load_dwordx4 v[32:35], v[4:5], off
	v_lshl_add_u64 v[4:5], v[4:5], 0, s[42:43]
	global_load_dwordx4 v[36:39], v[4:5], off
	v_lshl_add_u64 v[4:5], v[4:5], 0, s[42:43]
	global_load_dwordx4 v[40:43], v[4:5], off
	v_lshl_add_u64 v[4:5], v[4:5], 0, s[42:43]
	global_load_dwordx4 v[44:47], v[4:5], off
	v_add_u32_e32 v2, 0x10000, v3
	v_cmp_gt_u32_e32 vcc, 0x100, v157
	s_waitcnt vmcnt(8)
	ds_write_b128 v3, v[12:15]
	s_waitcnt vmcnt(7)
	ds_write_b128 v3, v[16:19] offset:8192
	s_waitcnt vmcnt(6)
	ds_write_b128 v3, v[20:23] offset:16384
	s_waitcnt vmcnt(5)
	ds_write_b128 v3, v[24:27] offset:24576
	s_waitcnt vmcnt(4)
	ds_write_b128 v3, v[28:31] offset:32768
	s_waitcnt vmcnt(3)
	ds_write_b128 v3, v[32:35] offset:40960
	s_waitcnt vmcnt(2)
	ds_write_b128 v3, v[36:39] offset:49152
	s_waitcnt vmcnt(1)
	ds_write_b128 v3, v[40:43] offset:57344
	s_waitcnt vmcnt(0)
	s_and_saveexec_b64 s[42:43], vcc
	ds_write_b128 v2, v[44:47]
	s_mov_b64 exec, s[42:43]

; template <int MODE, int TB>
; DI void toeplitz_task(const Params& P, int layer, int set, int cg, int chunk, char* smem) {
;     ...
;     auto load_group = [&](int g, u32x4 (&dst)[2 * GS]) {
; #pragma unroll
;       for (int q = 0; q < GS; ++q) {
;         const int s = -32 + (g * GS + q) * 32 + 8 * kg;
;         const int s2 = s + 8;
;         const int sc = min(max(s, 0), L - 8), sc2 = min(max(s2, 0), L - 8);
;         dst[2 * q] = *(const u32x4*)(Urow + sc);
;         dst[2 * q + 1] = *(const u32x4*)(Urow + sc2);
;       }
;     };
;     load_group(0, cur);
;     const int abase = OFF - tb - 8 * ((lane & 15) - kg);
;     half8 afn[TB];
; #pragma unroll
;     for (int ta = 0; ta < TB; ++ta) afn[ta] = *(const half8*)(krw + abase - 32 - 128 * ta);
;     for (int g = 0; g < ngroups; ++g) {
;       load_group(g + 1 < ngroups ? g + 1 : g, nxt);
;       __builtin_amdgcn_sched_barrier(0);
; #pragma unroll
;       for (int q = 0; q < GS; ++q) {
;         const int s0 = -32 + (g * GS + q) * 32;
;         half8 af[TB];
; #pragma unroll
;         for (int ta = 0; ta < TB; ++ta) { af[ta] = afn[ta]; afn[ta] = *(const half8*)(krw + abase + s0 + 32 - 128 * ta); }
;         unsigned d[8];
;         {
;           const int sw0 = s0 + 8 * kg, sw1 = sw0 + 8;
;           const bool va = (sw0 >= 0) && (sw0 < L), vb = (sw1 >= 0) && (sw1 < L);
; #pragma unroll
;           for (int e = 0; e < 4; ++e) { d[e] = va ? cur[2 * q][e] : 0u; d[4 + e] = vb ? cur[2 * q + 1][e] : 0u; }
;         }
; #pragma unroll
;         for (int r = 0; r < 8; ++r) {
;           u32x4 bw;
; #pragma unroll
;           for (int e = 0; e < 4; ++e)
;             bw[e] = (r & 1) ? __builtin_amdgcn_alignbit(d[(r >> 1) + e + 1 > 7 ? 7 : (r >> 1) + e + 1], d[(r >> 1) + e], 16) : d[(r >> 1) + e];
;           const half8 bfr = __builtin_bit_cast(half8, bw);
; #pragma unroll
;           for (int ta = 0; ta < TB; ++ta) acc[ta][r] = __builtin_amdgcn_mfma_f32_16x16x32_f16(af[ta], bfr, acc[ta][r], 0, 0, 0);
;         }
.LBB0_404:
	s_waitcnt vmcnt(3)
	v_mov_b64_e32 v[168:169], v[2:3]
	v_mov_b64_e32 v[166:167], v[0:1]
	v_subrev_u32_e32 v0, 32, v164
	v_min_u32_e32 v0, 0x7f0, v0
	v_min_u32_e32 v2, 0x7f8, v164
	v_lshlrev_b32_e32 v128, 1, v0
	v_min_u32_e32 v3, 0x7f0, v164
	v_lshl_add_u64 v[0:1], v[150:151], 0, v[128:129]
	v_lshlrev_b32_e32 v128, 1, v2
	v_lshl_add_u64 v[170:171], v[150:151], 0, v[128:129]
	v_lshlrev_b32_e32 v128, 1, v3
	global_load_dwordx4 v[142:145], v[154:155], off
	s_nop 0
	global_load_dwordx4 v[0:3], v[0:1], off offset:16
	s_nop 0
	global_load_dwordx4 v[170:173], v[170:171], off
	v_lshl_add_u64 v[174:175], v[150:151], 0, v[128:129]
	global_load_dwordx4 v[174:177], v[174:175], off offset:16
	v_add_u32_e32 v128, s3, v163
	ds_read_b128 v[178:181], v128 offset:8256
	ds_read_b128 v[182:185], v128 offset:8000
	ds_read_b128 v[186:189], v128 offset:7744
	ds_read_b128 v[190:193], v128 offset:7488
	s_waitcnt vmcnt(6) lgkmcnt(3)
	v_mfma_f32_16x16x32_f16 v[12:15], v[178:181], v[16:19], v[12:15]
	v_perm_b32 v194, v16, v17, s29
	v_perm_b32 v195, v17, v18, s29
	v_perm_b32 v196, v18, v19, s29
	s_waitcnt lgkmcnt(2)
	v_mfma_f32_16x16x32_f16 v[36:39], v[182:185], v[16:19], v[36:39]
	v_perm_b32 v197, v19, v166, s29
	v_pk_mov_b32 v[200:201], v[18:19], v[166:167] op_sel:[1,0]
	v_pk_mov_b32 v[198:199], v[16:17], v[18:19] op_sel:[1,0]
	s_waitcnt lgkmcnt(1)
	v_mfma_f32_16x16x32_f16 v[60:63], v[186:189], v[16:19], v[60:63]
	v_perm_b32 v205, v166, v167, s29
	v_mov_b32_e32 v202, v195
	v_mov_b32_e32 v203, v196
	s_waitcnt lgkmcnt(0)
	v_mfma_f32_16x16x32_f16 v[80:83], v[190:193], v[16:19], v[80:83]
	v_mov_b32_e32 v16, v18
	v_mov_b32_e32 v17, v19
	v_mov_b32_e32 v18, v166
	v_mov_b32_e32 v19, v167
	v_mov_b32_e32 v204, v197
	v_mfma_f32_16x16x32_f16 v[56:59], v[178:181], v[194:197], v[56:59]
	s_addk_i32 s3, 0x80
	v_add_u32_e32 v164, 64, v164
	v_lshl_add_u64 v[154:155], v[154:155], 0, s[22:23]
	v_mfma_f32_16x16x32_f16 v[120:123], v[178:181], v[16:19], v[120:123]
	s_cmp_lg_u32 s3, 0
	v_mfma_f32_16x16x32_f16 v[116:119], v[182:185], v[16:19], v[116:119]
	v_mfma_f32_16x16x32_f16 v[112:115], v[186:189], v[16:19], v[112:115]
	v_mfma_f32_16x16x32_f16 v[16:19], v[190:193], v[16:19], v[124:127]
	s_nop 2
	v_perm_b32 v127, v167, v168, s29
	v_mfma_f32_16x16x32_f16 v[28:31], v[178:181], v[202:205], v[28:31]
	v_mov_b32_e32 v124, v196
	v_mov_b32_e32 v125, v197
	v_mov_b32_e32 v126, v205
	v_mfma_f32_16x16x32_f16 v[24:27], v[182:185], v[202:205], v[24:27]
	v_mfma_f32_16x16x32_f16 v[20:23], v[186:189], v[202:205], v[20:23]
	v_mfma_f32_16x16x32_f16 v[32:35], v[190:193], v[202:205], v[32:35]
	v_pk_mov_b32 v[202:203], v[166:167], v[168:169] op_sel:[1,0]
	v_perm_b32 v169, v168, v169, s29
	v_mov_b32_e32 v166, v197
	v_mov_b32_e32 v167, v205
	v_mov_b32_e32 v168, v127
	v_mfma_f32_16x16x32_f16 v[52:55], v[182:185], v[194:197], v[52:55]
	s_waitcnt vmcnt(5)
	v_perm_b32 v205, v5, v6, s29
	v_mfma_f32_16x16x32_f16 v[48:51], v[186:189], v[194:197], v[48:51]
	v_mfma_f32_16x16x32_f16 v[104:107], v[178:181], v[198:201], v[104:107]
	v_mfma_f32_16x16x32_f16 v[96:99], v[182:185], v[198:201], v[96:99]
	v_mfma_f32_16x16x32_f16 v[88:91], v[186:189], v[198:201], v[88:91]
	v_mfma_f32_16x16x32_f16 v[76:79], v[178:181], v[124:127], v[76:79]
	v_mfma_f32_16x16x32_f16 v[72:75], v[182:185], v[124:127], v[72:75]
	v_mfma_f32_16x16x32_f16 v[68:71], v[186:189], v[124:127], v[68:71]
	v_mfma_f32_16x16x32_f16 v[100:103], v[178:181], v[200:203], v[100:103]
	v_mfma_f32_16x16x32_f16 v[92:95], v[182:185], v[200:203], v[92:95]
	v_mfma_f32_16x16x32_f16 v[84:87], v[186:189], v[200:203], v[84:87]
	v_mfma_f32_16x16x32_f16 v[130:133], v[178:181], v[166:169], v[130:133]
	ds_read_b128 v[178:181], v128 offset:8320
	v_mfma_f32_16x16x32_f16 v[134:137], v[182:185], v[166:169], v[134:137]
	ds_read_b128 v[182:185], v128 offset:7808
	v_mfma_f32_16x16x32_f16 v[138:141], v[186:189], v[166:169], v[138:141]
	ds_read_b128 v[186:189], v128 offset:7552
	v_mfma_f32_16x16x32_f16 v[146:149], v[190:193], v[166:169], v[146:149]
	ds_read_b128 v[166:169], v128 offset:8064
	v_mfma_f32_16x16x32_f16 v[44:47], v[190:193], v[194:197], v[44:47]
	s_waitcnt vmcnt(4)
	v_pk_mov_b32 v[196:197], v[10:11], v[4:5] op_sel:[1,0]
	v_pk_mov_b32 v[194:195], v[8:9], v[10:11] op_sel:[1,0]
	v_mfma_f32_16x16x32_f16 v[40:43], v[190:193], v[198:201], v[40:43]
	v_mfma_f32_16x16x32_f16 v[64:67], v[190:193], v[124:127], v[64:67]
	v_mfma_f32_16x16x32_f16 v[108:111], v[190:193], v[200:203], v[108:111]
	v_perm_b32 v190, v8, v9, s29
	v_perm_b32 v191, v9, v10, s29
	v_perm_b32 v192, v10, v11, s29
	s_waitcnt lgkmcnt(3)
	v_mfma_f32_16x16x32_f16 v[12:15], v[178:181], v[8:11], v[12:15]
	v_perm_b32 v193, v11, v4, s29
	v_perm_b32 v201, v4, v5, s29
	v_mov_b32_e32 v198, v191
	s_waitcnt lgkmcnt(0)
; template <int MODE, int TB>
; DI void toeplitz_task(const Params& P, int layer, int set, int cg, int chunk, char* smem) {
;     ...
;     for (int g = 0; g < ngroups; ++g) {
;       load_group(g + 1 < ngroups ? g + 1 : g, nxt);
;       __builtin_amdgcn_sched_barrier(0);
; #pragma unroll
;       for (int q = 0; q < GS; ++q) {
;         const int s0 = -32 + (g * GS + q) * 32;
;         half8 af[TB];
; #pragma unroll
;         for (int ta = 0; ta < TB; ++ta) { af[ta] = afn[ta]; afn[ta] = *(const half8*)(krw + abase + s0 + 32 - 128 * ta); }
;         unsigned d[8];
;         {
;           const int sw0 = s0 + 8 * kg, sw1 = sw0 + 8;
;           const bool va = (sw0 >= 0) && (sw0 < L), vb = (sw1 >= 0) && (sw1 < L);
; #pragma unroll
;           for (int e = 0; e < 4; ++e) { d[e] = va ? cur[2 * q][e] : 0u; d[4 + e] = vb ? cur[2 * q + 1][e] : 0u; }
;         }
; #pragma unroll
;         for (int r = 0; r < 8; ++r) {
;           u32x4 bw;
; #pragma unroll
;           for (int e = 0; e < 4; ++e)
;             bw[e] = (r & 1) ? __builtin_amdgcn_alignbit(d[(r >> 1) + e + 1 > 7 ? 7 : (r >> 1) + e + 1], d[(r >> 1) + e], 16) : d[(r >> 1) + e];
;           const half8 bfr = __builtin_bit_cast(half8, bw);
; #pragma unroll
;           for (int ta = 0; ta < TB; ++ta) acc[ta][r] = __builtin_amdgcn_mfma_f32_16x16x32_f16(af[ta], bfr, acc[ta][r], 0, 0, 0);
;         }
;       }
; #pragma unroll
;       for (int e = 0; e < 2 * GS; ++e) cur[e] = nxt[e];
;     }
	v_mfma_f32_16x16x32_f16 v[36:39], v[166:169], v[8:11], v[36:39]
	v_mov_b32_e32 v199, v192
	v_mov_b32_e32 v200, v193
	v_mov_b32_e32 v202, v192
	v_mfma_f32_16x16x32_f16 v[60:63], v[182:185], v[8:11], v[60:63]
	v_mov_b32_e32 v203, v193
	v_mov_b32_e32 v204, v201
	v_mfma_f32_16x16x32_f16 v[80:83], v[186:189], v[8:11], v[80:83]
	v_mov_b32_e32 v8, v10
	v_mov_b32_e32 v9, v11
	v_mov_b32_e32 v10, v4
	v_mov_b32_e32 v11, v5
	v_mfma_f32_16x16x32_f16 v[56:59], v[178:181], v[190:193], v[56:59]
	s_nop 0
	v_mfma_f32_16x16x32_f16 v[120:123], v[178:181], v[8:11], v[120:123]
	v_mfma_f32_16x16x32_f16 v[116:119], v[166:169], v[8:11], v[116:119]
	v_mfma_f32_16x16x32_f16 v[112:115], v[182:185], v[8:11], v[112:115]
	v_mfma_f32_16x16x32_f16 v[124:127], v[186:189], v[8:11], v[16:19]
	v_pk_mov_b32 v[10:11], v[4:5], v[6:7] op_sel:[1,0]
	v_mov_b32_e32 v8, v196
	v_mov_b32_e32 v9, v197
	v_perm_b32 v19, v6, v7, s29
	v_mov_b32_e32 v16, v193
	v_mov_b32_e32 v17, v201
	v_mov_b32_e32 v18, v205
	v_mfma_f32_16x16x32_f16 v[52:55], v[166:169], v[190:193], v[52:55]
	v_mfma_f32_16x16x32_f16 v[48:51], v[182:185], v[190:193], v[48:51]
	v_mfma_f32_16x16x32_f16 v[44:47], v[186:189], v[190:193], v[44:47]
	v_mfma_f32_16x16x32_f16 v[104:107], v[178:181], v[194:197], v[104:107]
	v_mfma_f32_16x16x32_f16 v[96:99], v[166:169], v[194:197], v[96:99]
	v_mfma_f32_16x16x32_f16 v[88:91], v[182:185], v[194:197], v[88:91]
	v_mfma_f32_16x16x32_f16 v[40:43], v[186:189], v[194:197], v[40:43]
	v_mfma_f32_16x16x32_f16 v[28:31], v[178:181], v[198:201], v[28:31]
	v_mfma_f32_16x16x32_f16 v[24:27], v[166:169], v[198:201], v[24:27]
	v_mfma_f32_16x16x32_f16 v[20:23], v[182:185], v[198:201], v[20:23]
	v_mfma_f32_16x16x32_f16 v[32:35], v[186:189], v[198:201], v[32:35]
	v_mfma_f32_16x16x32_f16 v[76:79], v[178:181], v[202:205], v[76:79]
	v_mfma_f32_16x16x32_f16 v[72:75], v[166:169], v[202:205], v[72:75]
	v_mfma_f32_16x16x32_f16 v[68:71], v[182:185], v[202:205], v[68:71]
	v_mfma_f32_16x16x32_f16 v[64:67], v[186:189], v[202:205], v[64:67]
	v_mfma_f32_16x16x32_f16 v[100:103], v[178:181], v[8:11], v[100:103]
	v_mfma_f32_16x16x32_f16 v[92:95], v[166:169], v[8:11], v[92:95]
	v_mfma_f32_16x16x32_f16 v[84:87], v[182:185], v[8:11], v[84:87]
	v_mfma_f32_16x16x32_f16 v[108:111], v[186:189], v[8:11], v[108:111]
	v_mfma_f32_16x16x32_f16 v[130:133], v[178:181], v[16:19], v[130:133]
	v_mfma_f32_16x16x32_f16 v[134:137], v[166:169], v[16:19], v[134:137]
	v_mfma_f32_16x16x32_f16 v[138:141], v[182:185], v[16:19], v[138:141]
	v_mfma_f32_16x16x32_f16 v[146:149], v[186:189], v[16:19], v[146:149]
	s_waitcnt vmcnt(0)
	v_mov_b64_e32 v[4:5], v[174:175]
	v_mov_b64_e32 v[6:7], v[176:177]
	v_mov_b64_e32 v[8:9], v[170:171]
	v_mov_b64_e32 v[10:11], v[172:173]
	v_mov_b64_e32 v[16:17], v[142:143]
	v_mov_b64_e32 v[18:19], v[144:145]
	s_cbranch_scc1 .LBB0_404
	v_add_u32_e32 v128, s3, v163
	ds_read_b128 v[4:7], v128 offset:8256
	ds_read_b128 v[8:11], v128 offset:8000
	ds_read_b128 v[16:19], v128 offset:7744
	ds_read_b128 v[164:167], v128 offset:7488
	v_cndmask_b32_e64 v187, v0, 0, vcc
	v_cndmask_b32_e64 v191, v1, 0, vcc
	v_cndmask_b32_e64 v195, v2, 0, vcc
	v_cndmask_b32_e64 v128, v3, 0, vcc
	s_waitcnt lgkmcnt(3)
	v_mfma_f32_16x16x32_f16 v[0:3], v[4:7], v[142:145], v[12:15]
	v_pk_mov_b32 v[184:185], v[142:143], v[144:145] op_sel:[1,0]
	v_mov_b32_e32 v186, v145
	ds_read_b128 v[168:171], v162 offset:8320
	ds_read_b128 v[172:175], v162 offset:8064
	ds_read_b128 v[176:179], v162 offset:7808
	ds_read_b128 v[180:183], v162 offset:7552
	s_waitcnt lgkmcnt(6)
	v_mfma_f32_16x16x32_f16 v[12:15], v[8:11], v[142:145], v[36:39]
	v_mov_b32_e32 v188, v144
	v_mov_b32_e32 v189, v145
	v_mov_b32_e32 v190, v187
	s_waitcnt lgkmcnt(5)
	v_mfma_f32_16x16x32_f16 v[36:39], v[16:19], v[142:145], v[60:63]
	v_mov_b32_e32 v192, v145
	v_mov_b32_e32 v193, v187
	v_mov_b32_e32 v194, v191
	v_perm_b32 v61, v143, v144, s29
	v_perm_b32 v62, v144, v145, s29
	v_alignbit_b32 v63, v187, v145, 16
	v_mfma_f32_16x16x32_f16 v[196:199], v[16:19], v[184:187], v[88:91]
	v_perm_b32 v60, v142, v143, s29
	s_mov_b32 s86, s85
	s_mov_b32 s87, s85
	v_alignbit_b32 v91, v191, v187, 16
	v_mov_b32_e32 v88, v61
	v_mov_b32_e32 v89, v62
	v_mov_b32_e32 v90, v63
	v_mfma_f32_16x16x32_f16 v[96:99], v[8:11], v[184:187], v[96:99]
	s_mov_b32 s84, s85
	s_lshl_b32 s24, s2, 1
	s_add_i32 s3, 0, 0x11000
	v_mfma_f32_16x16x32_f16 v[210:213], v[16:19], v[88:91], v[20:23]
	s_ashr_i32 s39, s38, 31
	s_nop 1
	v_alignbit_b32 v23, v195, v191, 16
	v_mfma_f32_16x16x32_f16 v[204:207], v[8:11], v[88:91], v[24:27]
	v_mov_b32_e32 v20, v62
	v_mov_b32_e32 v21, v63
	v_mov_b32_e32 v22, v91
	v_alignbit_b32 v27, v128, v195, 16
	v_mov_b32_e32 v24, v63
	v_mov_b32_e32 v25, v91
	v_mov_b32_e32 v26, v23
	s_waitcnt lgkmcnt(4)
	v_mfma_f32_16x16x32_f16 v[80:83], v[164:167], v[142:145], v[80:83]
	v_lshl_add_u32 v128, v160, 11, v152
	v_mfma_f32_16x16x32_f16 v[130:133], v[4:7], v[24:27], v[130:133]
	v_mfma_f32_16x16x32_f16 v[44:47], v[164:167], v[60:63], v[44:47]
	v_mfma_f32_16x16x32_f16 v[40:43], v[164:167], v[184:187], v[40:43]
	v_mfma_f32_16x16x32_f16 v[32:35], v[164:167], v[88:91], v[32:35]
	v_mfma_f32_16x16x32_f16 v[224:227], v[4:7], v[188:191], v[120:123]
	v_mfma_f32_16x16x32_f16 v[228:231], v[8:11], v[188:191], v[116:119]
	v_mfma_f32_16x16x32_f16 v[232:235], v[16:19], v[188:191], v[112:115]
	v_mfma_f32_16x16x32_f16 v[236:239], v[164:167], v[188:191], v[124:127]
	v_mfma_f32_16x16x32_f16 v[64:67], v[164:167], v[20:23], v[64:67]
	v_mfma_f32_16x16x32_f16 v[188:191], v[164:167], v[192:195], v[108:111]
	v_mfma_f32_16x16x32_f16 v[138:141], v[16:19], v[24:27], v[138:141]
	v_mfma_f32_16x16x32_f16 v[146:149], v[164:167], v[24:27], v[146:149]
	v_mov_b64_e32 v[164:165], s[86:87]
	v_mov_b64_e32 v[162:163], s[84:85]
	v_mfma_f32_16x16x32_f16 v[104:107], v[4:7], v[184:187], v[104:107]
	v_mfma_f32_16x16x32_f16 v[184:187], v[16:19], v[192:195], v[84:87]
	s_waitcnt lgkmcnt(2)
; template <int MODE, int TB>
; DI void toeplitz_task(const Params& P, int layer, int set, int cg, int chunk, char* smem) {
;     ...
;           for (int ta = 0; ta < TB; ++ta) acc[ta][r] = __builtin_amdgcn_mfma_f32_16x16x32_f16(af[ta], bfr, acc[ta][r], 0, 0, 0);
;         }
;       }
; #pragma unroll
;       for (int e = 0; e < 2 * GS; ++e) cur[e] = nxt[e];
;     }
; #pragma unroll
;     for (int hf = 0; hf < TB / 2; ++hf) {
;     const int tbh = tb + 256 * hf;
; #pragma unroll
;     for (int ta = 2 * hf; ta < 2 * hf + 2; ++ta) {
;       const int t0 = tb + 128 * ta + 32 * kg;
; #pragma unroll
;       for (int v = 0; v < 4; ++v) {
;         const int t = t0 + 8 * v;
;         if (MODE == 0) {
;           const half8 x1 = *(const half8*)(hT + (size_t)(bb * 2048 + 512 + c) * L + t);
;           const half8 uu = *(const half8*)(Urow + t);
;           half8 o;
; #pragma unroll
;           for (int r = 0; r < 8; ++r) o[r] = (h16)((float)x1[r] * (acc[ta][r][v] * invs + (float)uu[r] * bias));
;           *(half8*)(z1T + (size_t)(bb * 512 + c) * L + t) = o;
;         } else {
;           const half8 x2 = *(const half8*)(hT + (size_t)(bb * 2048 + 1024 + c) * L + t);
;           const half8 gt = *(const half8*)(hT + (size_t)(bb * 2048 + 1536 + c) * L + t);
;           const half8 uu = *(const half8*)(Urow + t);
; #pragma unroll
;           for (int r = 0; r < 8; ++r) {
;             const float y = (float)x2[r] * (acc[ta][r][v] * invs + (float)uu[r] * bias) * (float)gt[r];
;             const int tl = t - tbh + r;
;             *(h16*)(stg + ((tl * 16 + bb) * 8 + w) * 2) = (h16)y;
;           }
	v_mfma_f32_16x16x32_f16 v[84:87], v[172:175], v[162:165], v[96:99]
	v_mfma_f32_16x16x32_f16 v[96:99], v[168:171], v[162:165], v[130:133]
	s_nop 2
	v_add_u32_e32 v130, 0x400, v128
	v_mfma_f32_16x16x32_f16 v[134:137], v[8:11], v[24:27], v[134:137]
	v_ashrrev_i32_e32 v131, 31, v130
	v_add_u32_e32 v132, 0x600, v128
	v_lshl_or_b32 v128, v159, 6, s24
	v_mfma_f32_16x16x32_f16 v[48:51], v[16:19], v[60:63], v[48:51]
	v_lshlrev_b64 v[130:131], 12, v[130:131]
	v_ashrrev_i32_e32 v133, 31, v132
	v_lshl_add_u64 v[130:131], s[48:49], 0, v[130:131]
	v_mfma_f32_16x16x32_f16 v[68:71], v[16:19], v[20:23], v[68:71]
	v_lshlrev_b64 v[132:133], 12, v[132:133]
	v_lshl_add_u64 v[132:133], s[48:49], 0, v[132:133]
	v_readlane_b32 s24, v253, 45
	s_waitcnt lgkmcnt(0)
	v_mfma_f32_16x16x32_f16 v[16:19], v[180:183], v[162:165], v[32:35]
	v_mfma_f32_16x16x32_f16 v[32:35], v[176:179], v[162:165], v[138:141]
	s_nop 2
	v_lshl_add_u64 v[138:139], v[150:151], 0, v[128:129]
	v_mfma_f32_16x16x32_f16 v[124:127], v[168:171], v[162:165], v[0:3]
	v_lshl_add_u64 v[140:141], v[130:131], 0, v[128:129]
	v_mfma_f32_16x16x32_f16 v[0:3], v[180:183], v[162:165], v[146:149]
	s_nop 2
	global_load_dwordx4 v[146:149], v[138:139], off
	v_mfma_f32_16x16x32_f16 v[52:55], v[8:11], v[60:63], v[52:55]
	v_mfma_f32_16x16x32_f16 v[72:75], v[8:11], v[20:23], v[72:75]
	v_mfma_f32_16x16x32_f16 v[142:145], v[8:11], v[192:195], v[92:95]
	v_mfma_f32_16x16x32_f16 v[8:11], v[180:183], v[162:165], v[64:67]
	v_mfma_f32_16x16x32_f16 v[64:67], v[172:175], v[162:165], v[134:137]
	s_nop 2
	v_lshl_add_u64 v[136:137], v[132:133], 0, v[128:129]
	global_load_dwordx4 v[130:133], v[140:141], off
	v_mfma_f32_16x16x32_f16 v[56:59], v[4:7], v[60:63], v[56:59]
	s_waitcnt vmcnt(0)
	v_cvt_f32_f16_e32 v128, v130
	v_mfma_f32_16x16x32_f16 v[200:203], v[4:7], v[88:91], v[28:31]
	v_mfma_f32_16x16x32_f16 v[240:243], v[4:7], v[20:23], v[76:79]
	v_mfma_f32_16x16x32_f16 v[100:103], v[4:7], v[192:195], v[100:103]
	v_mfma_f32_16x16x32_f16 v[92:95], v[172:175], v[162:165], v[12:15]
	v_mfma_f32_16x16x32_f16 v[60:63], v[176:179], v[162:165], v[36:39]
	v_mfma_f32_16x16x32_f16 v[28:31], v[180:183], v[162:165], v[80:83]
	v_mfma_f32_16x16x32_f16 v[120:123], v[168:171], v[162:165], v[56:59]
	v_mfma_f32_16x16x32_f16 v[88:91], v[172:175], v[162:165], v[52:55]
	v_mfma_f32_16x16x32_f16 v[56:59], v[176:179], v[162:165], v[48:51]
	v_mfma_f32_16x16x32_f16 v[24:27], v[180:183], v[162:165], v[44:47]
	v_mfma_f32_16x16x32_f16 v[116:119], v[168:171], v[162:165], v[104:107]
	v_mfma_f32_16x16x32_f16 v[52:55], v[176:179], v[162:165], v[196:199]
	v_mfma_f32_16x16x32_f16 v[20:23], v[180:183], v[162:165], v[40:43]
	v_mfma_f32_16x16x32_f16 v[112:115], v[168:171], v[162:165], v[200:203]
	v_mfma_f32_16x16x32_f16 v[80:83], v[172:175], v[162:165], v[204:207]
	v_mfma_f32_16x16x32_f16 v[48:51], v[176:179], v[162:165], v[210:213]
	v_mfma_f32_16x16x32_f16 v[108:111], v[168:171], v[162:165], v[224:227]
	v_mfma_f32_16x16x32_f16 v[76:79], v[172:175], v[162:165], v[228:231]
	v_mfma_f32_16x16x32_f16 v[44:47], v[176:179], v[162:165], v[232:235]
	v_mfma_f32_16x16x32_f16 v[12:15], v[180:183], v[162:165], v[236:239]
	v_mfma_f32_16x16x32_f16 v[104:107], v[168:171], v[162:165], v[240:243]
	v_mfma_f32_16x16x32_f16 v[72:75], v[172:175], v[162:165], v[72:75]
	v_mfma_f32_16x16x32_f16 v[40:43], v[176:179], v[162:165], v[68:71]
	v_mfma_f32_16x16x32_f16 v[100:103], v[168:171], v[162:165], v[100:103]
	v_mfma_f32_16x16x32_f16 v[68:71], v[172:175], v[162:165], v[142:145]
	v_mfma_f32_16x16x32_f16 v[36:39], v[176:179], v[162:165], v[184:187]
	s_nop 1
	v_ashrrev_i32_e32 v142, 8, v157
	v_ashrrev_i32_e32 v143, 31, v142
	v_lshlrev_b64 v[134:135], 11, v[142:143]
	v_mfma_f32_16x16x32_f16 v[4:7], v[180:183], v[162:165], v[188:191]
	global_load_dwordx4 v[162:165], v[136:137], off
	v_cvt_f32_f16_e32 v143, v146
	v_and_b32_e32 v145, 0xff, v157
	v_lshl_add_u32 v144, v145, 8, s3
	v_mul_f32_e32 v143, v153, v143
	v_fmac_f32_e32 v143, v156, v124
	v_mul_f32_e32 v124, v143, v128
	v_lshl_add_u32 v143, v159, 13, s3
	s_waitcnt vmcnt(0)
	v_fma_mixlo_f16 v128, v124, v162, 0 op_sel_hi:[0,1,0]
	v_lshlrev_b32_e32 v124, 1, v158
	v_add3_u32 v124, v143, v161, v124
	ds_write_b16 v124, v128
	v_cvt_f32_f16_sdwa v128, v130 dst_sel:DWORD dst_unused:UNUSED_PAD src0_sel:WORD_1
	v_cvt_f32_f16_sdwa v130, v146 dst_sel:DWORD dst_unused:UNUSED_PAD src0_sel:WORD_1
	global_load_dwordx4 v[158:161], v[136:137], off offset:16
	v_mul_f32_e32 v130, v153, v130
	v_fmac_f32_e32 v130, v156, v120
	v_mul_f32_e32 v120, v130, v128
	v_cvt_f32_f16_e32 v128, v147
	v_fma_mixlo_f16 v120, v120, v162, 0 op_sel:[0,1,0] op_sel_hi:[0,1,0]
	ds_write_b16 v124, v120 offset:256
	v_cvt_f32_f16_e32 v120, v131
	v_mul_f32_e32 v128, v153, v128
	v_fmac_f32_e32 v128, v156, v116
	v_mul_f32_e32 v116, v128, v120
	v_cvt_f32_f16_sdwa v120, v147 dst_sel:DWORD dst_unused:UNUSED_PAD src0_sel:WORD_1
	v_fma_mixlo_f16 v116, v116, v163, 0 op_sel_hi:[0,1,0]
	ds_write_b16 v124, v116 offset:512
	v_cvt_f32_f16_sdwa v116, v131 dst_sel:DWORD dst_unused:UNUSED_PAD src0_sel:WORD_1
	v_mul_f32_e32 v120, v153, v120
	v_fmac_f32_e32 v120, v156, v112
	v_mul_f32_e32 v112, v120, v116
	v_cvt_f32_f16_e32 v116, v148
	v_fma_mixlo_f16 v112, v112, v163, 0 op_sel:[0,1,0] op_sel_hi:[0,1,0]
	ds_write_b16 v124, v112 offset:768
	v_cvt_f32_f16_e32 v112, v132
	v_mul_f32_e32 v116, v153, v116
	v_fmac_f32_e32 v116, v156, v108
	v_mul_f32_e32 v108, v116, v112
	v_cvt_f32_f16_sdwa v112, v148 dst_sel:DWORD dst_unused:UNUSED_PAD src0_sel:WORD_1
	v_fma_mixlo_f16 v108, v108, v164, 0 op_sel_hi:[0,1,0]
	ds_write_b16 v124, v108 offset:1024
	v_cvt_f32_f16_sdwa v108, v132 dst_sel:DWORD dst_unused:UNUSED_PAD src0_sel:WORD_1
	v_mul_f32_e32 v112, v153, v112
	v_fmac_f32_e32 v112, v156, v104
	v_mul_f32_e32 v104, v112, v108
	v_cvt_f32_f16_e32 v108, v149
	v_fma_mixlo_f16 v104, v104, v164, 0 op_sel:[0,1,0] op_sel_hi:[0,1,0]
	ds_write_b16 v124, v104 offset:1280
	v_cvt_f32_f16_e32 v104, v133
	v_mul_f32_e32 v108, v153, v108
	v_fmac_f32_e32 v108, v156, v100
	v_mul_f32_e32 v100, v108, v104
	v_cvt_f32_f16_sdwa v104, v149 dst_sel:DWORD dst_unused:UNUSED_PAD src0_sel:WORD_1
	global_load_dwordx4 v[146:149], v[138:139], off offset:16
	v_fma_mixlo_f16 v100, v100, v165, 0 op_sel_hi:[0,1,0]
	ds_write_b16 v124, v100 offset:1536
	v_cvt_f32_f16_sdwa v100, v133 dst_sel:DWORD dst_unused:UNUSED_PAD src0_sel:WORD_1
	global_load_dwordx4 v[130:133], v[140:141], off offset:16
	v_mul_f32_e32 v104, v153, v104
	v_fmac_f32_e32 v104, v156, v96
	v_mul_f32_e32 v96, v104, v100
	v_fma_mixlo_f16 v96, v96, v165, 0 op_sel:[0,1,0] op_sel_hi:[0,1,0]
	ds_write_b16 v124, v96 offset:1792
	s_waitcnt vmcnt(1)
; template <int MODE, int TB>
; DI void toeplitz_task(const Params& P, int layer, int set, int cg, int chunk, char* smem) {
;     ...
;       for (int v = 0; v < 4; ++v) {
;         const int t = t0 + 8 * v;
;         if (MODE == 0) {
;           const half8 x1 = *(const half8*)(hT + (size_t)(bb * 2048 + 512 + c) * L + t);
;           const half8 uu = *(const half8*)(Urow + t);
;           half8 o;
; #pragma unroll
;           for (int r = 0; r < 8; ++r) o[r] = (h16)((float)x1[r] * (acc[ta][r][v] * invs + (float)uu[r] * bias));
;           *(half8*)(z1T + (size_t)(bb * 512 + c) * L + t) = o;
;         } else {
;           const half8 x2 = *(const half8*)(hT + (size_t)(bb * 2048 + 1024 + c) * L + t);
;           const half8 gt = *(const half8*)(hT + (size_t)(bb * 2048 + 1536 + c) * L + t);
;           const half8 uu = *(const half8*)(Urow + t);
; #pragma unroll
;           for (int r = 0; r < 8; ++r) {
;             const float y = (float)x2[r] * (acc[ta][r][v] * invs + (float)uu[r] * bias) * (float)gt[r];
;             const int tl = t - tbh + r;
;             *(h16*)(stg + ((tl * 16 + bb) * 8 + w) * 2) = (h16)y;
;           }
	v_cvt_f32_f16_e32 v100, v146
	s_waitcnt vmcnt(0)
	v_cvt_f32_f16_e32 v96, v130
	v_mul_f32_e32 v100, v153, v100
	v_fmac_f32_e32 v100, v156, v125
	v_mul_f32_e32 v96, v100, v96
	v_cvt_f32_f16_sdwa v100, v146 dst_sel:DWORD dst_unused:UNUSED_PAD src0_sel:WORD_1
	v_fma_mixlo_f16 v96, v96, v158, 0 op_sel_hi:[0,1,0]
	ds_write_b16 v124, v96 offset:2048
	v_cvt_f32_f16_sdwa v96, v130 dst_sel:DWORD dst_unused:UNUSED_PAD src0_sel:WORD_1
	v_mul_f32_e32 v100, v153, v100
	v_fmac_f32_e32 v100, v156, v121
	v_mul_f32_e32 v96, v100, v96
	v_cvt_f32_f16_e32 v100, v147
	v_fma_mixlo_f16 v96, v96, v158, 0 op_sel:[0,1,0] op_sel_hi:[0,1,0]
	ds_write_b16 v124, v96 offset:2304
	v_cvt_f32_f16_e32 v96, v131
	v_mul_f32_e32 v100, v153, v100
	v_fmac_f32_e32 v100, v156, v117
	v_mul_f32_e32 v96, v100, v96
	v_cvt_f32_f16_sdwa v100, v147 dst_sel:DWORD dst_unused:UNUSED_PAD src0_sel:WORD_1
	v_fma_mixlo_f16 v96, v96, v159, 0 op_sel_hi:[0,1,0]
	ds_write_b16 v124, v96 offset:2560
	v_cvt_f32_f16_sdwa v96, v131 dst_sel:DWORD dst_unused:UNUSED_PAD src0_sel:WORD_1
	v_mul_f32_e32 v100, v153, v100
	v_fmac_f32_e32 v100, v156, v113
	v_mul_f32_e32 v96, v100, v96
	v_cvt_f32_f16_e32 v100, v148
	v_fma_mixlo_f16 v96, v96, v159, 0 op_sel:[0,1,0] op_sel_hi:[0,1,0]
	ds_write_b16 v124, v96 offset:2816
	v_cvt_f32_f16_e32 v96, v132
	v_mul_f32_e32 v100, v153, v100
	v_fmac_f32_e32 v100, v156, v109
	v_mul_f32_e32 v96, v100, v96
	v_cvt_f32_f16_sdwa v100, v148 dst_sel:DWORD dst_unused:UNUSED_PAD src0_sel:WORD_1
	v_fma_mixlo_f16 v96, v96, v160, 0 op_sel_hi:[0,1,0]
	ds_write_b16 v124, v96 offset:3072
	v_cvt_f32_f16_sdwa v96, v132 dst_sel:DWORD dst_unused:UNUSED_PAD src0_sel:WORD_1
	v_mul_f32_e32 v100, v153, v100
	v_fmac_f32_e32 v100, v156, v105
	v_mul_f32_e32 v96, v100, v96
	v_cvt_f32_f16_e32 v100, v149
	v_fma_mixlo_f16 v96, v96, v160, 0 op_sel:[0,1,0] op_sel_hi:[0,1,0]
	ds_write_b16 v124, v96 offset:3328
	v_cvt_f32_f16_e32 v96, v133
	v_mul_f32_e32 v100, v153, v100
	v_fmac_f32_e32 v100, v156, v101
	v_mul_f32_e32 v96, v100, v96
	v_cvt_f32_f16_sdwa v100, v149 dst_sel:DWORD dst_unused:UNUSED_PAD src0_sel:WORD_1
	global_load_dwordx4 v[146:149], v[138:139], off offset:32
	v_fma_mixlo_f16 v96, v96, v161, 0 op_sel_hi:[0,1,0]
	ds_write_b16 v124, v96 offset:3584
	v_cvt_f32_f16_sdwa v96, v133 dst_sel:DWORD dst_unused:UNUSED_PAD src0_sel:WORD_1
	global_load_dwordx4 v[130:133], v[140:141], off offset:32
	v_mul_f32_e32 v100, v153, v100
	v_fmac_f32_e32 v100, v156, v97
	v_mul_f32_e32 v96, v100, v96
	v_fma_mixlo_f16 v96, v96, v161, 0 op_sel:[0,1,0] op_sel_hi:[0,1,0]
	global_load_dwordx4 v[158:161], v[136:137], off offset:32
	ds_write_b16 v124, v96 offset:3840
	s_waitcnt vmcnt(2)
	v_cvt_f32_f16_e32 v97, v146
	s_waitcnt vmcnt(1)
	v_cvt_f32_f16_e32 v96, v130
	v_mul_f32_e32 v97, v153, v97
	v_fmac_f32_e32 v97, v156, v126
	v_mul_f32_e32 v96, v97, v96
	v_cvt_f32_f16_sdwa v97, v146 dst_sel:DWORD dst_unused:UNUSED_PAD src0_sel:WORD_1
	s_waitcnt vmcnt(0)
	v_fma_mixlo_f16 v96, v96, v158, 0 op_sel_hi:[0,1,0]
	ds_write_b16 v124, v96 offset:4096
	v_cvt_f32_f16_sdwa v96, v130 dst_sel:DWORD dst_unused:UNUSED_PAD src0_sel:WORD_1
	v_mul_f32_e32 v97, v153, v97
	v_fmac_f32_e32 v97, v156, v122
	v_mul_f32_e32 v96, v97, v96
	v_cvt_f32_f16_e32 v97, v147
	v_fma_mixlo_f16 v96, v96, v158, 0 op_sel:[0,1,0] op_sel_hi:[0,1,0]
	ds_write_b16 v124, v96 offset:4352
	v_cvt_f32_f16_e32 v96, v131
	v_mul_f32_e32 v97, v153, v97
	v_fmac_f32_e32 v97, v156, v118
	v_mul_f32_e32 v96, v97, v96
	v_cvt_f32_f16_sdwa v97, v147 dst_sel:DWORD dst_unused:UNUSED_PAD src0_sel:WORD_1
	v_fma_mixlo_f16 v96, v96, v159, 0 op_sel_hi:[0,1,0]
	ds_write_b16 v124, v96 offset:4608
	v_cvt_f32_f16_sdwa v96, v131 dst_sel:DWORD dst_unused:UNUSED_PAD src0_sel:WORD_1
	v_mul_f32_e32 v97, v153, v97
	v_fmac_f32_e32 v97, v156, v114
	v_mul_f32_e32 v96, v97, v96
	v_cvt_f32_f16_e32 v97, v148
	v_fma_mixlo_f16 v96, v96, v159, 0 op_sel:[0,1,0] op_sel_hi:[0,1,0]
	ds_write_b16 v124, v96 offset:4864
	v_cvt_f32_f16_e32 v96, v132
	v_mul_f32_e32 v97, v153, v97
	v_fmac_f32_e32 v97, v156, v110
	v_mul_f32_e32 v96, v97, v96
	v_cvt_f32_f16_sdwa v97, v148 dst_sel:DWORD dst_unused:UNUSED_PAD src0_sel:WORD_1
	v_fma_mixlo_f16 v96, v96, v160, 0 op_sel_hi:[0,1,0]
	ds_write_b16 v124, v96 offset:5120
	v_cvt_f32_f16_sdwa v96, v132 dst_sel:DWORD dst_unused:UNUSED_PAD src0_sel:WORD_1
	v_mul_f32_e32 v97, v153, v97
	v_fmac_f32_e32 v97, v156, v106
	v_mul_f32_e32 v96, v97, v96
	v_cvt_f32_f16_e32 v97, v149
	v_fma_mixlo_f16 v96, v96, v160, 0 op_sel:[0,1,0] op_sel_hi:[0,1,0]
	ds_write_b16 v124, v96 offset:5376
	v_cvt_f32_f16_e32 v96, v133
	v_mul_f32_e32 v97, v153, v97
	v_fmac_f32_e32 v97, v156, v102
	v_mul_f32_e32 v96, v97, v96
	v_cvt_f32_f16_sdwa v97, v149 dst_sel:DWORD dst_unused:UNUSED_PAD src0_sel:WORD_1
	global_load_dwordx4 v[146:149], v[138:139], off offset:48
	v_fma_mixlo_f16 v96, v96, v161, 0 op_sel_hi:[0,1,0]
	ds_write_b16 v124, v96 offset:5632
	v_cvt_f32_f16_sdwa v96, v133 dst_sel:DWORD dst_unused:UNUSED_PAD src0_sel:WORD_1
	global_load_dwordx4 v[130:133], v[140:141], off offset:48
	v_mul_f32_e32 v97, v153, v97
	v_fmac_f32_e32 v97, v156, v98
	v_mul_f32_e32 v96, v97, v96
	v_fma_mixlo_f16 v96, v96, v161, 0 op_sel:[0,1,0] op_sel_hi:[0,1,0]
	global_load_dwordx4 v[158:161], v[136:137], off offset:48
	ds_write_b16 v124, v96 offset:5888
	s_waitcnt vmcnt(2)
	v_cvt_f32_f16_e32 v97, v146
	s_waitcnt vmcnt(1)
	v_cvt_f32_f16_e32 v96, v130
	v_mul_f32_e32 v97, v153, v97
	v_fmac_f32_e32 v97, v156, v127
	v_mul_f32_e32 v96, v97, v96
	v_cvt_f32_f16_sdwa v97, v146 dst_sel:DWORD dst_unused:UNUSED_PAD src0_sel:WORD_1
	s_waitcnt vmcnt(0)
; template <int MODE, int TB>
; DI void toeplitz_task(const Params& P, int layer, int set, int cg, int chunk, char* smem) {
;     ...
;       for (int v = 0; v < 4; ++v) {
;         const int t = t0 + 8 * v;
;         if (MODE == 0) {
;           const half8 x1 = *(const half8*)(hT + (size_t)(bb * 2048 + 512 + c) * L + t);
;           const half8 uu = *(const half8*)(Urow + t);
;           half8 o;
; #pragma unroll
;           for (int r = 0; r < 8; ++r) o[r] = (h16)((float)x1[r] * (acc[ta][r][v] * invs + (float)uu[r] * bias));
;           *(half8*)(z1T + (size_t)(bb * 512 + c) * L + t) = o;
;         } else {
;           const half8 x2 = *(const half8*)(hT + (size_t)(bb * 2048 + 1024 + c) * L + t);
;           const half8 gt = *(const half8*)(hT + (size_t)(bb * 2048 + 1536 + c) * L + t);
;           const half8 uu = *(const half8*)(Urow + t);
; #pragma unroll
;           for (int r = 0; r < 8; ++r) {
;             const float y = (float)x2[r] * (acc[ta][r][v] * invs + (float)uu[r] * bias) * (float)gt[r];
;             const int tl = t - tbh + r;
;             *(h16*)(stg + ((tl * 16 + bb) * 8 + w) * 2) = (h16)y;
;           }
	v_fma_mixlo_f16 v96, v96, v158, 0 op_sel_hi:[0,1,0]
	ds_write_b16 v124, v96 offset:6144
	v_cvt_f32_f16_sdwa v96, v130 dst_sel:DWORD dst_unused:UNUSED_PAD src0_sel:WORD_1
	v_mul_f32_e32 v97, v153, v97
	v_fmac_f32_e32 v97, v156, v123
	v_mul_f32_e32 v96, v97, v96
	v_cvt_f32_f16_e32 v97, v147
	v_fma_mixlo_f16 v96, v96, v158, 0 op_sel:[0,1,0] op_sel_hi:[0,1,0]
	ds_write_b16 v124, v96 offset:6400
	v_cvt_f32_f16_e32 v96, v131
	v_mul_f32_e32 v97, v153, v97
	v_fmac_f32_e32 v97, v156, v119
	v_mul_f32_e32 v96, v97, v96
	v_cvt_f32_f16_sdwa v97, v147 dst_sel:DWORD dst_unused:UNUSED_PAD src0_sel:WORD_1
	v_fma_mixlo_f16 v96, v96, v159, 0 op_sel_hi:[0,1,0]
	ds_write_b16 v124, v96 offset:6656
	v_cvt_f32_f16_sdwa v96, v131 dst_sel:DWORD dst_unused:UNUSED_PAD src0_sel:WORD_1
	v_mul_f32_e32 v97, v153, v97
	v_fmac_f32_e32 v97, v156, v115
	v_mul_f32_e32 v96, v97, v96
	v_cvt_f32_f16_e32 v97, v148
	v_fma_mixlo_f16 v96, v96, v159, 0 op_sel:[0,1,0] op_sel_hi:[0,1,0]
	ds_write_b16 v124, v96 offset:6912
	v_cvt_f32_f16_e32 v96, v132
	v_mul_f32_e32 v97, v153, v97
	v_fmac_f32_e32 v97, v156, v111
	v_mul_f32_e32 v96, v97, v96
	v_cvt_f32_f16_sdwa v97, v148 dst_sel:DWORD dst_unused:UNUSED_PAD src0_sel:WORD_1
	v_fma_mixlo_f16 v96, v96, v160, 0 op_sel_hi:[0,1,0]
	ds_write_b16 v124, v96 offset:7168
	v_cvt_f32_f16_sdwa v96, v132 dst_sel:DWORD dst_unused:UNUSED_PAD src0_sel:WORD_1
	v_mul_f32_e32 v97, v153, v97
	v_fmac_f32_e32 v97, v156, v107
	v_mul_f32_e32 v96, v97, v96
	v_cvt_f32_f16_e32 v97, v149
	v_fma_mixlo_f16 v96, v96, v160, 0 op_sel:[0,1,0] op_sel_hi:[0,1,0]
	ds_write_b16 v124, v96 offset:7424
	v_cvt_f32_f16_e32 v96, v133
	v_mul_f32_e32 v97, v153, v97
	v_fmac_f32_e32 v97, v156, v103
	global_load_dwordx4 v[100:103], v[138:139], off offset:256
	v_mul_f32_e32 v96, v97, v96
	v_cvt_f32_f16_sdwa v97, v149 dst_sel:DWORD dst_unused:UNUSED_PAD src0_sel:WORD_1
	v_fma_mixlo_f16 v96, v96, v161, 0 op_sel_hi:[0,1,0]
	ds_write_b16 v124, v96 offset:7680
	v_cvt_f32_f16_sdwa v96, v133 dst_sel:DWORD dst_unused:UNUSED_PAD src0_sel:WORD_1
	v_mul_f32_e32 v97, v153, v97
	v_fmac_f32_e32 v97, v156, v99
	v_mul_f32_e32 v96, v97, v96
	v_fma_mixlo_f16 v96, v96, v161, 0 op_sel:[0,1,0] op_sel_hi:[0,1,0]
	ds_write_b16 v124, v96 offset:7936
	global_load_dwordx4 v[96:99], v[140:141], off offset:256
	s_waitcnt vmcnt(1)
	v_cvt_f32_f16_e32 v105, v100
	v_mul_f32_e32 v105, v153, v105
	v_fmac_f32_e32 v105, v156, v92
	s_waitcnt vmcnt(0)
	v_cvt_f32_f16_e32 v104, v96
	v_mul_f32_e32 v92, v105, v104
	global_load_dwordx4 v[104:107], v[136:137], off offset:256
	s_waitcnt vmcnt(0)
	v_fma_mixlo_f16 v92, v92, v104, 0 op_sel_hi:[0,1,0]
	ds_write_b16 v124, v92 offset:32768
	v_cvt_f32_f16_sdwa v92, v96 dst_sel:DWORD dst_unused:UNUSED_PAD src0_sel:WORD_1
	v_cvt_f32_f16_sdwa v96, v100 dst_sel:DWORD dst_unused:UNUSED_PAD src0_sel:WORD_1
	v_mul_f32_e32 v96, v153, v96
	v_fmac_f32_e32 v96, v156, v88
	v_mul_f32_e32 v88, v96, v92
	v_cvt_f32_f16_e32 v92, v101
	v_fma_mixlo_f16 v88, v88, v104, 0 op_sel:[0,1,0] op_sel_hi:[0,1,0]
	ds_write_b16 v124, v88 offset:33024
	v_cvt_f32_f16_e32 v88, v97
	v_mul_f32_e32 v92, v153, v92
	v_fmac_f32_e32 v92, v156, v84
	v_mul_f32_e32 v84, v92, v88
	v_cvt_f32_f16_sdwa v88, v101 dst_sel:DWORD dst_unused:UNUSED_PAD src0_sel:WORD_1
	v_fma_mixlo_f16 v84, v84, v105, 0 op_sel_hi:[0,1,0]
	ds_write_b16 v124, v84 offset:33280
	v_cvt_f32_f16_sdwa v84, v97 dst_sel:DWORD dst_unused:UNUSED_PAD src0_sel:WORD_1
	v_mul_f32_e32 v88, v153, v88
	v_fmac_f32_e32 v88, v156, v80
	v_mul_f32_e32 v80, v88, v84
	v_cvt_f32_f16_e32 v84, v102
	v_fma_mixlo_f16 v80, v80, v105, 0 op_sel:[0,1,0] op_sel_hi:[0,1,0]
	ds_write_b16 v124, v80 offset:33536
	v_cvt_f32_f16_e32 v80, v98
	v_mul_f32_e32 v84, v153, v84
	v_fmac_f32_e32 v84, v156, v76
	v_mul_f32_e32 v76, v84, v80
	v_cvt_f32_f16_sdwa v80, v102 dst_sel:DWORD dst_unused:UNUSED_PAD src0_sel:WORD_1
	v_fma_mixlo_f16 v76, v76, v106, 0 op_sel_hi:[0,1,0]
	ds_write_b16 v124, v76 offset:33792
	v_cvt_f32_f16_sdwa v76, v98 dst_sel:DWORD dst_unused:UNUSED_PAD src0_sel:WORD_1
	v_mul_f32_e32 v80, v153, v80
	v_fmac_f32_e32 v80, v156, v72
	v_or_b32_e32 v84, s2, v145
	v_mul_f32_e32 v72, v80, v76
	v_cvt_f32_f16_e32 v76, v103
	v_fma_mixlo_f16 v72, v72, v106, 0 op_sel:[0,1,0] op_sel_hi:[0,1,0]
	ds_write_b16 v124, v72 offset:34048
	v_cvt_f32_f16_e32 v72, v99
	v_mul_f32_e32 v76, v153, v76
	v_fmac_f32_e32 v76, v156, v68
	s_lshl_b64 s[2:3], s[38:39], 1
	v_mul_f32_e32 v68, v76, v72
	v_cvt_f32_f16_sdwa v72, v103 dst_sel:DWORD dst_unused:UNUSED_PAD src0_sel:WORD_1
	global_load_dwordx4 v[100:103], v[138:139], off offset:272
	v_fma_mixlo_f16 v68, v68, v107, 0 op_sel_hi:[0,1,0]
	ds_write_b16 v124, v68 offset:34304
	v_cvt_f32_f16_sdwa v68, v99 dst_sel:DWORD dst_unused:UNUSED_PAD src0_sel:WORD_1
	global_load_dwordx4 v[96:99], v[140:141], off offset:272
	v_mul_f32_e32 v72, v153, v72
	v_fmac_f32_e32 v72, v156, v64
	v_mul_f32_e32 v64, v72, v68
	v_fma_mixlo_f16 v64, v64, v107, 0 op_sel:[0,1,0] op_sel_hi:[0,1,0]
	global_load_dwordx4 v[104:107], v[136:137], off offset:272
	ds_write_b16 v124, v64 offset:34560
	s_add_u32 s2, s24, s2
	v_readlane_b32 s24, v253, 46
	s_addc_u32 s3, s24, s3
	s_waitcnt vmcnt(2)
	v_cvt_f32_f16_e32 v68, v100
	s_waitcnt vmcnt(1)
	v_cvt_f32_f16_e32 v64, v96
	v_mul_f32_e32 v68, v153, v68
	v_fmac_f32_e32 v68, v156, v93
	v_mul_f32_e32 v64, v68, v64
	v_cvt_f32_f16_sdwa v68, v100 dst_sel:DWORD dst_unused:UNUSED_PAD src0_sel:WORD_1
	s_waitcnt vmcnt(0)
; template <int MODE, int TB>
; DI void toeplitz_task(const Params& P, int layer, int set, int cg, int chunk, char* smem) {
;     ...
;       for (int v = 0; v < 4; ++v) {
;         const int t = t0 + 8 * v;
;         if (MODE == 0) {
;           const half8 x1 = *(const half8*)(hT + (size_t)(bb * 2048 + 512 + c) * L + t);
;           const half8 uu = *(const half8*)(Urow + t);
;           half8 o;
; #pragma unroll
;           for (int r = 0; r < 8; ++r) o[r] = (h16)((float)x1[r] * (acc[ta][r][v] * invs + (float)uu[r] * bias));
;           *(half8*)(z1T + (size_t)(bb * 512 + c) * L + t) = o;
;         } else {
;           const half8 x2 = *(const half8*)(hT + (size_t)(bb * 2048 + 1024 + c) * L + t);
;           const half8 gt = *(const half8*)(hT + (size_t)(bb * 2048 + 1536 + c) * L + t);
;           const half8 uu = *(const half8*)(Urow + t);
; #pragma unroll
;           for (int r = 0; r < 8; ++r) {
;             const float y = (float)x2[r] * (acc[ta][r][v] * invs + (float)uu[r] * bias) * (float)gt[r];
;             const int tl = t - tbh + r;
;             *(h16*)(stg + ((tl * 16 + bb) * 8 + w) * 2) = (h16)y;
;           }
	v_fma_mixlo_f16 v64, v64, v104, 0 op_sel_hi:[0,1,0]
	ds_write_b16 v124, v64 offset:34816
	v_cvt_f32_f16_sdwa v64, v96 dst_sel:DWORD dst_unused:UNUSED_PAD src0_sel:WORD_1
	v_mul_f32_e32 v68, v153, v68
	v_fmac_f32_e32 v68, v156, v89
	v_mul_f32_e32 v64, v68, v64
	v_cvt_f32_f16_e32 v68, v101
	v_fma_mixlo_f16 v64, v64, v104, 0 op_sel:[0,1,0] op_sel_hi:[0,1,0]
	ds_write_b16 v124, v64 offset:35072
	v_cvt_f32_f16_e32 v64, v97
	v_mul_f32_e32 v68, v153, v68
	v_fmac_f32_e32 v68, v156, v85
	v_lshl_add_u32 v85, v142, 4, v144
	v_mul_f32_e32 v64, v68, v64
	v_cvt_f32_f16_sdwa v68, v101 dst_sel:DWORD dst_unused:UNUSED_PAD src0_sel:WORD_1
	v_fma_mixlo_f16 v64, v64, v105, 0 op_sel_hi:[0,1,0]
	ds_write_b16 v124, v64 offset:35328
	v_cvt_f32_f16_sdwa v64, v97 dst_sel:DWORD dst_unused:UNUSED_PAD src0_sel:WORD_1
	v_mul_f32_e32 v68, v153, v68
	v_fmac_f32_e32 v68, v156, v81
	v_mul_f32_e32 v64, v68, v64
	v_cvt_f32_f16_e32 v68, v102
	v_fma_mixlo_f16 v64, v64, v105, 0 op_sel:[0,1,0] op_sel_hi:[0,1,0]
	ds_write_b16 v124, v64 offset:35584
	v_cvt_f32_f16_e32 v64, v98
	v_mul_f32_e32 v68, v153, v68
	v_fmac_f32_e32 v68, v156, v77
	v_mul_f32_e32 v64, v68, v64
	v_cvt_f32_f16_sdwa v68, v102 dst_sel:DWORD dst_unused:UNUSED_PAD src0_sel:WORD_1
	v_fma_mixlo_f16 v64, v64, v106, 0 op_sel_hi:[0,1,0]
	ds_write_b16 v124, v64 offset:35840
	v_cvt_f32_f16_sdwa v64, v98 dst_sel:DWORD dst_unused:UNUSED_PAD src0_sel:WORD_1
	v_mul_f32_e32 v68, v153, v68
	v_fmac_f32_e32 v68, v156, v73
	v_mul_f32_e32 v64, v68, v64
	v_cvt_f32_f16_e32 v68, v103
	v_fma_mixlo_f16 v64, v64, v106, 0 op_sel:[0,1,0] op_sel_hi:[0,1,0]
	ds_write_b16 v124, v64 offset:36096
	v_cvt_f32_f16_e32 v64, v99
	v_mul_f32_e32 v68, v153, v68
	v_fmac_f32_e32 v68, v156, v69
	v_mul_f32_e32 v64, v68, v64
	v_cvt_f32_f16_sdwa v68, v103 dst_sel:DWORD dst_unused:UNUSED_PAD src0_sel:WORD_1
	global_load_dwordx4 v[100:103], v[138:139], off offset:288
	v_fma_mixlo_f16 v64, v64, v107, 0 op_sel_hi:[0,1,0]
	ds_write_b16 v124, v64 offset:36352
	v_cvt_f32_f16_sdwa v64, v99 dst_sel:DWORD dst_unused:UNUSED_PAD src0_sel:WORD_1
	global_load_dwordx4 v[96:99], v[140:141], off offset:288
	v_mul_f32_e32 v68, v153, v68
	v_fmac_f32_e32 v68, v156, v65
	v_mul_f32_e32 v64, v68, v64
	v_fma_mixlo_f16 v64, v64, v107, 0 op_sel:[0,1,0] op_sel_hi:[0,1,0]
	global_load_dwordx4 v[104:107], v[136:137], off offset:288
	ds_write_b16 v124, v64 offset:36608
	v_mov_b64_e32 v[68:69], s[2:3]
	s_waitcnt vmcnt(2)
	v_cvt_f32_f16_e32 v65, v100
	s_waitcnt vmcnt(1)
	v_cvt_f32_f16_e32 v64, v96
	v_mul_f32_e32 v65, v153, v65
	v_fmac_f32_e32 v65, v156, v94
	v_mul_f32_e32 v64, v65, v64
	v_cvt_f32_f16_sdwa v65, v100 dst_sel:DWORD dst_unused:UNUSED_PAD src0_sel:WORD_1
	s_waitcnt vmcnt(0)
	v_fma_mixlo_f16 v64, v64, v104, 0 op_sel_hi:[0,1,0]
	ds_write_b16 v124, v64 offset:36864
	v_cvt_f32_f16_sdwa v64, v96 dst_sel:DWORD dst_unused:UNUSED_PAD src0_sel:WORD_1
	v_mul_f32_e32 v65, v153, v65
	v_fmac_f32_e32 v65, v156, v90
	v_mul_f32_e32 v64, v65, v64
	v_cvt_f32_f16_e32 v65, v101
	v_fma_mixlo_f16 v64, v64, v104, 0 op_sel:[0,1,0] op_sel_hi:[0,1,0]
	ds_write_b16 v124, v64 offset:37120
	v_cvt_f32_f16_e32 v64, v97
	v_mul_f32_e32 v65, v153, v65
	v_fmac_f32_e32 v65, v156, v86
	v_mul_f32_e32 v64, v65, v64
	v_cvt_f32_f16_sdwa v65, v101 dst_sel:DWORD dst_unused:UNUSED_PAD src0_sel:WORD_1
	v_fma_mixlo_f16 v64, v64, v105, 0 op_sel_hi:[0,1,0]
	ds_write_b16 v124, v64 offset:37376
	v_cvt_f32_f16_sdwa v64, v97 dst_sel:DWORD dst_unused:UNUSED_PAD src0_sel:WORD_1
	v_mul_f32_e32 v65, v153, v65
	v_fmac_f32_e32 v65, v156, v82
	v_mul_f32_e32 v64, v65, v64
	v_cvt_f32_f16_e32 v65, v102
	v_fma_mixlo_f16 v64, v64, v105, 0 op_sel:[0,1,0] op_sel_hi:[0,1,0]
	ds_write_b16 v124, v64 offset:37632
	v_cvt_f32_f16_e32 v64, v98
	v_mul_f32_e32 v65, v153, v65
	v_fmac_f32_e32 v65, v156, v78
	v_mul_f32_e32 v64, v65, v64
	v_cvt_f32_f16_sdwa v65, v102 dst_sel:DWORD dst_unused:UNUSED_PAD src0_sel:WORD_1
	v_fma_mixlo_f16 v64, v64, v106, 0 op_sel_hi:[0,1,0]
	ds_write_b16 v124, v64 offset:37888
	v_cvt_f32_f16_sdwa v64, v98 dst_sel:DWORD dst_unused:UNUSED_PAD src0_sel:WORD_1
	v_mul_f32_e32 v65, v153, v65
	v_fmac_f32_e32 v65, v156, v74
	v_mul_f32_e32 v64, v65, v64
	v_cvt_f32_f16_e32 v65, v103
	v_fma_mixlo_f16 v64, v64, v106, 0 op_sel:[0,1,0] op_sel_hi:[0,1,0]
	ds_write_b16 v124, v64 offset:38144
	v_cvt_f32_f16_e32 v64, v99
	v_mul_f32_e32 v65, v153, v65
	v_fmac_f32_e32 v65, v156, v70
	v_or_b32_e32 v70, v134, v84
	v_mul_f32_e32 v64, v65, v64
	v_cvt_f32_f16_sdwa v65, v103 dst_sel:DWORD dst_unused:UNUSED_PAD src0_sel:WORD_1
	global_load_dwordx4 v[100:103], v[138:139], off offset:304
	v_fma_mixlo_f16 v64, v64, v107, 0 op_sel_hi:[0,1,0]
	ds_write_b16 v124, v64 offset:38400
	v_cvt_f32_f16_sdwa v64, v99 dst_sel:DWORD dst_unused:UNUSED_PAD src0_sel:WORD_1
	v_mul_f32_e32 v65, v153, v65
	v_fmac_f32_e32 v65, v156, v66
	global_load_dwordx4 v[96:99], v[140:141], off offset:304
	v_mul_f32_e32 v64, v65, v64
	v_fma_mixlo_f16 v64, v64, v107, 0 op_sel:[0,1,0] op_sel_hi:[0,1,0]
	ds_write_b16 v124, v64 offset:38656
	s_waitcnt vmcnt(1)
	v_cvt_f32_f16_e32 v65, v100
	v_mul_f32_e32 v65, v153, v65
	v_fmac_f32_e32 v65, v156, v95
	global_load_dwordx4 v[92:95], v[136:137], off offset:304
	s_waitcnt vmcnt(1)
	v_cvt_f32_f16_e32 v64, v96
	v_mul_f32_e32 v64, v65, v64
	v_cvt_f32_f16_sdwa v65, v100 dst_sel:DWORD dst_unused:UNUSED_PAD src0_sel:WORD_1
	v_mul_f32_e32 v65, v153, v65
	v_fmac_f32_e32 v65, v156, v91
	s_waitcnt vmcnt(0)
;   DI int item(int i) const { const int li = j + i * nxb; if (li >= per) return -1; const int lin = xcd * per + li; return lin < total ? lin : -1; }
; template <int MODE, int TB>
; DI void toeplitz_task(const Params& P, int layer, int set, int cg, int chunk, char* smem) {
;     ...
;           const half8 x2 = *(const half8*)(hT + (size_t)(bb * 2048 + 1024 + c) * L + t);
;           const half8 gt = *(const half8*)(hT + (size_t)(bb * 2048 + 1536 + c) * L + t);
;           const half8 uu = *(const half8*)(Urow + t);
; #pragma unroll
;           for (int r = 0; r < 8; ++r) {
;             const float y = (float)x2[r] * (acc[ta][r][v] * invs + (float)uu[r] * bias) * (float)gt[r];
;             const int tl = t - tbh + r;
;             *(h16*)(stg + ((tl * 16 + bb) * 8 + w) * 2) = (h16)y;
;           }
;         }
;       }
;     }
;     if (MODE == 1) {
;       __syncthreads();
;       h16* yb = (h16*)(P.ws + WS_YB);
; #pragma unroll
;       for (int i = 0; i < 8; ++i) {
;         const int item = tid + 512 * i;
;         const int b = item >> 8, tl = item & 255;
;         const size_t tok = set ? (size_t)T_LAT + b * CTXL + tbh + tl : (size_t)b * SEQ + tbh + tl;
;         *(half8*)(yb + tok * LDY + cg * 8) = *(const half8*)(stg + (tl * 16 + b) * 16);
;       }
;       __syncthreads();
	v_fma_mixlo_f16 v64, v64, v92, 0 op_sel_hi:[0,1,0]
	ds_write_b16 v124, v64 offset:38912
	v_cvt_f32_f16_sdwa v64, v96 dst_sel:DWORD dst_unused:UNUSED_PAD src0_sel:WORD_1
	v_mul_f32_e32 v64, v65, v64
	v_cvt_f32_f16_e32 v65, v101
	v_fma_mixlo_f16 v64, v64, v92, 0 op_sel:[0,1,0] op_sel_hi:[0,1,0]
	ds_write_b16 v124, v64 offset:39168
	v_cvt_f32_f16_e32 v64, v97
	v_mul_f32_e32 v65, v153, v65
	v_fmac_f32_e32 v65, v156, v87
	v_mul_f32_e32 v64, v65, v64
	v_cvt_f32_f16_sdwa v65, v101 dst_sel:DWORD dst_unused:UNUSED_PAD src0_sel:WORD_1
	v_fma_mixlo_f16 v64, v64, v93, 0 op_sel_hi:[0,1,0]
	ds_write_b16 v124, v64 offset:39424
	v_cvt_f32_f16_sdwa v64, v97 dst_sel:DWORD dst_unused:UNUSED_PAD src0_sel:WORD_1
	v_mul_f32_e32 v65, v153, v65
	v_fmac_f32_e32 v65, v156, v83
	v_mul_f32_e32 v64, v65, v64
	v_cvt_f32_f16_e32 v65, v102
	v_fma_mixlo_f16 v64, v64, v93, 0 op_sel:[0,1,0] op_sel_hi:[0,1,0]
	ds_write_b16 v124, v64 offset:39680
	v_cvt_f32_f16_e32 v64, v98
	v_mul_f32_e32 v65, v153, v65
	v_fmac_f32_e32 v65, v156, v79
	v_mul_f32_e32 v64, v65, v64
	v_cvt_f32_f16_sdwa v65, v102 dst_sel:DWORD dst_unused:UNUSED_PAD src0_sel:WORD_1
	v_fma_mixlo_f16 v64, v64, v94, 0 op_sel_hi:[0,1,0]
	ds_write_b16 v124, v64 offset:39936
	v_cvt_f32_f16_sdwa v64, v98 dst_sel:DWORD dst_unused:UNUSED_PAD src0_sel:WORD_1
	v_mul_f32_e32 v65, v153, v65
	v_fmac_f32_e32 v65, v156, v75
	v_mul_f32_e32 v64, v65, v64
	v_cvt_f32_f16_e32 v65, v103
	v_fma_mixlo_f16 v64, v64, v94, 0 op_sel:[0,1,0] op_sel_hi:[0,1,0]
	ds_write_b16 v124, v64 offset:40192
	v_cvt_f32_f16_e32 v64, v99
	v_mul_f32_e32 v65, v153, v65
	v_fmac_f32_e32 v65, v156, v71
	v_mad_u64_u32 v[70:71], s[2:3], v70, s4, v[68:69]
	v_mul_f32_e32 v64, v65, v64
	v_cvt_f32_f16_sdwa v65, v103 dst_sel:DWORD dst_unused:UNUSED_PAD src0_sel:WORD_1
	v_fma_mixlo_f16 v64, v64, v95, 0 op_sel_hi:[0,1,0]
	ds_write_b16 v124, v64 offset:40448
	v_cvt_f32_f16_sdwa v64, v99 dst_sel:DWORD dst_unused:UNUSED_PAD src0_sel:WORD_1
	v_mul_f32_e32 v65, v153, v65
	v_fmac_f32_e32 v65, v156, v67
	v_mad_i32_i24 v71, v135, s4, v71
	v_mul_f32_e32 v64, v65, v64
	v_fma_mixlo_f16 v64, v64, v95, 0 op_sel:[0,1,0] op_sel_hi:[0,1,0]
	ds_write_b16 v124, v64 offset:40704
	s_waitcnt lgkmcnt(0)
	s_barrier
	ds_read_b128 v[64:67], v85
	s_waitcnt lgkmcnt(0)
	global_store_dwordx4 v[70:71], v[64:67], off
	s_nop 1
	v_add_u32_e32 v64, 0x200, v157
	v_ashrrev_i32_e32 v64, 8, v64
	v_ashrrev_i32_e32 v65, 31, v64
	v_lshl_add_u32 v86, v64, 4, v144
	v_lshlrev_b64 v[70:71], 11, v[64:65]
	ds_read_b128 v[64:67], v86
	v_or_b32_e32 v72, v70, v84
	v_mad_u64_u32 v[72:73], s[2:3], v72, s4, v[68:69]
	v_mad_i32_i24 v73, v71, s4, v73
	s_waitcnt lgkmcnt(0)
	global_store_dwordx4 v[72:73], v[64:67], off
	s_nop 1
	v_add_u32_e32 v64, 0x400, v157
	v_ashrrev_i32_e32 v64, 8, v64
	v_ashrrev_i32_e32 v65, 31, v64
	v_lshl_add_u32 v87, v64, 4, v144
	v_lshlrev_b64 v[74:75], 11, v[64:65]
	ds_read_b128 v[64:67], v87
	v_or_b32_e32 v72, v74, v84
	v_mad_u64_u32 v[72:73], s[2:3], v72, s4, v[68:69]
	v_mad_i32_i24 v73, v75, s4, v73
	s_waitcnt lgkmcnt(0)
	global_store_dwordx4 v[72:73], v[64:67], off
	s_nop 1
	v_add_u32_e32 v64, 0x600, v157
	v_ashrrev_i32_e32 v64, 8, v64
	v_ashrrev_i32_e32 v65, 31, v64
	v_lshl_add_u32 v88, v64, 4, v144
	v_lshlrev_b64 v[72:73], 11, v[64:65]
	ds_read_b128 v[64:67], v88
	v_or_b32_e32 v76, v72, v84
	v_mad_u64_u32 v[76:77], s[2:3], v76, s4, v[68:69]
	v_mad_i32_i24 v77, v73, s4, v77
	s_waitcnt lgkmcnt(0)
	global_store_dwordx4 v[76:77], v[64:67], off
	s_nop 1
	v_add_u32_e32 v64, 0x800, v157
	v_ashrrev_i32_e32 v64, 8, v64
	v_ashrrev_i32_e32 v65, 31, v64
	v_lshl_add_u32 v89, v64, 4, v144
	v_lshlrev_b64 v[78:79], 11, v[64:65]
	ds_read_b128 v[64:67], v89
	v_or_b32_e32 v76, v78, v84
	v_mad_u64_u32 v[76:77], s[2:3], v76, s4, v[68:69]
	v_mad_i32_i24 v77, v79, s4, v77
	s_waitcnt lgkmcnt(0)
	global_store_dwordx4 v[76:77], v[64:67], off
	s_nop 1
	v_add_u32_e32 v64, 0xa00, v157
	v_ashrrev_i32_e32 v64, 8, v64
	v_ashrrev_i32_e32 v65, 31, v64
	v_lshl_add_u32 v90, v64, 4, v144
	v_lshlrev_b64 v[76:77], 11, v[64:65]
	ds_read_b128 v[64:67], v90
	v_or_b32_e32 v80, v76, v84
	v_mad_u64_u32 v[80:81], s[2:3], v80, s4, v[68:69]
	v_mad_i32_i24 v81, v77, s4, v81
	s_waitcnt lgkmcnt(0)
	global_store_dwordx4 v[80:81], v[64:67], off
	s_nop 1
	v_add_u32_e32 v64, 0xc00, v157
	v_ashrrev_i32_e32 v64, 8, v64
	v_ashrrev_i32_e32 v65, 31, v64
	v_lshl_add_u32 v91, v64, 4, v144
	v_lshlrev_b64 v[82:83], 11, v[64:65]
	ds_read_b128 v[64:67], v91
	v_or_b32_e32 v80, v82, v84
	v_mad_u64_u32 v[80:81], s[2:3], v80, s4, v[68:69]
	v_mad_i32_i24 v81, v83, s4, v81
	s_waitcnt lgkmcnt(0)
	global_store_dwordx4 v[80:81], v[64:67], off
	s_nop 1
	v_add_u32_e32 v64, 0xe00, v157
	v_ashrrev_i32_e32 v64, 8, v64
	v_ashrrev_i32_e32 v65, 31, v64
	v_lshl_add_u32 v92, v64, 4, v144
	v_lshlrev_b64 v[80:81], 11, v[64:65]
	ds_read_b128 v[64:67], v92
	v_or_b32_e32 v93, v80, v84
	v_mad_u64_u32 v[94:95], s[2:3], v93, s4, v[68:69]
	v_mad_i32_i24 v95, v81, s4, v95
	s_waitcnt lgkmcnt(0)
	global_store_dwordx4 v[94:95], v[64:67], off
	s_barrier
; template <int MODE, int TB>
; DI void toeplitz_task(const Params& P, int layer, int set, int cg, int chunk, char* smem) {
;     ...
;     for (int hf = 0; hf < TB / 2; ++hf) {
;     const int tbh = tb + 256 * hf;
; #pragma unroll
;     for (int ta = 2 * hf; ta < 2 * hf + 2; ++ta) {
;       const int t0 = tb + 128 * ta + 32 * kg;
; #pragma unroll
;       for (int v = 0; v < 4; ++v) {
;         const int t = t0 + 8 * v;
;         if (MODE == 0) {
;           const half8 x1 = *(const half8*)(hT + (size_t)(bb * 2048 + 512 + c) * L + t);
;           const half8 uu = *(const half8*)(Urow + t);
;           half8 o;
; #pragma unroll
;           for (int r = 0; r < 8; ++r) o[r] = (h16)((float)x1[r] * (acc[ta][r][v] * invs + (float)uu[r] * bias));
;           *(half8*)(z1T + (size_t)(bb * 512 + c) * L + t) = o;
;         } else {
;           const half8 x2 = *(const half8*)(hT + (size_t)(bb * 2048 + 1024 + c) * L + t);
;           const half8 gt = *(const half8*)(hT + (size_t)(bb * 2048 + 1536 + c) * L + t);
;           const half8 uu = *(const half8*)(Urow + t);
; #pragma unroll
;           for (int r = 0; r < 8; ++r) {
;             const float y = (float)x2[r] * (acc[ta][r][v] * invs + (float)uu[r] * bias) * (float)gt[r];
;             const int tl = t - tbh + r;
;             *(h16*)(stg + ((tl * 16 + bb) * 8 + w) * 2) = (h16)y;
;           }
	global_load_dwordx4 v[64:67], v[140:141], off offset:512
	global_load_dwordx4 v[94:97], v[138:139], off offset:512
	s_waitcnt vmcnt(1)
	v_cvt_f32_f16_e32 v93, v64
	s_waitcnt vmcnt(0)
	v_cvt_f32_f16_e32 v98, v94
	v_mul_f32_e32 v98, v153, v98
	v_fmac_f32_e32 v98, v156, v60
	v_mul_f32_e32 v60, v98, v93
	global_load_dwordx4 v[98:101], v[136:137], off offset:512
	s_waitcnt vmcnt(0)
	v_fma_mixlo_f16 v60, v60, v98, 0 op_sel_hi:[0,1,0]
	ds_write_b16 v124, v60
	v_cvt_f32_f16_sdwa v60, v64 dst_sel:DWORD dst_unused:UNUSED_PAD src0_sel:WORD_1
	v_cvt_f32_f16_sdwa v64, v94 dst_sel:DWORD dst_unused:UNUSED_PAD src0_sel:WORD_1
	v_mul_f32_e32 v64, v153, v64
	v_fmac_f32_e32 v64, v156, v56
	v_mul_f32_e32 v56, v64, v60
	v_cvt_f32_f16_e32 v60, v95
	v_fma_mixlo_f16 v56, v56, v98, 0 op_sel:[0,1,0] op_sel_hi:[0,1,0]
	ds_write_b16 v124, v56 offset:256
	v_cvt_f32_f16_e32 v56, v65
	v_mul_f32_e32 v60, v153, v60
	v_fmac_f32_e32 v60, v156, v52
	v_mul_f32_e32 v52, v60, v56
	v_cvt_f32_f16_sdwa v56, v95 dst_sel:DWORD dst_unused:UNUSED_PAD src0_sel:WORD_1
	v_fma_mixlo_f16 v52, v52, v99, 0 op_sel_hi:[0,1,0]
	ds_write_b16 v124, v52 offset:512
	v_cvt_f32_f16_sdwa v52, v65 dst_sel:DWORD dst_unused:UNUSED_PAD src0_sel:WORD_1
	v_mul_f32_e32 v56, v153, v56
	v_fmac_f32_e32 v56, v156, v48
	v_mul_f32_e32 v48, v56, v52
	v_cvt_f32_f16_e32 v52, v96
	v_fma_mixlo_f16 v48, v48, v99, 0 op_sel:[0,1,0] op_sel_hi:[0,1,0]
	ds_write_b16 v124, v48 offset:768
	v_cvt_f32_f16_e32 v48, v66
	v_mul_f32_e32 v52, v153, v52
	v_fmac_f32_e32 v52, v156, v44
	v_mul_f32_e32 v44, v52, v48
	v_cvt_f32_f16_sdwa v48, v96 dst_sel:DWORD dst_unused:UNUSED_PAD src0_sel:WORD_1
	v_fma_mixlo_f16 v44, v44, v100, 0 op_sel_hi:[0,1,0]
	ds_write_b16 v124, v44 offset:1024
	v_cvt_f32_f16_sdwa v44, v66 dst_sel:DWORD dst_unused:UNUSED_PAD src0_sel:WORD_1
	v_mul_f32_e32 v48, v153, v48
	v_fmac_f32_e32 v48, v156, v40
	v_mul_f32_e32 v40, v48, v44
	v_cvt_f32_f16_e32 v44, v97
	v_fma_mixlo_f16 v40, v40, v100, 0 op_sel:[0,1,0] op_sel_hi:[0,1,0]
	ds_write_b16 v124, v40 offset:1280
	v_cvt_f32_f16_e32 v40, v67
	v_mul_f32_e32 v44, v153, v44
	v_fmac_f32_e32 v44, v156, v36
	v_mul_f32_e32 v36, v44, v40
	v_cvt_f32_f16_sdwa v40, v97 dst_sel:DWORD dst_unused:UNUSED_PAD src0_sel:WORD_1
	global_load_dwordx4 v[94:97], v[138:139], off offset:528
	v_fma_mixlo_f16 v36, v36, v101, 0 op_sel_hi:[0,1,0]
	ds_write_b16 v124, v36 offset:1536
	v_cvt_f32_f16_sdwa v36, v67 dst_sel:DWORD dst_unused:UNUSED_PAD src0_sel:WORD_1
	global_load_dwordx4 v[64:67], v[140:141], off offset:528
	v_mul_f32_e32 v40, v153, v40
	v_fmac_f32_e32 v40, v156, v32
	v_mul_f32_e32 v32, v40, v36
	v_fma_mixlo_f16 v32, v32, v101, 0 op_sel:[0,1,0] op_sel_hi:[0,1,0]
	global_load_dwordx4 v[98:101], v[136:137], off offset:528
	ds_write_b16 v124, v32 offset:1792
	s_waitcnt vmcnt(2)
	v_cvt_f32_f16_e32 v36, v94
	s_waitcnt vmcnt(1)
	v_cvt_f32_f16_e32 v32, v64
	v_mul_f32_e32 v36, v153, v36
	v_fmac_f32_e32 v36, v156, v61
	v_mul_f32_e32 v32, v36, v32
	v_cvt_f32_f16_sdwa v36, v94 dst_sel:DWORD dst_unused:UNUSED_PAD src0_sel:WORD_1
	s_waitcnt vmcnt(0)
	v_fma_mixlo_f16 v32, v32, v98, 0 op_sel_hi:[0,1,0]
	ds_write_b16 v124, v32 offset:2048
	v_cvt_f32_f16_sdwa v32, v64 dst_sel:DWORD dst_unused:UNUSED_PAD src0_sel:WORD_1
	v_mul_f32_e32 v36, v153, v36
	v_fmac_f32_e32 v36, v156, v57
	v_mul_f32_e32 v32, v36, v32
	v_cvt_f32_f16_e32 v36, v95
	v_fma_mixlo_f16 v32, v32, v98, 0 op_sel:[0,1,0] op_sel_hi:[0,1,0]
	ds_write_b16 v124, v32 offset:2304
	v_cvt_f32_f16_e32 v32, v65
	v_mul_f32_e32 v36, v153, v36
	v_fmac_f32_e32 v36, v156, v53
	v_mul_f32_e32 v32, v36, v32
	v_cvt_f32_f16_sdwa v36, v95 dst_sel:DWORD dst_unused:UNUSED_PAD src0_sel:WORD_1
	v_fma_mixlo_f16 v32, v32, v99, 0 op_sel_hi:[0,1,0]
	ds_write_b16 v124, v32 offset:2560
	v_cvt_f32_f16_sdwa v32, v65 dst_sel:DWORD dst_unused:UNUSED_PAD src0_sel:WORD_1
	v_mul_f32_e32 v36, v153, v36
	v_fmac_f32_e32 v36, v156, v49
	v_mul_f32_e32 v32, v36, v32
	v_cvt_f32_f16_e32 v36, v96
	v_fma_mixlo_f16 v32, v32, v99, 0 op_sel:[0,1,0] op_sel_hi:[0,1,0]
	ds_write_b16 v124, v32 offset:2816
	v_cvt_f32_f16_e32 v32, v66
	v_mul_f32_e32 v36, v153, v36
	v_fmac_f32_e32 v36, v156, v45
	v_mul_f32_e32 v32, v36, v32
	v_cvt_f32_f16_sdwa v36, v96 dst_sel:DWORD dst_unused:UNUSED_PAD src0_sel:WORD_1
	v_fma_mixlo_f16 v32, v32, v100, 0 op_sel_hi:[0,1,0]
	ds_write_b16 v124, v32 offset:3072
	v_cvt_f32_f16_sdwa v32, v66 dst_sel:DWORD dst_unused:UNUSED_PAD src0_sel:WORD_1
	v_mul_f32_e32 v36, v153, v36
	v_fmac_f32_e32 v36, v156, v41
	v_mul_f32_e32 v32, v36, v32
	v_cvt_f32_f16_e32 v36, v97
	v_fma_mixlo_f16 v32, v32, v100, 0 op_sel:[0,1,0] op_sel_hi:[0,1,0]
	ds_write_b16 v124, v32 offset:3328
	v_cvt_f32_f16_e32 v32, v67
	v_mul_f32_e32 v36, v153, v36
	v_fmac_f32_e32 v36, v156, v37
	v_mul_f32_e32 v32, v36, v32
	v_cvt_f32_f16_sdwa v36, v97 dst_sel:DWORD dst_unused:UNUSED_PAD src0_sel:WORD_1
	global_load_dwordx4 v[94:97], v[138:139], off offset:544
	v_fma_mixlo_f16 v32, v32, v101, 0 op_sel_hi:[0,1,0]
	ds_write_b16 v124, v32 offset:3584
	v_cvt_f32_f16_sdwa v32, v67 dst_sel:DWORD dst_unused:UNUSED_PAD src0_sel:WORD_1
	global_load_dwordx4 v[64:67], v[140:141], off offset:544
	v_mul_f32_e32 v36, v153, v36
	v_fmac_f32_e32 v36, v156, v33
	v_mul_f32_e32 v32, v36, v32
	v_fma_mixlo_f16 v32, v32, v101, 0 op_sel:[0,1,0] op_sel_hi:[0,1,0]
	global_load_dwordx4 v[98:101], v[136:137], off offset:544
	ds_write_b16 v124, v32 offset:3840
	s_waitcnt vmcnt(2)
	v_cvt_f32_f16_e32 v33, v94
	s_waitcnt vmcnt(1)
	v_cvt_f32_f16_e32 v32, v64
	v_mul_f32_e32 v33, v153, v33
	v_fmac_f32_e32 v33, v156, v62
	v_mul_f32_e32 v32, v33, v32
	v_cvt_f32_f16_sdwa v33, v94 dst_sel:DWORD dst_unused:UNUSED_PAD src0_sel:WORD_1
	s_waitcnt vmcnt(0)
; template <int MODE, int TB>
; DI void toeplitz_task(const Params& P, int layer, int set, int cg, int chunk, char* smem) {
;     ...
;       for (int v = 0; v < 4; ++v) {
;         const int t = t0 + 8 * v;
;         if (MODE == 0) {
;           const half8 x1 = *(const half8*)(hT + (size_t)(bb * 2048 + 512 + c) * L + t);
;           const half8 uu = *(const half8*)(Urow + t);
;           half8 o;
; #pragma unroll
;           for (int r = 0; r < 8; ++r) o[r] = (h16)((float)x1[r] * (acc[ta][r][v] * invs + (float)uu[r] * bias));
;           *(half8*)(z1T + (size_t)(bb * 512 + c) * L + t) = o;
;         } else {
;           const half8 x2 = *(const half8*)(hT + (size_t)(bb * 2048 + 1024 + c) * L + t);
;           const half8 gt = *(const half8*)(hT + (size_t)(bb * 2048 + 1536 + c) * L + t);
;           const half8 uu = *(const half8*)(Urow + t);
; #pragma unroll
;           for (int r = 0; r < 8; ++r) {
;             const float y = (float)x2[r] * (acc[ta][r][v] * invs + (float)uu[r] * bias) * (float)gt[r];
;             const int tl = t - tbh + r;
;             *(h16*)(stg + ((tl * 16 + bb) * 8 + w) * 2) = (h16)y;
;           }
	v_fma_mixlo_f16 v32, v32, v98, 0 op_sel_hi:[0,1,0]
	ds_write_b16 v124, v32 offset:4096
	v_cvt_f32_f16_sdwa v32, v64 dst_sel:DWORD dst_unused:UNUSED_PAD src0_sel:WORD_1
	v_mul_f32_e32 v33, v153, v33
	v_fmac_f32_e32 v33, v156, v58
	v_mul_f32_e32 v32, v33, v32
	v_cvt_f32_f16_e32 v33, v95
	v_fma_mixlo_f16 v32, v32, v98, 0 op_sel:[0,1,0] op_sel_hi:[0,1,0]
	ds_write_b16 v124, v32 offset:4352
	v_cvt_f32_f16_e32 v32, v65
	v_mul_f32_e32 v33, v153, v33
	v_fmac_f32_e32 v33, v156, v54
	v_mul_f32_e32 v32, v33, v32
	v_cvt_f32_f16_sdwa v33, v95 dst_sel:DWORD dst_unused:UNUSED_PAD src0_sel:WORD_1
	v_fma_mixlo_f16 v32, v32, v99, 0 op_sel_hi:[0,1,0]
	ds_write_b16 v124, v32 offset:4608
	v_cvt_f32_f16_sdwa v32, v65 dst_sel:DWORD dst_unused:UNUSED_PAD src0_sel:WORD_1
	v_mul_f32_e32 v33, v153, v33
	v_fmac_f32_e32 v33, v156, v50
	v_mul_f32_e32 v32, v33, v32
	v_cvt_f32_f16_e32 v33, v96
	v_fma_mixlo_f16 v32, v32, v99, 0 op_sel:[0,1,0] op_sel_hi:[0,1,0]
	ds_write_b16 v124, v32 offset:4864
	v_cvt_f32_f16_e32 v32, v66
	v_mul_f32_e32 v33, v153, v33
	v_fmac_f32_e32 v33, v156, v46
	v_mul_f32_e32 v32, v33, v32
	v_cvt_f32_f16_sdwa v33, v96 dst_sel:DWORD dst_unused:UNUSED_PAD src0_sel:WORD_1
	v_fma_mixlo_f16 v32, v32, v100, 0 op_sel_hi:[0,1,0]
	ds_write_b16 v124, v32 offset:5120
	v_cvt_f32_f16_sdwa v32, v66 dst_sel:DWORD dst_unused:UNUSED_PAD src0_sel:WORD_1
	v_mul_f32_e32 v33, v153, v33
	v_fmac_f32_e32 v33, v156, v42
	v_mul_f32_e32 v32, v33, v32
	v_cvt_f32_f16_e32 v33, v97
	v_fma_mixlo_f16 v32, v32, v100, 0 op_sel:[0,1,0] op_sel_hi:[0,1,0]
	ds_write_b16 v124, v32 offset:5376
	v_cvt_f32_f16_e32 v32, v67
	v_mul_f32_e32 v33, v153, v33
	v_fmac_f32_e32 v33, v156, v38
	v_mul_f32_e32 v32, v33, v32
	v_cvt_f32_f16_sdwa v33, v97 dst_sel:DWORD dst_unused:UNUSED_PAD src0_sel:WORD_1
	global_load_dwordx4 v[94:97], v[138:139], off offset:560
	v_fma_mixlo_f16 v32, v32, v101, 0 op_sel_hi:[0,1,0]
	ds_write_b16 v124, v32 offset:5632
	v_cvt_f32_f16_sdwa v32, v67 dst_sel:DWORD dst_unused:UNUSED_PAD src0_sel:WORD_1
	v_mul_f32_e32 v33, v153, v33
	v_fmac_f32_e32 v33, v156, v34
	global_load_dwordx4 v[64:67], v[140:141], off offset:560
	v_mul_f32_e32 v32, v33, v32
	v_fma_mixlo_f16 v32, v32, v101, 0 op_sel:[0,1,0] op_sel_hi:[0,1,0]
	ds_write_b16 v124, v32 offset:5888
	s_waitcnt vmcnt(1)
	v_cvt_f32_f16_e32 v33, v94
	v_mul_f32_e32 v33, v153, v33
	v_fmac_f32_e32 v33, v156, v63
	global_load_dwordx4 v[60:63], v[136:137], off offset:560
	s_waitcnt vmcnt(1)
	v_cvt_f32_f16_e32 v32, v64
	v_mul_f32_e32 v32, v33, v32
	v_cvt_f32_f16_sdwa v33, v94 dst_sel:DWORD dst_unused:UNUSED_PAD src0_sel:WORD_1
	v_mul_f32_e32 v33, v153, v33
	v_fmac_f32_e32 v33, v156, v59
	s_waitcnt vmcnt(0)
	v_fma_mixlo_f16 v32, v32, v60, 0 op_sel_hi:[0,1,0]
	ds_write_b16 v124, v32 offset:6144
	v_cvt_f32_f16_sdwa v32, v64 dst_sel:DWORD dst_unused:UNUSED_PAD src0_sel:WORD_1
	v_mul_f32_e32 v32, v33, v32
	v_cvt_f32_f16_e32 v33, v95
	v_fma_mixlo_f16 v32, v32, v60, 0 op_sel:[0,1,0] op_sel_hi:[0,1,0]
	ds_write_b16 v124, v32 offset:6400
	v_cvt_f32_f16_e32 v32, v65
	v_mul_f32_e32 v33, v153, v33
	v_fmac_f32_e32 v33, v156, v55
	v_mul_f32_e32 v32, v33, v32
	v_cvt_f32_f16_sdwa v33, v95 dst_sel:DWORD dst_unused:UNUSED_PAD src0_sel:WORD_1
	v_fma_mixlo_f16 v32, v32, v61, 0 op_sel_hi:[0,1,0]
	ds_write_b16 v124, v32 offset:6656
	v_cvt_f32_f16_sdwa v32, v65 dst_sel:DWORD dst_unused:UNUSED_PAD src0_sel:WORD_1
	v_mul_f32_e32 v33, v153, v33
	v_fmac_f32_e32 v33, v156, v51
	v_mul_f32_e32 v32, v33, v32
	v_cvt_f32_f16_e32 v33, v96
	v_fma_mixlo_f16 v32, v32, v61, 0 op_sel:[0,1,0] op_sel_hi:[0,1,0]
	ds_write_b16 v124, v32 offset:6912
	v_cvt_f32_f16_e32 v32, v66
	v_mul_f32_e32 v33, v153, v33
	v_fmac_f32_e32 v33, v156, v47
	v_mul_f32_e32 v32, v33, v32
	v_cvt_f32_f16_sdwa v33, v96 dst_sel:DWORD dst_unused:UNUSED_PAD src0_sel:WORD_1
	v_fma_mixlo_f16 v32, v32, v62, 0 op_sel_hi:[0,1,0]
	ds_write_b16 v124, v32 offset:7168
	v_cvt_f32_f16_sdwa v32, v66 dst_sel:DWORD dst_unused:UNUSED_PAD src0_sel:WORD_1
	v_mul_f32_e32 v33, v153, v33
	v_fmac_f32_e32 v33, v156, v43
	v_mul_f32_e32 v32, v33, v32
	v_cvt_f32_f16_e32 v33, v97
	v_fma_mixlo_f16 v32, v32, v62, 0 op_sel:[0,1,0] op_sel_hi:[0,1,0]
	ds_write_b16 v124, v32 offset:7424
	v_cvt_f32_f16_e32 v32, v67
	v_mul_f32_e32 v33, v153, v33
	v_fmac_f32_e32 v33, v156, v39
	global_load_dwordx4 v[36:39], v[138:139], off offset:768
	v_mul_f32_e32 v32, v33, v32
	v_cvt_f32_f16_sdwa v33, v97 dst_sel:DWORD dst_unused:UNUSED_PAD src0_sel:WORD_1
	v_fma_mixlo_f16 v32, v32, v63, 0 op_sel_hi:[0,1,0]
	ds_write_b16 v124, v32 offset:7680
	v_cvt_f32_f16_sdwa v32, v67 dst_sel:DWORD dst_unused:UNUSED_PAD src0_sel:WORD_1
	v_mul_f32_e32 v33, v153, v33
	v_fmac_f32_e32 v33, v156, v35
	v_mul_f32_e32 v32, v33, v32
	v_fma_mixlo_f16 v32, v32, v63, 0 op_sel:[0,1,0] op_sel_hi:[0,1,0]
	ds_write_b16 v124, v32 offset:7936
	global_load_dwordx4 v[32:35], v[140:141], off offset:768
	s_waitcnt vmcnt(1)
	v_cvt_f32_f16_e32 v41, v36
	v_mul_f32_e32 v41, v153, v41
	v_fmac_f32_e32 v41, v156, v28
	s_waitcnt vmcnt(0)
	v_cvt_f32_f16_e32 v40, v32
	v_mul_f32_e32 v28, v41, v40
	global_load_dwordx4 v[40:43], v[136:137], off offset:768
	s_waitcnt vmcnt(0)
; template <int MODE, int TB>
; DI void toeplitz_task(const Params& P, int layer, int set, int cg, int chunk, char* smem) {
;     ...
;       for (int v = 0; v < 4; ++v) {
;         const int t = t0 + 8 * v;
;         if (MODE == 0) {
;           const half8 x1 = *(const half8*)(hT + (size_t)(bb * 2048 + 512 + c) * L + t);
;           const half8 uu = *(const half8*)(Urow + t);
;           half8 o;
; #pragma unroll
;           for (int r = 0; r < 8; ++r) o[r] = (h16)((float)x1[r] * (acc[ta][r][v] * invs + (float)uu[r] * bias));
;           *(half8*)(z1T + (size_t)(bb * 512 + c) * L + t) = o;
;         } else {
;           const half8 x2 = *(const half8*)(hT + (size_t)(bb * 2048 + 1024 + c) * L + t);
;           const half8 gt = *(const half8*)(hT + (size_t)(bb * 2048 + 1536 + c) * L + t);
;           const half8 uu = *(const half8*)(Urow + t);
; #pragma unroll
;           for (int r = 0; r < 8; ++r) {
;             const float y = (float)x2[r] * (acc[ta][r][v] * invs + (float)uu[r] * bias) * (float)gt[r];
;             const int tl = t - tbh + r;
;             *(h16*)(stg + ((tl * 16 + bb) * 8 + w) * 2) = (h16)y;
;           }
	v_fma_mixlo_f16 v28, v28, v40, 0 op_sel_hi:[0,1,0]
	ds_write_b16 v124, v28 offset:32768
	v_cvt_f32_f16_sdwa v28, v32 dst_sel:DWORD dst_unused:UNUSED_PAD src0_sel:WORD_1
	v_cvt_f32_f16_sdwa v32, v36 dst_sel:DWORD dst_unused:UNUSED_PAD src0_sel:WORD_1
	v_mul_f32_e32 v32, v153, v32
	v_fmac_f32_e32 v32, v156, v24
	v_mul_f32_e32 v24, v32, v28
	v_cvt_f32_f16_e32 v28, v37
	v_fma_mixlo_f16 v24, v24, v40, 0 op_sel:[0,1,0] op_sel_hi:[0,1,0]
	ds_write_b16 v124, v24 offset:33024
	v_cvt_f32_f16_e32 v24, v33
	v_mul_f32_e32 v28, v153, v28
	v_fmac_f32_e32 v28, v156, v20
	v_mul_f32_e32 v20, v28, v24
	v_cvt_f32_f16_sdwa v24, v37 dst_sel:DWORD dst_unused:UNUSED_PAD src0_sel:WORD_1
	v_fma_mixlo_f16 v20, v20, v41, 0 op_sel_hi:[0,1,0]
	ds_write_b16 v124, v20 offset:33280
	v_cvt_f32_f16_sdwa v20, v33 dst_sel:DWORD dst_unused:UNUSED_PAD src0_sel:WORD_1
	v_mul_f32_e32 v24, v153, v24
	v_fmac_f32_e32 v24, v156, v16
	v_mul_f32_e32 v16, v24, v20
	v_cvt_f32_f16_e32 v20, v38
	v_fma_mixlo_f16 v16, v16, v41, 0 op_sel:[0,1,0] op_sel_hi:[0,1,0]
	ds_write_b16 v124, v16 offset:33536
	v_cvt_f32_f16_e32 v16, v34
	v_mul_f32_e32 v20, v153, v20
	v_fmac_f32_e32 v20, v156, v12
	v_mul_f32_e32 v12, v20, v16
	v_cvt_f32_f16_sdwa v16, v38 dst_sel:DWORD dst_unused:UNUSED_PAD src0_sel:WORD_1
	v_fma_mixlo_f16 v12, v12, v42, 0 op_sel_hi:[0,1,0]
	ds_write_b16 v124, v12 offset:33792
	v_cvt_f32_f16_sdwa v12, v34 dst_sel:DWORD dst_unused:UNUSED_PAD src0_sel:WORD_1
	v_mul_f32_e32 v16, v153, v16
	v_fmac_f32_e32 v16, v156, v8
	v_mul_f32_e32 v8, v16, v12
	v_cvt_f32_f16_e32 v12, v39
	v_fma_mixlo_f16 v8, v8, v42, 0 op_sel:[0,1,0] op_sel_hi:[0,1,0]
	ds_write_b16 v124, v8 offset:34048
	v_cvt_f32_f16_e32 v8, v35
	v_mul_f32_e32 v12, v153, v12
	v_fmac_f32_e32 v12, v156, v4
	v_mul_f32_e32 v4, v12, v8
	v_cvt_f32_f16_sdwa v8, v39 dst_sel:DWORD dst_unused:UNUSED_PAD src0_sel:WORD_1
	global_load_dwordx4 v[36:39], v[138:139], off offset:784
	v_fma_mixlo_f16 v4, v4, v43, 0 op_sel_hi:[0,1,0]
	ds_write_b16 v124, v4 offset:34304
	v_cvt_f32_f16_sdwa v4, v35 dst_sel:DWORD dst_unused:UNUSED_PAD src0_sel:WORD_1
	global_load_dwordx4 v[32:35], v[140:141], off offset:784
	v_mul_f32_e32 v8, v153, v8
	v_fmac_f32_e32 v8, v156, v0
	v_mul_f32_e32 v0, v8, v4
	v_fma_mixlo_f16 v0, v0, v43, 0 op_sel:[0,1,0] op_sel_hi:[0,1,0]
	global_load_dwordx4 v[40:43], v[136:137], off offset:784
	ds_write_b16 v124, v0 offset:34560
	s_waitcnt vmcnt(2)
	v_cvt_f32_f16_e32 v4, v36
	s_waitcnt vmcnt(1)
	v_cvt_f32_f16_e32 v0, v32
	v_mul_f32_e32 v4, v153, v4
	v_fmac_f32_e32 v4, v156, v29
	v_mul_f32_e32 v0, v4, v0
	v_cvt_f32_f16_sdwa v4, v36 dst_sel:DWORD dst_unused:UNUSED_PAD src0_sel:WORD_1
	s_waitcnt vmcnt(0)
	v_fma_mixlo_f16 v0, v0, v40, 0 op_sel_hi:[0,1,0]
	ds_write_b16 v124, v0 offset:34816
	v_cvt_f32_f16_sdwa v0, v32 dst_sel:DWORD dst_unused:UNUSED_PAD src0_sel:WORD_1
	v_mul_f32_e32 v4, v153, v4
	v_fmac_f32_e32 v4, v156, v25
	v_mul_f32_e32 v0, v4, v0
	v_cvt_f32_f16_e32 v4, v37
	v_fma_mixlo_f16 v0, v0, v40, 0 op_sel:[0,1,0] op_sel_hi:[0,1,0]
	ds_write_b16 v124, v0 offset:35072
	v_cvt_f32_f16_e32 v0, v33
	v_mul_f32_e32 v4, v153, v4
	v_fmac_f32_e32 v4, v156, v21
	v_mul_f32_e32 v0, v4, v0
	v_cvt_f32_f16_sdwa v4, v37 dst_sel:DWORD dst_unused:UNUSED_PAD src0_sel:WORD_1
	v_fma_mixlo_f16 v0, v0, v41, 0 op_sel_hi:[0,1,0]
	ds_write_b16 v124, v0 offset:35328
	v_cvt_f32_f16_sdwa v0, v33 dst_sel:DWORD dst_unused:UNUSED_PAD src0_sel:WORD_1
	v_mul_f32_e32 v4, v153, v4
	v_fmac_f32_e32 v4, v156, v17
	v_mul_f32_e32 v0, v4, v0
	v_cvt_f32_f16_e32 v4, v38
	v_fma_mixlo_f16 v0, v0, v41, 0 op_sel:[0,1,0] op_sel_hi:[0,1,0]
	ds_write_b16 v124, v0 offset:35584
	v_cvt_f32_f16_e32 v0, v34
	v_mul_f32_e32 v4, v153, v4
	v_fmac_f32_e32 v4, v156, v13
	v_mul_f32_e32 v0, v4, v0
	v_cvt_f32_f16_sdwa v4, v38 dst_sel:DWORD dst_unused:UNUSED_PAD src0_sel:WORD_1
	v_fma_mixlo_f16 v0, v0, v42, 0 op_sel_hi:[0,1,0]
	ds_write_b16 v124, v0 offset:35840
	v_cvt_f32_f16_sdwa v0, v34 dst_sel:DWORD dst_unused:UNUSED_PAD src0_sel:WORD_1
	v_mul_f32_e32 v4, v153, v4
	v_fmac_f32_e32 v4, v156, v9
	v_mul_f32_e32 v0, v4, v0
	v_cvt_f32_f16_e32 v4, v39
	v_fma_mixlo_f16 v0, v0, v42, 0 op_sel:[0,1,0] op_sel_hi:[0,1,0]
	ds_write_b16 v124, v0 offset:36096
	v_cvt_f32_f16_e32 v0, v35
	v_mul_f32_e32 v4, v153, v4
	v_fmac_f32_e32 v4, v156, v5
	v_mul_f32_e32 v0, v4, v0
	v_cvt_f32_f16_sdwa v4, v39 dst_sel:DWORD dst_unused:UNUSED_PAD src0_sel:WORD_1
	global_load_dwordx4 v[36:39], v[138:139], off offset:800
	v_fma_mixlo_f16 v0, v0, v43, 0 op_sel_hi:[0,1,0]
	ds_write_b16 v124, v0 offset:36352
	v_cvt_f32_f16_sdwa v0, v35 dst_sel:DWORD dst_unused:UNUSED_PAD src0_sel:WORD_1
	global_load_dwordx4 v[32:35], v[140:141], off offset:800
	v_mul_f32_e32 v4, v153, v4
	v_fmac_f32_e32 v4, v156, v1
	v_mul_f32_e32 v0, v4, v0
	v_fma_mixlo_f16 v0, v0, v43, 0 op_sel:[0,1,0] op_sel_hi:[0,1,0]
	global_load_dwordx4 v[40:43], v[136:137], off offset:800
	ds_write_b16 v124, v0 offset:36608
	s_waitcnt vmcnt(2)
	v_cvt_f32_f16_e32 v1, v36
	s_waitcnt vmcnt(1)
	v_cvt_f32_f16_e32 v0, v32
	v_mul_f32_e32 v1, v153, v1
	v_fmac_f32_e32 v1, v156, v30
	v_mul_f32_e32 v0, v1, v0
	v_cvt_f32_f16_sdwa v1, v36 dst_sel:DWORD dst_unused:UNUSED_PAD src0_sel:WORD_1
	s_waitcnt vmcnt(0)
;   DI int item(int i) const { const int li = j + i * nxb; if (li >= per) return -1; const int lin = xcd * per + li; return lin < total ? lin : -1; }
; template <int MODE, int TB>
; DI void toeplitz_task(const Params& P, int layer, int set, int cg, int chunk, char* smem) {
;     ...
;           const half8 x2 = *(const half8*)(hT + (size_t)(bb * 2048 + 1024 + c) * L + t);
;           const half8 gt = *(const half8*)(hT + (size_t)(bb * 2048 + 1536 + c) * L + t);
;           const half8 uu = *(const half8*)(Urow + t);
; #pragma unroll
;           for (int r = 0; r < 8; ++r) {
;             const float y = (float)x2[r] * (acc[ta][r][v] * invs + (float)uu[r] * bias) * (float)gt[r];
;             const int tl = t - tbh + r;
;             *(h16*)(stg + ((tl * 16 + bb) * 8 + w) * 2) = (h16)y;
;           }
;         }
;       }
;     }
;     if (MODE == 1) {
;       __syncthreads();
;       h16* yb = (h16*)(P.ws + WS_YB);
; #pragma unroll
;       for (int i = 0; i < 8; ++i) {
;         const int item = tid + 512 * i;
;         const int b = item >> 8, tl = item & 255;
;         const size_t tok = set ? (size_t)T_LAT + b * CTXL + tbh + tl : (size_t)b * SEQ + tbh + tl;
;         *(half8*)(yb + tok * LDY + cg * 8) = *(const half8*)(stg + (tl * 16 + b) * 16);
;       }
;       __syncthreads();
;     }
;     }
;   }
;   __syncthreads();
	v_fma_mixlo_f16 v0, v0, v40, 0 op_sel_hi:[0,1,0]
	ds_write_b16 v124, v0 offset:36864
	v_cvt_f32_f16_sdwa v0, v32 dst_sel:DWORD dst_unused:UNUSED_PAD src0_sel:WORD_1
	v_mul_f32_e32 v1, v153, v1
	v_fmac_f32_e32 v1, v156, v26
	v_mul_f32_e32 v0, v1, v0
	v_cvt_f32_f16_e32 v1, v37
	v_fma_mixlo_f16 v0, v0, v40, 0 op_sel:[0,1,0] op_sel_hi:[0,1,0]
	ds_write_b16 v124, v0 offset:37120
	v_cvt_f32_f16_e32 v0, v33
	v_mul_f32_e32 v1, v153, v1
	v_fmac_f32_e32 v1, v156, v22
	v_mul_f32_e32 v0, v1, v0
	v_cvt_f32_f16_sdwa v1, v37 dst_sel:DWORD dst_unused:UNUSED_PAD src0_sel:WORD_1
	v_fma_mixlo_f16 v0, v0, v41, 0 op_sel_hi:[0,1,0]
	ds_write_b16 v124, v0 offset:37376
	v_cvt_f32_f16_sdwa v0, v33 dst_sel:DWORD dst_unused:UNUSED_PAD src0_sel:WORD_1
	v_mul_f32_e32 v1, v153, v1
	v_fmac_f32_e32 v1, v156, v18
	v_mul_f32_e32 v0, v1, v0
	v_cvt_f32_f16_e32 v1, v38
	v_fma_mixlo_f16 v0, v0, v41, 0 op_sel:[0,1,0] op_sel_hi:[0,1,0]
	ds_write_b16 v124, v0 offset:37632
	v_cvt_f32_f16_e32 v0, v34
	v_mul_f32_e32 v1, v153, v1
	v_fmac_f32_e32 v1, v156, v14
	v_mul_f32_e32 v0, v1, v0
	v_cvt_f32_f16_sdwa v1, v38 dst_sel:DWORD dst_unused:UNUSED_PAD src0_sel:WORD_1
	v_fma_mixlo_f16 v0, v0, v42, 0 op_sel_hi:[0,1,0]
	ds_write_b16 v124, v0 offset:37888
	v_cvt_f32_f16_sdwa v0, v34 dst_sel:DWORD dst_unused:UNUSED_PAD src0_sel:WORD_1
	v_mul_f32_e32 v1, v153, v1
	v_fmac_f32_e32 v1, v156, v10
	v_mul_f32_e32 v0, v1, v0
	v_cvt_f32_f16_e32 v1, v39
	v_fma_mixlo_f16 v0, v0, v42, 0 op_sel:[0,1,0] op_sel_hi:[0,1,0]
	ds_write_b16 v124, v0 offset:38144
	v_cvt_f32_f16_e32 v0, v35
	v_mul_f32_e32 v1, v153, v1
	v_fmac_f32_e32 v1, v156, v6
	v_or_b32_e32 v6, 0x100, v84
	v_mul_f32_e32 v0, v1, v0
	v_cvt_f32_f16_sdwa v1, v39 dst_sel:DWORD dst_unused:UNUSED_PAD src0_sel:WORD_1
	global_load_dwordx4 v[36:39], v[138:139], off offset:816
	v_fma_mixlo_f16 v0, v0, v43, 0 op_sel_hi:[0,1,0]
	ds_write_b16 v124, v0 offset:38400
	v_cvt_f32_f16_sdwa v0, v35 dst_sel:DWORD dst_unused:UNUSED_PAD src0_sel:WORD_1
	v_mul_f32_e32 v1, v153, v1
	v_fmac_f32_e32 v1, v156, v2
	global_load_dwordx4 v[32:35], v[140:141], off offset:816
	v_mul_f32_e32 v0, v1, v0
	v_fma_mixlo_f16 v0, v0, v43, 0 op_sel:[0,1,0] op_sel_hi:[0,1,0]
	ds_write_b16 v124, v0 offset:38656
	v_or_b32_e32 v4, v134, v6
	v_mad_u64_u32 v[4:5], s[2:3], v4, s4, v[68:69]
	v_mad_i32_i24 v5, v135, s4, v5
	s_waitcnt vmcnt(1)
	v_cvt_f32_f16_e32 v1, v36
	v_mul_f32_e32 v1, v153, v1
	v_fmac_f32_e32 v1, v156, v31
	global_load_dwordx4 v[28:31], v[136:137], off offset:816
	s_waitcnt vmcnt(1)
	v_cvt_f32_f16_e32 v0, v32
	v_mul_f32_e32 v0, v1, v0
	v_cvt_f32_f16_sdwa v1, v36 dst_sel:DWORD dst_unused:UNUSED_PAD src0_sel:WORD_1
	v_mul_f32_e32 v1, v153, v1
	v_fmac_f32_e32 v1, v156, v27
	s_waitcnt vmcnt(0)
	v_fma_mixlo_f16 v0, v0, v28, 0 op_sel_hi:[0,1,0]
	ds_write_b16 v124, v0 offset:38912
	v_cvt_f32_f16_sdwa v0, v32 dst_sel:DWORD dst_unused:UNUSED_PAD src0_sel:WORD_1
	v_mul_f32_e32 v0, v1, v0
	v_cvt_f32_f16_e32 v1, v37
	v_fma_mixlo_f16 v0, v0, v28, 0 op_sel:[0,1,0] op_sel_hi:[0,1,0]
	ds_write_b16 v124, v0 offset:39168
	v_cvt_f32_f16_e32 v0, v33
	v_mul_f32_e32 v1, v153, v1
	v_fmac_f32_e32 v1, v156, v23
	v_mul_f32_e32 v0, v1, v0
	v_cvt_f32_f16_sdwa v1, v37 dst_sel:DWORD dst_unused:UNUSED_PAD src0_sel:WORD_1
	v_fma_mixlo_f16 v0, v0, v29, 0 op_sel_hi:[0,1,0]
	ds_write_b16 v124, v0 offset:39424
	v_cvt_f32_f16_sdwa v0, v33 dst_sel:DWORD dst_unused:UNUSED_PAD src0_sel:WORD_1
	v_mul_f32_e32 v1, v153, v1
	v_fmac_f32_e32 v1, v156, v19
	v_mul_f32_e32 v0, v1, v0
	v_cvt_f32_f16_e32 v1, v38
	v_fma_mixlo_f16 v0, v0, v29, 0 op_sel:[0,1,0] op_sel_hi:[0,1,0]
	ds_write_b16 v124, v0 offset:39680
	v_cvt_f32_f16_e32 v0, v34
	v_mul_f32_e32 v1, v153, v1
	v_fmac_f32_e32 v1, v156, v15
	v_mul_f32_e32 v0, v1, v0
	v_cvt_f32_f16_sdwa v1, v38 dst_sel:DWORD dst_unused:UNUSED_PAD src0_sel:WORD_1
	v_fma_mixlo_f16 v0, v0, v30, 0 op_sel_hi:[0,1,0]
	ds_write_b16 v124, v0 offset:39936
	v_cvt_f32_f16_sdwa v0, v34 dst_sel:DWORD dst_unused:UNUSED_PAD src0_sel:WORD_1
	v_mul_f32_e32 v1, v153, v1
	v_fmac_f32_e32 v1, v156, v11
	v_mul_f32_e32 v0, v1, v0
	v_cvt_f32_f16_e32 v1, v39
	v_fma_mixlo_f16 v0, v0, v30, 0 op_sel:[0,1,0] op_sel_hi:[0,1,0]
	ds_write_b16 v124, v0 offset:40192
	v_cvt_f32_f16_e32 v0, v35
	v_mul_f32_e32 v1, v153, v1
	v_fmac_f32_e32 v1, v156, v7
	v_mul_f32_e32 v0, v1, v0
	v_cvt_f32_f16_sdwa v1, v39 dst_sel:DWORD dst_unused:UNUSED_PAD src0_sel:WORD_1
	v_fma_mixlo_f16 v0, v0, v31, 0 op_sel_hi:[0,1,0]
	ds_write_b16 v124, v0 offset:40448
	v_cvt_f32_f16_sdwa v0, v35 dst_sel:DWORD dst_unused:UNUSED_PAD src0_sel:WORD_1
	v_mul_f32_e32 v1, v153, v1
	v_fmac_f32_e32 v1, v156, v3
	v_mul_f32_e32 v0, v1, v0
	v_fma_mixlo_f16 v0, v0, v31, 0 op_sel:[0,1,0] op_sel_hi:[0,1,0]
	ds_write_b16 v124, v0 offset:40704
	s_waitcnt lgkmcnt(0)
	s_barrier
	ds_read_b128 v[0:3], v85
	s_waitcnt lgkmcnt(0)
	global_store_dwordx4 v[4:5], v[0:3], off
	ds_read_b128 v[0:3], v86
	v_or_b32_e32 v4, v70, v6
	v_mad_u64_u32 v[4:5], s[2:3], v4, s4, v[68:69]
	v_mad_i32_i24 v5, v71, s4, v5
	s_waitcnt lgkmcnt(0)
	global_store_dwordx4 v[4:5], v[0:3], off
	ds_read_b128 v[0:3], v87
	v_or_b32_e32 v4, v74, v6
	v_mad_u64_u32 v[4:5], s[2:3], v4, s4, v[68:69]
	v_mad_i32_i24 v5, v75, s4, v5
	s_waitcnt lgkmcnt(0)
	global_store_dwordx4 v[4:5], v[0:3], off
	ds_read_b128 v[0:3], v88
	v_or_b32_e32 v4, v72, v6
	v_mad_u64_u32 v[4:5], s[2:3], v4, s4, v[68:69]
	v_mad_i32_i24 v5, v73, s4, v5
	s_waitcnt lgkmcnt(0)
	global_store_dwordx4 v[4:5], v[0:3], off
	ds_read_b128 v[0:3], v89
	v_or_b32_e32 v4, v78, v6
	v_mad_u64_u32 v[4:5], s[2:3], v4, s4, v[68:69]
	v_mad_i32_i24 v5, v79, s4, v5
	s_waitcnt lgkmcnt(0)
	global_store_dwordx4 v[4:5], v[0:3], off
	ds_read_b128 v[0:3], v90
	v_or_b32_e32 v4, v76, v6
	v_mad_u64_u32 v[4:5], s[2:3], v4, s4, v[68:69]
	v_mad_i32_i24 v5, v77, s4, v5
	s_waitcnt lgkmcnt(0)
	global_store_dwordx4 v[4:5], v[0:3], off
	ds_read_b128 v[0:3], v91
	v_or_b32_e32 v4, v82, v6
	v_mad_u64_u32 v[4:5], s[2:3], v4, s4, v[68:69]
	v_mad_i32_i24 v5, v83, s4, v5
	s_waitcnt lgkmcnt(0)
	global_store_dwordx4 v[4:5], v[0:3], off
	ds_read_b128 v[0:3], v92
	v_or_b32_e32 v4, v80, v6
	v_mad_u64_u32 v[4:5], s[2:3], v4, s4, v[68:69]
	v_mad_i32_i24 v5, v81, s4, v5
	s_waitcnt lgkmcnt(0)
	global_store_dwordx4 v[4:5], v[0:3], off
	s_barrier
	s_barrier
	s_branch .LBB0_393

;   DI int item(int i) const { const int li = j + i * nxb; if (li >= per) return -1; const int lin = xcd * per + li; return lin < total ? lin : -1; }
; template <int MODE, int TB>
; DI void toeplitz_task(const Params& P, int layer, int set, int cg, int chunk, char* smem) {
;     ...
;   const h16* krg = (const h16*)(P.ws + (set ? WS_KRC : WS_KRL)) + (size_t)(MODE * 512 + cg * 8) * KLEN;
;   h16* krs = (h16*)smem;
;   char* stg = smem + 8 * KLEN_L * 2;
;   for (int i = tid; i < KLEN; i += 512) *(half8*)(krs + i * 8) = *(const half8*)(krg + i * 8);
;   __syncthreads();
; template <int MODE>
; DI void phase_toeplitz(const Params& P, int layer, char* smem) {
;     ...
;   for (int item = blockIdx.x; item < total; item += gridDim.x) {
;     if (item < 256) {
;       const int xj = item >> 3;
;       toeplitz_task<MODE, 4>(P, layer, 0, (item & 7) + 8 * (xj >> 2), xj & 3, smem);
.LBB0_418:
	s_and_b64 vcc, exec, s[0:1]
	s_cbranch_vccz .LBB0_412
	s_lshr_b32 s1, s42, 2
	s_and_b32 s0, s42, 7
	s_and_b32 s1, s1, 0x1ffffff8
	s_or_b32 s0, s1, s0
	v_mov_b32_e32 v2, v208
	s_lshl_b32 s24, s0, 3
	s_movk_i32 s0, 0x1100
	s_nop 0
	v_cmp_gt_i32_e32 vcc, s0, v2
	s_and_saveexec_b64 s[0:1], vcc
	s_cbranch_execz .LBB0_422
	s_mul_i32 s2, s24, 0x2200
	v_readlane_b32 s25, v253, 47
	s_mul_hi_i32 s3, s24, 0x2200
	s_add_u32 s2, s25, s2
	v_readlane_b32 s25, v253, 48
	s_addc_u32 s3, s25, s3
	v_add_u32_e32 v3, 0xfffffe00, v2
	v_lshl_add_u32 v4, v2, 4, 0
	v_lshlrev_b32_e32 v0, 3, v2
	s_mov_b64 s[38:39], 0x2000
	v_ashrrev_i32_e32 v1, 31, v0
	v_lshl_add_u64 v[6:7], v[0:1], 1, s[2:3]
	global_load_dwordx4 v[12:15], v[6:7], off
	v_lshl_add_u64 v[6:7], v[6:7], 0, s[38:39]
	global_load_dwordx4 v[16:19], v[6:7], off
	v_lshl_add_u64 v[6:7], v[6:7], 0, s[38:39]
	global_load_dwordx4 v[20:23], v[6:7], off
	v_lshl_add_u64 v[6:7], v[6:7], 0, s[38:39]
	global_load_dwordx4 v[24:27], v[6:7], off
	v_lshl_add_u64 v[6:7], v[6:7], 0, s[38:39]
	global_load_dwordx4 v[28:31], v[6:7], off
	v_lshl_add_u64 v[6:7], v[6:7], 0, s[38:39]
	global_load_dwordx4 v[32:35], v[6:7], off
	v_lshl_add_u64 v[6:7], v[6:7], 0, s[38:39]
	global_load_dwordx4 v[36:39], v[6:7], off
	v_lshl_add_u64 v[6:7], v[6:7], 0, s[38:39]
	global_load_dwordx4 v[40:43], v[6:7], off
	v_lshl_add_u64 v[6:7], v[6:7], 0, s[38:39]
	global_load_dwordx4 v[44:47], v[6:7], off
	v_add_u32_e32 v3, 0x10000, v4
	v_cmp_gt_u32_e32 vcc, 0x100, v2
	s_waitcnt vmcnt(8)
	ds_write_b128 v4, v[12:15]
	s_waitcnt vmcnt(7)
	ds_write_b128 v4, v[16:19] offset:8192
	s_waitcnt vmcnt(6)
	ds_write_b128 v4, v[20:23] offset:16384
	s_waitcnt vmcnt(5)
	ds_write_b128 v4, v[24:27] offset:24576
	s_waitcnt vmcnt(4)
	ds_write_b128 v4, v[28:31] offset:32768
	s_waitcnt vmcnt(3)
	ds_write_b128 v4, v[32:35] offset:40960
	s_waitcnt vmcnt(2)
	ds_write_b128 v4, v[36:39] offset:49152
	s_waitcnt vmcnt(1)
	ds_write_b128 v4, v[40:43] offset:57344
	s_waitcnt vmcnt(0)
	s_and_saveexec_b64 s[38:39], vcc
	ds_write_b128 v3, v[44:47]
	s_mov_b64 exec, s[38:39]

; template <int MODE, int TB>
; DI void toeplitz_task(const Params& P, int layer, int set, int cg, int chunk, char* smem) {
;     ...
;     auto load_group = [&](int g, u32x4 (&dst)[2 * GS]) {
; #pragma unroll
;       for (int q = 0; q < GS; ++q) {
;         const int s = -32 + (g * GS + q) * 32 + 8 * kg;
;         const int s2 = s + 8;
;         const int sc = min(max(s, 0), L - 8), sc2 = min(max(s2, 0), L - 8);
;         dst[2 * q] = *(const u32x4*)(Urow + sc);
;         dst[2 * q + 1] = *(const u32x4*)(Urow + sc2);
;       }
;     };
;     load_group(0, cur);
;     const int abase = OFF - tb - 8 * ((lane & 15) - kg);
;     half8 afn[TB];
; #pragma unroll
;     for (int ta = 0; ta < TB; ++ta) afn[ta] = *(const half8*)(krw + abase - 32 - 128 * ta);
;     for (int g = 0; g < ngroups; ++g) {
;       load_group(g + 1 < ngroups ? g + 1 : g, nxt);
;       __builtin_amdgcn_sched_barrier(0);
; #pragma unroll
;       for (int q = 0; q < GS; ++q) {
;         const int s0 = -32 + (g * GS + q) * 32;
;         half8 af[TB];
; #pragma unroll
;         for (int ta = 0; ta < TB; ++ta) { af[ta] = afn[ta]; afn[ta] = *(const half8*)(krw + abase + s0 + 32 - 128 * ta); }
;         unsigned d[8];
;         {
;           const int sw0 = s0 + 8 * kg, sw1 = sw0 + 8;
;           const bool va = (sw0 >= 0) && (sw0 < L), vb = (sw1 >= 0) && (sw1 < L);
; #pragma unroll
;           for (int e = 0; e < 4; ++e) { d[e] = va ? cur[2 * q][e] : 0u; d[4 + e] = vb ? cur[2 * q + 1][e] : 0u; }
;         }
; #pragma unroll
;         for (int r = 0; r < 8; ++r) {
;           u32x4 bw;
; #pragma unroll
;           for (int e = 0; e < 4; ++e)
;             bw[e] = (r & 1) ? __builtin_amdgcn_alignbit(d[(r >> 1) + e + 1 > 7 ? 7 : (r >> 1) + e + 1], d[(r >> 1) + e], 16) : d[(r >> 1) + e];
;           const half8 bfr = __builtin_bit_cast(half8, bw);
; #pragma unroll
;           for (int ta = 0; ta < TB; ++ta) acc[ta][r] = __builtin_amdgcn_mfma_f32_16x16x32_f16(af[ta], bfr, acc[ta][r], 0, 0, 0);
;         }
.LBB0_423:
	s_waitcnt vmcnt(3)
	v_mov_b64_e32 v[166:167], v[2:3]
	v_mov_b64_e32 v[164:165], v[0:1]
	v_subrev_u32_e32 v0, 32, v162
	v_min_u32_e32 v0, 0x7f0, v0
	v_min_u32_e32 v2, 0x7f8, v162
	v_lshlrev_b32_e32 v128, 1, v0
	v_min_u32_e32 v3, 0x7f0, v162
	v_lshl_add_u64 v[0:1], v[154:155], 0, v[128:129]
	v_lshlrev_b32_e32 v128, 1, v2
	v_lshl_add_u64 v[168:169], v[154:155], 0, v[128:129]
	v_lshlrev_b32_e32 v128, 1, v3
	global_load_dwordx4 v[142:145], v[158:159], off
	s_nop 0
	global_load_dwordx4 v[0:3], v[0:1], off offset:16
	s_nop 0
	global_load_dwordx4 v[168:171], v[168:169], off
	v_lshl_add_u64 v[172:173], v[154:155], 0, v[128:129]
	global_load_dwordx4 v[172:175], v[172:173], off offset:16
	v_add_u32_e32 v128, s1, v161
	ds_read_b128 v[176:179], v128 offset:8256
	ds_read_b128 v[180:183], v128 offset:8000
	ds_read_b128 v[184:187], v128 offset:7744
	ds_read_b128 v[188:191], v128 offset:7488
	s_waitcnt vmcnt(6) lgkmcnt(3)
	v_mfma_f32_16x16x32_f16 v[28:31], v[176:179], v[100:103], v[28:31]
	v_perm_b32 v192, v100, v101, s29
	v_perm_b32 v193, v101, v102, s29
	v_perm_b32 v194, v102, v103, s29
	s_waitcnt lgkmcnt(2)
	v_mfma_f32_16x16x32_f16 v[52:55], v[180:183], v[100:103], v[52:55]
	v_perm_b32 v195, v103, v164, s29
	v_pk_mov_b32 v[198:199], v[102:103], v[164:165] op_sel:[1,0]
	v_pk_mov_b32 v[196:197], v[100:101], v[102:103] op_sel:[1,0]
	s_waitcnt lgkmcnt(1)
	v_mfma_f32_16x16x32_f16 v[80:83], v[184:187], v[100:103], v[80:83]
	v_perm_b32 v203, v164, v165, s29
	v_mov_b32_e32 v200, v193
	v_mov_b32_e32 v201, v194
	s_waitcnt lgkmcnt(0)
	v_mfma_f32_16x16x32_f16 v[124:127], v[188:191], v[100:103], v[124:127]
	v_mov_b32_e32 v100, v102
	v_mov_b32_e32 v101, v103
	v_mov_b32_e32 v102, v164
	v_mov_b32_e32 v103, v165
	v_mov_b32_e32 v202, v195
	v_mfma_f32_16x16x32_f16 v[48:51], v[176:179], v[192:195], v[48:51]
	s_addk_i32 s1, 0x80
	v_add_u32_e32 v162, 64, v162
	v_lshl_add_u64 v[158:159], v[158:159], 0, s[22:23]
	v_mfma_f32_16x16x32_f16 v[116:119], v[176:179], v[100:103], v[116:119]
	s_cmp_lg_u32 s1, 0
	v_mfma_f32_16x16x32_f16 v[112:115], v[180:183], v[100:103], v[112:115]
	v_mfma_f32_16x16x32_f16 v[108:111], v[184:187], v[100:103], v[108:111]
	v_mfma_f32_16x16x32_f16 v[100:103], v[188:191], v[100:103], v[120:123]
	s_nop 2
	v_perm_b32 v123, v165, v166, s29
	v_mfma_f32_16x16x32_f16 v[20:23], v[176:179], v[200:203], v[20:23]
	v_mov_b32_e32 v120, v194
	v_mov_b32_e32 v121, v195
	v_mov_b32_e32 v122, v203
	v_mfma_f32_16x16x32_f16 v[16:19], v[180:183], v[200:203], v[16:19]
	v_mfma_f32_16x16x32_f16 v[12:15], v[184:187], v[200:203], v[12:15]
	v_mfma_f32_16x16x32_f16 v[24:27], v[188:191], v[200:203], v[24:27]
	v_pk_mov_b32 v[200:201], v[164:165], v[166:167] op_sel:[1,0]
	v_perm_b32 v167, v166, v167, s29
	v_mov_b32_e32 v164, v195
	v_mov_b32_e32 v165, v203
	v_mov_b32_e32 v166, v123
	v_mfma_f32_16x16x32_f16 v[44:47], v[180:183], v[192:195], v[44:47]
	s_waitcnt vmcnt(5)
	v_perm_b32 v203, v5, v6, s29
	v_mfma_f32_16x16x32_f16 v[40:43], v[184:187], v[192:195], v[40:43]
	v_mfma_f32_16x16x32_f16 v[96:99], v[176:179], v[196:199], v[96:99]
	v_mfma_f32_16x16x32_f16 v[88:91], v[180:183], v[196:199], v[88:91]
	v_mfma_f32_16x16x32_f16 v[76:79], v[184:187], v[196:199], v[76:79]
	v_mfma_f32_16x16x32_f16 v[68:71], v[176:179], v[120:123], v[68:71]
	v_mfma_f32_16x16x32_f16 v[64:67], v[180:183], v[120:123], v[64:67]
	v_mfma_f32_16x16x32_f16 v[60:63], v[184:187], v[120:123], v[60:63]
	v_mfma_f32_16x16x32_f16 v[92:95], v[176:179], v[198:201], v[92:95]
	v_mfma_f32_16x16x32_f16 v[84:87], v[180:183], v[198:201], v[84:87]
	v_mfma_f32_16x16x32_f16 v[72:75], v[184:187], v[198:201], v[72:75]
	v_mfma_f32_16x16x32_f16 v[130:133], v[176:179], v[164:167], v[130:133]
	ds_read_b128 v[176:179], v128 offset:8320
	v_mfma_f32_16x16x32_f16 v[134:137], v[180:183], v[164:167], v[134:137]
	ds_read_b128 v[180:183], v128 offset:7808
	v_mfma_f32_16x16x32_f16 v[138:141], v[184:187], v[164:167], v[138:141]
	ds_read_b128 v[184:187], v128 offset:7552
	v_mfma_f32_16x16x32_f16 v[146:149], v[188:191], v[164:167], v[146:149]
	ds_read_b128 v[164:167], v128 offset:8064
	v_mfma_f32_16x16x32_f16 v[36:39], v[188:191], v[192:195], v[36:39]
	s_waitcnt vmcnt(4)
	v_pk_mov_b32 v[194:195], v[10:11], v[4:5] op_sel:[1,0]
	v_pk_mov_b32 v[192:193], v[8:9], v[10:11] op_sel:[1,0]
	v_mfma_f32_16x16x32_f16 v[32:35], v[188:191], v[196:199], v[32:35]
	v_mfma_f32_16x16x32_f16 v[56:59], v[188:191], v[120:123], v[56:59]
	v_mfma_f32_16x16x32_f16 v[104:107], v[188:191], v[198:201], v[104:107]
	v_perm_b32 v188, v8, v9, s29
	v_perm_b32 v189, v9, v10, s29
	v_perm_b32 v190, v10, v11, s29
	s_waitcnt lgkmcnt(3)
	v_mfma_f32_16x16x32_f16 v[28:31], v[176:179], v[8:11], v[28:31]
	v_perm_b32 v191, v11, v4, s29
	v_perm_b32 v199, v4, v5, s29
	v_mov_b32_e32 v196, v189
	s_waitcnt lgkmcnt(0)
; template <int MODE, int TB>
; DI void toeplitz_task(const Params& P, int layer, int set, int cg, int chunk, char* smem) {
;     ...
;     for (int g = 0; g < ngroups; ++g) {
;       load_group(g + 1 < ngroups ? g + 1 : g, nxt);
;       __builtin_amdgcn_sched_barrier(0);
; #pragma unroll
;       for (int q = 0; q < GS; ++q) {
;         const int s0 = -32 + (g * GS + q) * 32;
;         half8 af[TB];
; #pragma unroll
;         for (int ta = 0; ta < TB; ++ta) { af[ta] = afn[ta]; afn[ta] = *(const half8*)(krw + abase + s0 + 32 - 128 * ta); }
;         unsigned d[8];
;         {
;           const int sw0 = s0 + 8 * kg, sw1 = sw0 + 8;
;           const bool va = (sw0 >= 0) && (sw0 < L), vb = (sw1 >= 0) && (sw1 < L);
; #pragma unroll
;           for (int e = 0; e < 4; ++e) { d[e] = va ? cur[2 * q][e] : 0u; d[4 + e] = vb ? cur[2 * q + 1][e] : 0u; }
;         }
; #pragma unroll
;         for (int r = 0; r < 8; ++r) {
;           u32x4 bw;
; #pragma unroll
;           for (int e = 0; e < 4; ++e)
;             bw[e] = (r & 1) ? __builtin_amdgcn_alignbit(d[(r >> 1) + e + 1 > 7 ? 7 : (r >> 1) + e + 1], d[(r >> 1) + e], 16) : d[(r >> 1) + e];
;           const half8 bfr = __builtin_bit_cast(half8, bw);
; #pragma unroll
;           for (int ta = 0; ta < TB; ++ta) acc[ta][r] = __builtin_amdgcn_mfma_f32_16x16x32_f16(af[ta], bfr, acc[ta][r], 0, 0, 0);
;         }
;       }
; #pragma unroll
;       for (int e = 0; e < 2 * GS; ++e) cur[e] = nxt[e];
;     }
	v_mfma_f32_16x16x32_f16 v[52:55], v[164:167], v[8:11], v[52:55]
	v_mov_b32_e32 v197, v190
	v_mov_b32_e32 v198, v191
	v_mov_b32_e32 v200, v190
	v_mfma_f32_16x16x32_f16 v[80:83], v[180:183], v[8:11], v[80:83]
	v_mov_b32_e32 v201, v191
	v_mov_b32_e32 v202, v199
	v_mfma_f32_16x16x32_f16 v[124:127], v[184:187], v[8:11], v[124:127]
	v_mov_b32_e32 v8, v10
	v_mov_b32_e32 v9, v11
	v_mov_b32_e32 v10, v4
	v_mov_b32_e32 v11, v5
	v_mfma_f32_16x16x32_f16 v[48:51], v[176:179], v[188:191], v[48:51]
	s_nop 0
	v_mfma_f32_16x16x32_f16 v[116:119], v[176:179], v[8:11], v[116:119]
	v_mfma_f32_16x16x32_f16 v[112:115], v[164:167], v[8:11], v[112:115]
	v_mfma_f32_16x16x32_f16 v[108:111], v[180:183], v[8:11], v[108:111]
	v_mfma_f32_16x16x32_f16 v[120:123], v[184:187], v[8:11], v[100:103]
	v_pk_mov_b32 v[10:11], v[4:5], v[6:7] op_sel:[1,0]
	v_mov_b32_e32 v8, v194
	v_mov_b32_e32 v9, v195
	v_perm_b32 v103, v6, v7, s29
	v_mov_b32_e32 v100, v191
	v_mov_b32_e32 v101, v199
	v_mov_b32_e32 v102, v203
	v_mfma_f32_16x16x32_f16 v[44:47], v[164:167], v[188:191], v[44:47]
	v_mfma_f32_16x16x32_f16 v[40:43], v[180:183], v[188:191], v[40:43]
	v_mfma_f32_16x16x32_f16 v[36:39], v[184:187], v[188:191], v[36:39]
	v_mfma_f32_16x16x32_f16 v[96:99], v[176:179], v[192:195], v[96:99]
	v_mfma_f32_16x16x32_f16 v[88:91], v[164:167], v[192:195], v[88:91]
	v_mfma_f32_16x16x32_f16 v[76:79], v[180:183], v[192:195], v[76:79]
	v_mfma_f32_16x16x32_f16 v[32:35], v[184:187], v[192:195], v[32:35]
	v_mfma_f32_16x16x32_f16 v[20:23], v[176:179], v[196:199], v[20:23]
	v_mfma_f32_16x16x32_f16 v[16:19], v[164:167], v[196:199], v[16:19]
	v_mfma_f32_16x16x32_f16 v[12:15], v[180:183], v[196:199], v[12:15]
	v_mfma_f32_16x16x32_f16 v[24:27], v[184:187], v[196:199], v[24:27]
	v_mfma_f32_16x16x32_f16 v[68:71], v[176:179], v[200:203], v[68:71]
	v_mfma_f32_16x16x32_f16 v[64:67], v[164:167], v[200:203], v[64:67]
	v_mfma_f32_16x16x32_f16 v[60:63], v[180:183], v[200:203], v[60:63]
	v_mfma_f32_16x16x32_f16 v[56:59], v[184:187], v[200:203], v[56:59]
	v_mfma_f32_16x16x32_f16 v[92:95], v[176:179], v[8:11], v[92:95]
	v_mfma_f32_16x16x32_f16 v[84:87], v[164:167], v[8:11], v[84:87]
	v_mfma_f32_16x16x32_f16 v[72:75], v[180:183], v[8:11], v[72:75]
	v_mfma_f32_16x16x32_f16 v[104:107], v[184:187], v[8:11], v[104:107]
	v_mfma_f32_16x16x32_f16 v[130:133], v[176:179], v[100:103], v[130:133]
	v_mfma_f32_16x16x32_f16 v[134:137], v[164:167], v[100:103], v[134:137]
	v_mfma_f32_16x16x32_f16 v[138:141], v[180:183], v[100:103], v[138:141]
	v_mfma_f32_16x16x32_f16 v[146:149], v[184:187], v[100:103], v[146:149]
	s_waitcnt vmcnt(0)
	v_mov_b64_e32 v[4:5], v[172:173]
	v_mov_b64_e32 v[6:7], v[174:175]
	v_mov_b64_e32 v[8:9], v[168:169]
	v_mov_b64_e32 v[10:11], v[170:171]
	v_mov_b64_e32 v[100:101], v[142:143]
	v_mov_b64_e32 v[102:103], v[144:145]
	s_cbranch_scc1 .LBB0_423
	v_add_u32_e32 v128, s1, v161
	ds_read_b128 v[4:7], v128 offset:8256
	ds_read_b128 v[8:11], v128 offset:8000
	ds_read_b128 v[100:103], v128 offset:7744
	ds_read_b128 v[162:165], v128 offset:7488
	v_cndmask_b32_e64 v185, v0, 0, vcc
	v_cndmask_b32_e64 v189, v1, 0, vcc
	v_cndmask_b32_e64 v193, v2, 0, vcc
	v_cndmask_b32_e64 v128, v3, 0, vcc
	s_waitcnt lgkmcnt(3)
	v_mfma_f32_16x16x32_f16 v[0:3], v[4:7], v[142:145], v[28:31]
	v_pk_mov_b32 v[182:183], v[142:143], v[144:145] op_sel:[1,0]
	v_mov_b32_e32 v184, v145
	v_mov_b32_e32 v186, v144
	s_waitcnt lgkmcnt(2)
	v_mfma_f32_16x16x32_f16 v[28:31], v[8:11], v[142:145], v[52:55]
	v_mov_b32_e32 v187, v145
	v_mov_b32_e32 v188, v185
	v_mov_b32_e32 v190, v145
	s_waitcnt lgkmcnt(1)
	v_mfma_f32_16x16x32_f16 v[52:55], v[100:103], v[142:145], v[80:83]
	v_mov_b32_e32 v191, v185
	v_mov_b32_e32 v192, v189
	s_mov_b32 s86, s85
	s_waitcnt lgkmcnt(0)
	v_mfma_f32_16x16x32_f16 v[80:83], v[162:165], v[142:145], v[124:127]
	s_mov_b32 s87, s85
	ds_read_b128 v[166:169], v157 offset:8320
	ds_read_b128 v[170:173], v157 offset:8064
	ds_read_b128 v[174:177], v157 offset:7808
	ds_read_b128 v[178:181], v157 offset:7552
	v_perm_b32 v125, v143, v144, s29
	v_perm_b32 v126, v144, v145, s29
	v_alignbit_b32 v127, v185, v145, 16
	v_mfma_f32_16x16x32_f16 v[194:197], v[8:11], v[182:185], v[88:91]
	v_perm_b32 v124, v142, v143, s29
	s_mov_b32 s84, s85
	s_movk_i32 s1, 0x200
	v_alignbit_b32 v91, v189, v185, 16
	v_mov_b32_e32 v88, v125
	v_mov_b32_e32 v89, v126
	v_mov_b32_e32 v90, v127
	v_mfma_f32_16x16x32_f16 v[36:39], v[162:165], v[124:127], v[36:39]
	v_readlane_b32 s2, v253, 35
	s_lshl_b32 s0, s0, 1
	v_readlane_b32 s3, v253, 36
	v_mfma_f32_16x16x32_f16 v[198:201], v[4:7], v[88:91], v[20:23]
	s_nop 2
	v_alignbit_b32 v23, v193, v189, 16
	v_mfma_f32_16x16x32_f16 v[202:205], v[162:165], v[88:91], v[24:27]
	v_mov_b32_e32 v20, v126
	v_mov_b32_e32 v21, v127
	v_mov_b32_e32 v22, v91
	v_alignbit_b32 v27, v128, v193, 16
	v_mov_b32_e32 v24, v127
	v_mov_b32_e32 v25, v91
	v_mov_b32_e32 v26, v23
	v_mfma_f32_16x16x32_f16 v[32:35], v[162:165], v[182:185], v[32:35]
	v_lshl_or_b32 v128, v151, 6, s0
	v_mfma_f32_16x16x32_f16 v[130:133], v[4:7], v[24:27], v[130:133]
	v_mfma_f32_16x16x32_f16 v[228:231], v[162:165], v[186:189], v[120:123]
	v_mfma_f32_16x16x32_f16 v[236:239], v[162:165], v[20:23], v[56:59]
	v_mfma_f32_16x16x32_f16 v[240:243], v[162:165], v[190:193], v[104:107]
	v_mfma_f32_16x16x32_f16 v[146:149], v[162:165], v[24:27], v[146:149]
	v_mov_b64_e32 v[164:165], s[86:87]
	v_mov_b64_e32 v[162:163], s[84:85]
	v_mfma_f32_16x16x32_f16 v[40:43], v[100:103], v[124:127], v[40:43]
	v_mfma_f32_16x16x32_f16 v[96:99], v[4:7], v[182:185], v[96:99]
	v_mfma_f32_16x16x32_f16 v[76:79], v[100:103], v[182:185], v[76:79]
	v_mfma_f32_16x16x32_f16 v[12:15], v[100:103], v[88:91], v[12:15]
	v_mfma_f32_16x16x32_f16 v[210:213], v[4:7], v[186:189], v[116:119]
	v_mfma_f32_16x16x32_f16 v[224:227], v[8:11], v[186:189], v[112:115]
	v_mfma_f32_16x16x32_f16 v[108:111], v[100:103], v[186:189], v[108:111]
	v_mfma_f32_16x16x32_f16 v[68:71], v[4:7], v[20:23], v[68:71]
	v_mfma_f32_16x16x32_f16 v[232:235], v[100:103], v[20:23], v[60:63]
	v_mfma_f32_16x16x32_f16 v[142:145], v[4:7], v[190:193], v[92:95]
	v_mfma_f32_16x16x32_f16 v[186:189], v[100:103], v[190:193], v[72:75]
	v_mfma_f32_16x16x32_f16 v[134:137], v[8:11], v[24:27], v[134:137]
	v_mfma_f32_16x16x32_f16 v[138:141], v[100:103], v[24:27], v[138:141]
	s_waitcnt lgkmcnt(3)
; template <int MODE, int TB>
; DI void toeplitz_task(const Params& P, int layer, int set, int cg, int chunk, char* smem) {
;     ...
;           for (int ta = 0; ta < TB; ++ta) acc[ta][r] = __builtin_amdgcn_mfma_f32_16x16x32_f16(af[ta], bfr, acc[ta][r], 0, 0, 0);
;         }
;       }
; #pragma unroll
;       for (int e = 0; e < 2 * GS; ++e) cur[e] = nxt[e];
;     }
; #pragma unroll
;     for (int hf = 0; hf < TB / 2; ++hf) {
;     const int tbh = tb + 256 * hf;
; #pragma unroll
;     for (int ta = 2 * hf; ta < 2 * hf + 2; ++ta) {
;       const int t0 = tb + 128 * ta + 32 * kg;
; #pragma unroll
;       for (int v = 0; v < 4; ++v) {
;         const int t = t0 + 8 * v;
;         if (MODE == 0) {
;           const half8 x1 = *(const half8*)(hT + (size_t)(bb * 2048 + 512 + c) * L + t);
;           const half8 uu = *(const half8*)(Urow + t);
;           half8 o;
; #pragma unroll
;           for (int r = 0; r < 8; ++r) o[r] = (h16)((float)x1[r] * (acc[ta][r][v] * invs + (float)uu[r] * bias));
;           *(half8*)(z1T + (size_t)(bb * 512 + c) * L + t) = o;
	v_mfma_f32_16x16x32_f16 v[100:103], v[166:169], v[162:165], v[130:133]
	s_nop 2
	v_add3_u32 v130, v156, v160, s1
	v_ashrrev_i32_e32 v131, 31, v130
	v_lshl_add_u32 v132, v153, 9, v156
	v_lshlrev_b64 v[130:131], 12, v[130:131]
	v_ashrrev_i32_e32 v133, 31, v132
	v_lshl_add_u64 v[130:131], s[48:49], 0, v[130:131]
	v_lshlrev_b64 v[132:133], 12, v[132:133]
	s_waitcnt lgkmcnt(1)
	v_mfma_f32_16x16x32_f16 v[60:63], v[174:177], v[162:165], v[40:43]
	v_mfma_f32_16x16x32_f16 v[112:115], v[166:169], v[162:165], v[96:99]
	v_mfma_f32_16x16x32_f16 v[40:43], v[174:177], v[162:165], v[108:111]
	v_mfma_f32_16x16x32_f16 v[108:111], v[166:169], v[162:165], v[68:71]
	v_mfma_f32_16x16x32_f16 v[96:99], v[166:169], v[162:165], v[142:145]
	v_mfma_f32_16x16x32_f16 v[68:71], v[170:173], v[162:165], v[134:137]
	s_nop 1
	v_lshl_add_u64 v[144:145], s[2:3], 0, v[132:133]
	v_lshl_add_u64 v[132:133], v[154:155], 0, v[128:129]
	v_lshl_add_u64 v[134:135], v[130:131], 0, v[128:129]
	s_waitcnt lgkmcnt(0)
	v_mfma_f32_16x16x32_f16 v[24:27], v[178:181], v[162:165], v[36:39]
	v_mfma_f32_16x16x32_f16 v[36:39], v[174:177], v[162:165], v[138:141]
	s_nop 2
	global_load_dwordx4 v[136:139], v[134:135], off
	global_load_dwordx4 v[140:143], v[132:133], off
	v_mfma_f32_16x16x32_f16 v[48:51], v[4:7], v[124:127], v[48:51]
	s_waitcnt vmcnt(1)
	v_cvt_f32_f16_e32 v130, v136
	v_mfma_f32_16x16x32_f16 v[44:47], v[8:11], v[124:127], v[44:47]
	v_cvt_f32_f16_sdwa v131, v136 dst_sel:DWORD dst_unused:UNUSED_PAD src0_sel:WORD_1
	v_mfma_f32_16x16x32_f16 v[120:123], v[166:169], v[162:165], v[0:3]
	v_mfma_f32_16x16x32_f16 v[124:127], v[166:169], v[162:165], v[48:51]
	v_mfma_f32_16x16x32_f16 v[0:3], v[178:181], v[162:165], v[146:149]
	s_waitcnt vmcnt(0)
	s_nop 1
	v_cvt_f32_f16_e32 v148, v140
	v_cvt_f32_f16_sdwa v149, v140 dst_sel:DWORD dst_unused:UNUSED_PAD src0_sel:WORD_1
	s_nop 0
	v_mov_b32_e32 v146, v120
	v_mov_b32_e32 v147, v124
	v_mfma_f32_16x16x32_f16 v[116:119], v[166:169], v[162:165], v[198:201]
	v_mul_f32_e64 v148, v152, v148
	v_mul_f32_e64 v149, v152, v149
	v_pk_fma_f32 v[146:147], v[150:151], v[146:147], v[148:149] op_sel_hi:[0,1,1]
	v_cvt_f32_f16_e32 v140, v141
	v_cvt_f32_f16_sdwa v141, v141 dst_sel:DWORD dst_unused:UNUSED_PAD src0_sel:WORD_1
	v_pk_mul_f32 v[130:131], v[146:147], v[130:131]
	v_mov_b32_e32 v146, v112
	v_cvt_pk_f16_f32 v136, v130, v131
	v_cvt_f32_f16_e32 v130, v137
	v_cvt_f32_f16_sdwa v131, v137 dst_sel:DWORD dst_unused:UNUSED_PAD src0_sel:WORD_1
	v_mov_b32_e32 v147, v116
	v_pk_mul_f32 v[140:141], v[152:153], v[140:141] op_sel_hi:[0,1]
	v_mfma_f32_16x16x32_f16 v[104:107], v[166:169], v[162:165], v[210:213]
	v_fma_f32 v140, v150, v146, v140
	v_fma_f32 v141, v150, v147, v141
	v_cvt_f32_f16_e32 v146, v142
	v_cvt_f32_f16_sdwa v147, v142 dst_sel:DWORD dst_unused:UNUSED_PAD src0_sel:WORD_1
	v_pk_mul_f32 v[130:131], v[140:141], v[130:131]
	v_mov_b32_e32 v141, v108
	v_cvt_pk_f16_f32 v137, v130, v131
	v_cvt_f32_f16_e32 v130, v138
	v_cvt_f32_f16_sdwa v131, v138 dst_sel:DWORD dst_unused:UNUSED_PAD src0_sel:WORD_1
	v_mov_b32_e32 v140, v104
	v_pk_mul_f32 v[146:147], v[152:153], v[146:147] op_sel_hi:[0,1]
	v_pk_fma_f32 v[140:141], v[150:151], v[140:141], v[146:147] op_sel_hi:[0,1,1]
	v_cvt_f32_f16_e32 v142, v143
	v_cvt_f32_f16_sdwa v143, v143 dst_sel:DWORD dst_unused:UNUSED_PAD src0_sel:WORD_1
	v_pk_mul_f32 v[130:131], v[140:141], v[130:131]
	v_mov_b32_e32 v140, v96
	v_cvt_pk_f16_f32 v138, v130, v131
	v_cvt_f32_f16_e32 v130, v139
	v_cvt_f32_f16_sdwa v131, v139 dst_sel:DWORD dst_unused:UNUSED_PAD src0_sel:WORD_1
	v_mov_b32_e32 v141, v100
	v_pk_mul_f32 v[142:143], v[152:153], v[142:143] op_sel_hi:[0,1]
	v_pk_fma_f32 v[140:141], v[150:151], v[140:141], v[142:143] op_sel_hi:[0,1,1]
	v_pk_mul_f32 v[130:131], v[140:141], v[130:131]
	v_mov_b32_e32 v124, v121
	v_cvt_pk_f16_f32 v139, v130, v131
	v_lshl_add_u64 v[130:131], v[144:145], 0, v[128:129]
	global_store_dwordx4 v[130:131], v[136:139], off
	global_load_dwordx4 v[136:139], v[134:135], off offset:16
	s_nop 0
	global_load_dwordx4 v[140:143], v[132:133], off offset:16
	v_mov_b32_e32 v116, v113
	v_mov_b32_e32 v108, v105
	v_mov_b32_e32 v100, v97
	v_mfma_f32_16x16x32_f16 v[16:19], v[8:11], v[88:91], v[16:19]
	s_waitcnt vmcnt(1)
	v_cvt_f32_f16_e32 v144, v136
	s_waitcnt vmcnt(0)
	v_cvt_f32_f16_e32 v120, v140
	v_cvt_f32_f16_sdwa v121, v140 dst_sel:DWORD dst_unused:UNUSED_PAD src0_sel:WORD_1
	v_cvt_f32_f16_sdwa v145, v136 dst_sel:DWORD dst_unused:UNUSED_PAD src0_sel:WORD_1
	v_cvt_f32_f16_e32 v112, v141
	v_cvt_f32_f16_sdwa v113, v141 dst_sel:DWORD dst_unused:UNUSED_PAD src0_sel:WORD_1
	v_pk_mul_f32 v[120:121], v[152:153], v[120:121] op_sel_hi:[0,1]
	v_pk_fma_f32 v[120:121], v[150:151], v[124:125], v[120:121] op_sel_hi:[0,1,1]
	v_pk_mul_f32 v[120:121], v[120:121], v[144:145]
	v_pk_mul_f32 v[112:113], v[152:153], v[112:113] op_sel_hi:[0,1]
	v_cvt_pk_f16_f32 v136, v120, v121
	v_cvt_f32_f16_e32 v120, v137
	v_cvt_f32_f16_sdwa v121, v137 dst_sel:DWORD dst_unused:UNUSED_PAD src0_sel:WORD_1
	v_pk_fma_f32 v[112:113], v[150:151], v[116:117], v[112:113] op_sel_hi:[0,1,1]
	v_cvt_f32_f16_e32 v104, v142
	v_cvt_f32_f16_sdwa v105, v142 dst_sel:DWORD dst_unused:UNUSED_PAD src0_sel:WORD_1
	v_pk_mul_f32 v[112:113], v[112:113], v[120:121]
	v_cvt_f32_f16_e32 v96, v143
	v_cvt_pk_f16_f32 v137, v112, v113
	v_cvt_f32_f16_e32 v112, v138
	v_cvt_f32_f16_sdwa v113, v138 dst_sel:DWORD dst_unused:UNUSED_PAD src0_sel:WORD_1
	v_pk_mul_f32 v[104:105], v[152:153], v[104:105] op_sel_hi:[0,1]
	v_pk_fma_f32 v[104:105], v[150:151], v[108:109], v[104:105] op_sel_hi:[0,1,1]
	v_cvt_f32_f16_sdwa v97, v143 dst_sel:DWORD dst_unused:UNUSED_PAD src0_sel:WORD_1
	v_pk_mul_f32 v[104:105], v[104:105], v[112:113]
	v_mfma_f32_16x16x32_f16 v[88:91], v[170:173], v[162:165], v[28:31]
	v_cvt_pk_f16_f32 v138, v104, v105
	v_cvt_f32_f16_e32 v104, v139
	v_cvt_f32_f16_sdwa v105, v139 dst_sel:DWORD dst_unused:UNUSED_PAD src0_sel:WORD_1
	v_pk_mul_f32 v[96:97], v[152:153], v[96:97] op_sel_hi:[0,1]
	v_pk_fma_f32 v[96:97], v[150:151], v[100:101], v[96:97] op_sel_hi:[0,1,1]
	v_mov_b32_e32 v100, v122
	v_pk_mul_f32 v[96:97], v[96:97], v[104:105]
	v_mov_b32_e32 v101, v126
	v_cvt_pk_f16_f32 v139, v96, v97
	global_store_dwordx4 v[130:131], v[136:139], off offset:16
	global_load_dwordx4 v[136:139], v[134:135], off offset:32
	s_nop 0
	global_load_dwordx4 v[140:143], v[132:133], off offset:32
	v_mov_b32_e32 v126, v123
	v_mfma_f32_16x16x32_f16 v[92:95], v[170:173], v[162:165], v[44:47]
	s_waitcnt vmcnt(1)
; template <int MODE, int TB>
; DI void toeplitz_task(const Params& P, int layer, int set, int cg, int chunk, char* smem) {
;     ...
;       for (int v = 0; v < 4; ++v) {
;         const int t = t0 + 8 * v;
;         if (MODE == 0) {
;           const half8 x1 = *(const half8*)(hT + (size_t)(bb * 2048 + 512 + c) * L + t);
;           const half8 uu = *(const half8*)(Urow + t);
;           half8 o;
; #pragma unroll
;           for (int r = 0; r < 8; ++r) o[r] = (h16)((float)x1[r] * (acc[ta][r][v] * invs + (float)uu[r] * bias));
;           *(half8*)(z1T + (size_t)(bb * 512 + c) * L + t) = o;
	v_cvt_f32_f16_e32 v96, v136
	s_waitcnt vmcnt(0)
	v_cvt_f32_f16_e32 v104, v140
	v_cvt_f32_f16_sdwa v105, v140 dst_sel:DWORD dst_unused:UNUSED_PAD src0_sel:WORD_1
	v_cvt_f32_f16_sdwa v97, v136 dst_sel:DWORD dst_unused:UNUSED_PAD src0_sel:WORD_1
	v_mfma_f32_16x16x32_f16 v[182:185], v[8:11], v[190:193], v[84:87]
	v_mul_f32_e64 v104, v152, v104
	v_mul_f32_e64 v105, v152, v105
	v_pk_fma_f32 v[100:101], v[150:151], v[100:101], v[104:105] op_sel_hi:[0,1,1]
	v_cvt_f32_f16_e32 v104, v141
	v_cvt_f32_f16_sdwa v105, v141 dst_sel:DWORD dst_unused:UNUSED_PAD src0_sel:WORD_1
	v_pk_mul_f32 v[96:97], v[100:101], v[96:97]
	v_mov_b32_e32 v100, v114
	v_cvt_pk_f16_f32 v136, v96, v97
	v_cvt_f32_f16_e32 v96, v137
	v_cvt_f32_f16_sdwa v97, v137 dst_sel:DWORD dst_unused:UNUSED_PAD src0_sel:WORD_1
	v_mov_b32_e32 v101, v118
	v_pk_mul_f32 v[104:105], v[152:153], v[104:105] op_sel_hi:[0,1]
	v_pk_fma_f32 v[100:101], v[150:151], v[100:101], v[104:105] op_sel_hi:[0,1,1]
	v_cvt_f32_f16_e32 v104, v142
	v_cvt_f32_f16_sdwa v105, v142 dst_sel:DWORD dst_unused:UNUSED_PAD src0_sel:WORD_1
	v_pk_mul_f32 v[96:97], v[100:101], v[96:97]
	v_mov_b32_e32 v100, v106
	v_cvt_pk_f16_f32 v137, v96, v97
	v_cvt_f32_f16_e32 v96, v138
	v_cvt_f32_f16_sdwa v97, v138 dst_sel:DWORD dst_unused:UNUSED_PAD src0_sel:WORD_1
	v_mov_b32_e32 v101, v110
	v_pk_mul_f32 v[104:105], v[152:153], v[104:105] op_sel_hi:[0,1]
	v_pk_fma_f32 v[100:101], v[150:151], v[100:101], v[104:105] op_sel_hi:[0,1,1]
	v_cvt_f32_f16_e32 v104, v143
	v_cvt_f32_f16_sdwa v105, v143 dst_sel:DWORD dst_unused:UNUSED_PAD src0_sel:WORD_1
	v_pk_mul_f32 v[96:97], v[100:101], v[96:97]
	v_mov_b32_e32 v100, v98
	v_cvt_pk_f16_f32 v138, v96, v97
	v_cvt_f32_f16_e32 v96, v139
	v_cvt_f32_f16_sdwa v97, v139 dst_sel:DWORD dst_unused:UNUSED_PAD src0_sel:WORD_1
	v_mov_b32_e32 v101, v102
	v_pk_mul_f32 v[104:105], v[152:153], v[104:105] op_sel_hi:[0,1]
	v_pk_fma_f32 v[100:101], v[150:151], v[100:101], v[104:105] op_sel_hi:[0,1,1]
	v_pk_mul_f32 v[96:97], v[100:101], v[96:97]
	v_mov_b32_e32 v118, v115
	v_cvt_pk_f16_f32 v139, v96, v97
	global_store_dwordx4 v[130:131], v[136:139], off offset:32
	global_load_dwordx4 v[136:139], v[134:135], off offset:48
	s_nop 0
	global_load_dwordx4 v[140:143], v[132:133], off offset:48
	v_mov_b32_e32 v110, v107
	v_mov_b32_e32 v102, v99
	v_mov_b32_e32 v106, v88
	v_mov_b32_e32 v107, v92
	v_mfma_f32_16x16x32_f16 v[28:31], v[178:181], v[162:165], v[80:83]
	v_mov_b32_e32 v92, v89
	s_waitcnt vmcnt(1)
	v_cvt_f32_f16_e32 v96, v136
	s_waitcnt vmcnt(0)
	v_cvt_f32_f16_e32 v100, v140
	v_cvt_f32_f16_sdwa v101, v140 dst_sel:DWORD dst_unused:UNUSED_PAD src0_sel:WORD_1
	v_cvt_f32_f16_sdwa v97, v136 dst_sel:DWORD dst_unused:UNUSED_PAD src0_sel:WORD_1
	v_cvt_f32_f16_e32 v104, v141
	v_cvt_f32_f16_sdwa v105, v141 dst_sel:DWORD dst_unused:UNUSED_PAD src0_sel:WORD_1
	v_pk_mul_f32 v[100:101], v[152:153], v[100:101] op_sel_hi:[0,1]
	v_pk_fma_f32 v[100:101], v[150:151], v[126:127], v[100:101] op_sel_hi:[0,1,1]
	v_pk_mul_f32 v[96:97], v[100:101], v[96:97]
	v_cvt_f32_f16_e32 v100, v137
	v_cvt_f32_f16_sdwa v101, v137 dst_sel:DWORD dst_unused:UNUSED_PAD src0_sel:WORD_1
	v_pk_mul_f32 v[104:105], v[152:153], v[104:105] op_sel_hi:[0,1]
	v_pk_fma_f32 v[104:105], v[150:151], v[118:119], v[104:105] op_sel_hi:[0,1,1]
	v_cvt_pk_f16_f32 v96, v96, v97
	v_pk_mul_f32 v[100:101], v[104:105], v[100:101]
	v_cvt_f32_f16_e32 v104, v142
	v_cvt_f32_f16_sdwa v105, v142 dst_sel:DWORD dst_unused:UNUSED_PAD src0_sel:WORD_1
	v_cvt_pk_f16_f32 v97, v100, v101
	v_cvt_f32_f16_e32 v100, v138
	v_cvt_f32_f16_sdwa v101, v138 dst_sel:DWORD dst_unused:UNUSED_PAD src0_sel:WORD_1
	v_pk_mul_f32 v[104:105], v[152:153], v[104:105] op_sel_hi:[0,1]
	v_pk_fma_f32 v[104:105], v[150:151], v[110:111], v[104:105] op_sel_hi:[0,1,1]
	v_mfma_f32_16x16x32_f16 v[80:83], v[170:173], v[162:165], v[194:197]
	v_mul_f32_e64 v100, v104, v100
	v_mul_f32_e64 v101, v105, v101
	v_cvt_f32_f16_e32 v104, v143
	v_cvt_f32_f16_sdwa v105, v143 dst_sel:DWORD dst_unused:UNUSED_PAD src0_sel:WORD_1
	v_cvt_pk_f16_f32 v98, v100, v101
	v_cvt_f32_f16_e32 v100, v139
	v_cvt_f32_f16_sdwa v101, v139 dst_sel:DWORD dst_unused:UNUSED_PAD src0_sel:WORD_1
	v_pk_mul_f32 v[104:105], v[152:153], v[104:105] op_sel_hi:[0,1]
	v_pk_fma_f32 v[102:103], v[150:151], v[102:103], v[104:105] op_sel_hi:[0,1,1]
	v_mfma_f32_16x16x32_f16 v[84:87], v[170:173], v[162:165], v[16:19]
	v_mul_f32_e64 v100, v102, v100
	v_mul_f32_e64 v101, v103, v101
	v_cvt_pk_f16_f32 v99, v100, v101
	global_store_dwordx4 v[130:131], v[96:99], off offset:48
	global_load_dwordx4 v[96:99], v[134:135], off offset:256
	s_nop 0
	global_load_dwordx4 v[100:103], v[132:133], off offset:256
	v_mfma_f32_16x16x32_f16 v[64:67], v[8:11], v[20:23], v[64:67]
	s_waitcnt vmcnt(1)
	v_cvt_f32_f16_e32 v104, v96
	s_waitcnt vmcnt(0)
; template <int MODE, int TB>
; DI void toeplitz_task(const Params& P, int layer, int set, int cg, int chunk, char* smem) {
;     ...
;       for (int v = 0; v < 4; ++v) {
;         const int t = t0 + 8 * v;
;         if (MODE == 0) {
;           const half8 x1 = *(const half8*)(hT + (size_t)(bb * 2048 + 512 + c) * L + t);
;           const half8 uu = *(const half8*)(Urow + t);
;           half8 o;
; #pragma unroll
;           for (int r = 0; r < 8; ++r) o[r] = (h16)((float)x1[r] * (acc[ta][r][v] * invs + (float)uu[r] * bias));
;           *(half8*)(z1T + (size_t)(bb * 512 + c) * L + t) = o;
	v_cvt_f32_f16_e32 v108, v100
	v_cvt_f32_f16_sdwa v109, v100 dst_sel:DWORD dst_unused:UNUSED_PAD src0_sel:WORD_1
	v_cvt_f32_f16_sdwa v105, v96 dst_sel:DWORD dst_unused:UNUSED_PAD src0_sel:WORD_1
	v_cvt_f32_f16_e32 v100, v101
	v_cvt_f32_f16_sdwa v101, v101 dst_sel:DWORD dst_unused:UNUSED_PAD src0_sel:WORD_1
	v_pk_mul_f32 v[108:109], v[152:153], v[108:109] op_sel_hi:[0,1]
	v_pk_fma_f32 v[106:107], v[150:151], v[106:107], v[108:109] op_sel_hi:[0,1,1]
	v_pk_mul_f32 v[104:105], v[106:107], v[104:105]
	v_mov_b32_e32 v106, v80
	v_cvt_pk_f16_f32 v96, v104, v105
	v_cvt_f32_f16_e32 v104, v97
	v_cvt_f32_f16_sdwa v105, v97 dst_sel:DWORD dst_unused:UNUSED_PAD src0_sel:WORD_1
	v_mov_b32_e32 v107, v84
	v_pk_mul_f32 v[100:101], v[152:153], v[100:101] op_sel_hi:[0,1]
	v_mfma_f32_16x16x32_f16 v[48:51], v[174:177], v[162:165], v[76:79]
	v_fma_f32 v100, v150, v106, v100
	v_fma_f32 v101, v150, v107, v101
	v_cvt_f32_f16_e32 v106, v102
	v_cvt_f32_f16_sdwa v107, v102 dst_sel:DWORD dst_unused:UNUSED_PAD src0_sel:WORD_1
	v_mfma_f32_16x16x32_f16 v[72:75], v[170:173], v[162:165], v[224:227]
	v_mul_f32_e64 v100, v100, v104
	v_mul_f32_e64 v101, v101, v105
	v_cvt_f32_f16_e32 v102, v103
	v_cvt_pk_f16_f32 v97, v100, v101
	v_mfma_f32_16x16x32_f16 v[76:79], v[170:173], v[162:165], v[64:67]
	v_cvt_f32_f16_e32 v100, v98
	v_cvt_f32_f16_sdwa v101, v98 dst_sel:DWORD dst_unused:UNUSED_PAD src0_sel:WORD_1
	s_nop 0
	v_mov_b32_e32 v104, v72
	v_pk_mul_f32 v[106:107], v[152:153], v[106:107] op_sel_hi:[0,1]
	v_mfma_f32_16x16x32_f16 v[64:67], v[170:173], v[162:165], v[182:185]
	s_nop 1
	v_mov_b32_e32 v105, v76
	v_pk_fma_f32 v[104:105], v[150:151], v[104:105], v[106:107] op_sel_hi:[0,1,1]
	v_cvt_f32_f16_sdwa v103, v103 dst_sel:DWORD dst_unused:UNUSED_PAD src0_sel:WORD_1
	v_pk_mul_f32 v[100:101], v[104:105], v[100:101]
	v_mov_b32_e32 v105, v68
	v_cvt_pk_f16_f32 v98, v100, v101
	v_cvt_f32_f16_e32 v100, v99
	v_cvt_f32_f16_sdwa v101, v99 dst_sel:DWORD dst_unused:UNUSED_PAD src0_sel:WORD_1
	v_mov_b32_e32 v104, v64
	v_pk_mul_f32 v[102:103], v[152:153], v[102:103] op_sel_hi:[0,1]
	v_pk_fma_f32 v[102:103], v[150:151], v[104:105], v[102:103] op_sel_hi:[0,1,1]
	v_pk_mul_f32 v[100:101], v[102:103], v[100:101]
	v_mov_b32_e32 v84, v81
	v_cvt_pk_f16_f32 v99, v100, v101
	global_store_dwordx4 v[130:131], v[96:99], off offset:256
	global_load_dwordx4 v[96:99], v[134:135], off offset:272
	s_nop 0
	global_load_dwordx4 v[100:103], v[132:133], off offset:272
	v_mov_b32_e32 v76, v73
	v_mov_b32_e32 v68, v65
	v_mfma_f32_16x16x32_f16 v[56:59], v[174:177], v[162:165], v[52:55]
	s_waitcnt vmcnt(1)
	v_cvt_f32_f16_e32 v104, v96
	s_waitcnt vmcnt(0)
	v_cvt_f32_f16_e32 v88, v100
	v_cvt_f32_f16_sdwa v89, v100 dst_sel:DWORD dst_unused:UNUSED_PAD src0_sel:WORD_1
	v_cvt_f32_f16_sdwa v105, v96 dst_sel:DWORD dst_unused:UNUSED_PAD src0_sel:WORD_1
	v_cvt_f32_f16_e32 v80, v101
	v_cvt_f32_f16_sdwa v81, v101 dst_sel:DWORD dst_unused:UNUSED_PAD src0_sel:WORD_1
	v_pk_mul_f32 v[88:89], v[152:153], v[88:89] op_sel_hi:[0,1]
	v_pk_fma_f32 v[88:89], v[150:151], v[92:93], v[88:89] op_sel_hi:[0,1,1]
	v_pk_mul_f32 v[88:89], v[88:89], v[104:105]
	v_pk_mul_f32 v[80:81], v[152:153], v[80:81] op_sel_hi:[0,1]
	v_cvt_pk_f16_f32 v96, v88, v89
	v_cvt_f32_f16_e32 v88, v97
	v_cvt_f32_f16_sdwa v89, v97 dst_sel:DWORD dst_unused:UNUSED_PAD src0_sel:WORD_1
	v_pk_fma_f32 v[80:81], v[150:151], v[84:85], v[80:81] op_sel_hi:[0,1,1]
	v_cvt_f32_f16_e32 v72, v102
	v_cvt_f32_f16_sdwa v73, v102 dst_sel:DWORD dst_unused:UNUSED_PAD src0_sel:WORD_1
	v_pk_mul_f32 v[80:81], v[80:81], v[88:89]
	v_cvt_f32_f16_e32 v64, v103
	v_cvt_pk_f16_f32 v97, v80, v81
	v_cvt_f32_f16_e32 v80, v98
	v_cvt_f32_f16_sdwa v81, v98 dst_sel:DWORD dst_unused:UNUSED_PAD src0_sel:WORD_1
	v_pk_mul_f32 v[72:73], v[152:153], v[72:73] op_sel_hi:[0,1]
	v_pk_fma_f32 v[72:73], v[150:151], v[76:77], v[72:73] op_sel_hi:[0,1,1]
	v_cvt_f32_f16_sdwa v65, v103 dst_sel:DWORD dst_unused:UNUSED_PAD src0_sel:WORD_1
	v_pk_mul_f32 v[72:73], v[72:73], v[80:81]
	v_mfma_f32_16x16x32_f16 v[52:55], v[174:177], v[162:165], v[12:15]
	v_cvt_pk_f16_f32 v98, v72, v73
	v_cvt_f32_f16_e32 v72, v99
	v_cvt_f32_f16_sdwa v73, v99 dst_sel:DWORD dst_unused:UNUSED_PAD src0_sel:WORD_1
	v_pk_mul_f32 v[64:65], v[152:153], v[64:65] op_sel_hi:[0,1]
	v_pk_fma_f32 v[64:65], v[150:151], v[68:69], v[64:65] op_sel_hi:[0,1,1]
	v_mov_b32_e32 v68, v90
	v_pk_mul_f32 v[64:65], v[64:65], v[72:73]
	v_mov_b32_e32 v69, v94
	v_cvt_pk_f16_f32 v99, v64, v65
	global_store_dwordx4 v[130:131], v[96:99], off offset:272
	global_load_dwordx4 v[96:99], v[134:135], off offset:288
	s_nop 0
	global_load_dwordx4 v[100:103], v[132:133], off offset:288
	v_mov_b32_e32 v94, v91
	v_mfma_f32_16x16x32_f16 v[44:47], v[174:177], v[162:165], v[232:235]
	s_waitcnt vmcnt(1)
	v_cvt_f32_f16_e32 v64, v96
	s_waitcnt vmcnt(0)
; template <int MODE, int TB>
; DI void toeplitz_task(const Params& P, int layer, int set, int cg, int chunk, char* smem) {
;     ...
;       for (int v = 0; v < 4; ++v) {
;         const int t = t0 + 8 * v;
;         if (MODE == 0) {
;           const half8 x1 = *(const half8*)(hT + (size_t)(bb * 2048 + 512 + c) * L + t);
;           const half8 uu = *(const half8*)(Urow + t);
;           half8 o;
; #pragma unroll
;           for (int r = 0; r < 8; ++r) o[r] = (h16)((float)x1[r] * (acc[ta][r][v] * invs + (float)uu[r] * bias));
;           *(half8*)(z1T + (size_t)(bb * 512 + c) * L + t) = o;
	v_cvt_f32_f16_e32 v72, v100
	v_cvt_f32_f16_sdwa v73, v100 dst_sel:DWORD dst_unused:UNUSED_PAD src0_sel:WORD_1
	v_cvt_f32_f16_sdwa v65, v96 dst_sel:DWORD dst_unused:UNUSED_PAD src0_sel:WORD_1
	v_mfma_f32_16x16x32_f16 v[20:23], v[178:181], v[162:165], v[32:35]
	v_mul_f32_e64 v72, v152, v72
	v_mul_f32_e64 v73, v152, v73
	v_pk_fma_f32 v[68:69], v[150:151], v[68:69], v[72:73] op_sel_hi:[0,1,1]
	v_cvt_f32_f16_e32 v72, v101
	v_cvt_f32_f16_sdwa v73, v101 dst_sel:DWORD dst_unused:UNUSED_PAD src0_sel:WORD_1
	v_pk_mul_f32 v[64:65], v[68:69], v[64:65]
	v_mov_b32_e32 v68, v82
	v_cvt_pk_f16_f32 v96, v64, v65
	v_cvt_f32_f16_e32 v64, v97
	v_cvt_f32_f16_sdwa v65, v97 dst_sel:DWORD dst_unused:UNUSED_PAD src0_sel:WORD_1
	v_mov_b32_e32 v69, v86
	v_pk_mul_f32 v[72:73], v[152:153], v[72:73] op_sel_hi:[0,1]
	v_pk_fma_f32 v[68:69], v[150:151], v[68:69], v[72:73] op_sel_hi:[0,1,1]
	v_cvt_f32_f16_e32 v72, v102
	v_cvt_f32_f16_sdwa v73, v102 dst_sel:DWORD dst_unused:UNUSED_PAD src0_sel:WORD_1
	v_pk_mul_f32 v[64:65], v[68:69], v[64:65]
	v_mov_b32_e32 v68, v74
	v_cvt_pk_f16_f32 v97, v64, v65
	v_cvt_f32_f16_e32 v64, v98
	v_cvt_f32_f16_sdwa v65, v98 dst_sel:DWORD dst_unused:UNUSED_PAD src0_sel:WORD_1
	v_mov_b32_e32 v69, v78
	v_pk_mul_f32 v[72:73], v[152:153], v[72:73] op_sel_hi:[0,1]
	v_pk_fma_f32 v[68:69], v[150:151], v[68:69], v[72:73] op_sel_hi:[0,1,1]
	v_cvt_f32_f16_e32 v72, v103
	v_cvt_f32_f16_sdwa v73, v103 dst_sel:DWORD dst_unused:UNUSED_PAD src0_sel:WORD_1
	v_pk_mul_f32 v[64:65], v[68:69], v[64:65]
	v_mov_b32_e32 v68, v66
	v_cvt_pk_f16_f32 v98, v64, v65
	v_cvt_f32_f16_e32 v64, v99
	v_cvt_f32_f16_sdwa v65, v99 dst_sel:DWORD dst_unused:UNUSED_PAD src0_sel:WORD_1
	v_mov_b32_e32 v69, v70
	v_pk_mul_f32 v[72:73], v[152:153], v[72:73] op_sel_hi:[0,1]
	v_pk_fma_f32 v[68:69], v[150:151], v[68:69], v[72:73] op_sel_hi:[0,1,1]
	v_pk_mul_f32 v[64:65], v[68:69], v[64:65]
	v_mov_b32_e32 v86, v83
	v_cvt_pk_f16_f32 v99, v64, v65
	global_store_dwordx4 v[130:131], v[96:99], off offset:288
	global_load_dwordx4 v[96:99], v[134:135], off offset:304
	s_nop 0
	global_load_dwordx4 v[100:103], v[132:133], off offset:304
	v_mov_b32_e32 v78, v75
	v_mov_b32_e32 v70, v67
	v_mov_b32_e32 v74, v56
	v_mov_b32_e32 v75, v60
	v_mfma_f32_16x16x32_f16 v[32:35], v[174:177], v[162:165], v[186:189]
	v_mov_b32_e32 v60, v57
	s_waitcnt vmcnt(1)
	v_cvt_f32_f16_e32 v64, v96
	s_waitcnt vmcnt(0)
	v_cvt_f32_f16_e32 v68, v100
	v_cvt_f32_f16_sdwa v69, v100 dst_sel:DWORD dst_unused:UNUSED_PAD src0_sel:WORD_1
	v_cvt_f32_f16_sdwa v65, v96 dst_sel:DWORD dst_unused:UNUSED_PAD src0_sel:WORD_1
	v_cvt_f32_f16_e32 v72, v101
	v_cvt_f32_f16_sdwa v73, v101 dst_sel:DWORD dst_unused:UNUSED_PAD src0_sel:WORD_1
	v_pk_mul_f32 v[68:69], v[152:153], v[68:69] op_sel_hi:[0,1]
	v_pk_fma_f32 v[68:69], v[150:151], v[94:95], v[68:69] op_sel_hi:[0,1,1]
	v_pk_mul_f32 v[64:65], v[68:69], v[64:65]
	v_cvt_f32_f16_e32 v68, v97
	v_cvt_f32_f16_sdwa v69, v97 dst_sel:DWORD dst_unused:UNUSED_PAD src0_sel:WORD_1
	v_pk_mul_f32 v[72:73], v[152:153], v[72:73] op_sel_hi:[0,1]
	v_pk_fma_f32 v[72:73], v[150:151], v[86:87], v[72:73] op_sel_hi:[0,1,1]
	v_cvt_pk_f16_f32 v64, v64, v65
	v_pk_mul_f32 v[68:69], v[72:73], v[68:69]
	v_cvt_f32_f16_e32 v72, v102
	v_cvt_f32_f16_sdwa v73, v102 dst_sel:DWORD dst_unused:UNUSED_PAD src0_sel:WORD_1
	v_cvt_pk_f16_f32 v65, v68, v69
	v_cvt_f32_f16_e32 v68, v98
	v_cvt_f32_f16_sdwa v69, v98 dst_sel:DWORD dst_unused:UNUSED_PAD src0_sel:WORD_1
	v_pk_mul_f32 v[72:73], v[152:153], v[72:73] op_sel_hi:[0,1]
	v_pk_fma_f32 v[72:73], v[150:151], v[78:79], v[72:73] op_sel_hi:[0,1,1]
	v_mfma_f32_16x16x32_f16 v[16:19], v[178:181], v[162:165], v[202:205]
	v_mul_f32_e64 v68, v72, v68
	v_mul_f32_e64 v69, v73, v69
	v_cvt_f32_f16_e32 v72, v103
	v_cvt_f32_f16_sdwa v73, v103 dst_sel:DWORD dst_unused:UNUSED_PAD src0_sel:WORD_1
	v_cvt_pk_f16_f32 v66, v68, v69
	v_cvt_f32_f16_e32 v68, v99
	v_cvt_f32_f16_sdwa v69, v99 dst_sel:DWORD dst_unused:UNUSED_PAD src0_sel:WORD_1
	v_pk_mul_f32 v[72:73], v[152:153], v[72:73] op_sel_hi:[0,1]
	v_pk_fma_f32 v[70:71], v[150:151], v[70:71], v[72:73] op_sel_hi:[0,1,1]
	v_mfma_f32_16x16x32_f16 v[12:15], v[178:181], v[162:165], v[228:231]
	v_mul_f32_e64 v68, v70, v68
	v_mul_f32_e64 v69, v71, v69
	v_cvt_pk_f16_f32 v67, v68, v69
	global_store_dwordx4 v[130:131], v[64:67], off offset:304
	global_load_dwordx4 v[64:67], v[134:135], off offset:512
	s_nop 0
	global_load_dwordx4 v[68:71], v[132:133], off offset:512
	v_mfma_f32_16x16x32_f16 v[8:11], v[178:181], v[162:165], v[236:239]
	s_waitcnt vmcnt(1)
	v_cvt_f32_f16_e32 v72, v64
	s_waitcnt vmcnt(0)
	v_cvt_f32_f16_e32 v76, v68
	v_cvt_f32_f16_sdwa v77, v68 dst_sel:DWORD dst_unused:UNUSED_PAD src0_sel:WORD_1
	v_cvt_f32_f16_sdwa v73, v64 dst_sel:DWORD dst_unused:UNUSED_PAD src0_sel:WORD_1
	v_cvt_f32_f16_e32 v68, v69
	v_cvt_f32_f16_sdwa v69, v69 dst_sel:DWORD dst_unused:UNUSED_PAD src0_sel:WORD_1
	v_pk_mul_f32 v[76:77], v[152:153], v[76:77] op_sel_hi:[0,1]
	v_pk_fma_f32 v[74:75], v[150:151], v[74:75], v[76:77] op_sel_hi:[0,1,1]
	v_pk_mul_f32 v[72:73], v[74:75], v[72:73]
	v_mov_b32_e32 v74, v48
	v_cvt_pk_f16_f32 v64, v72, v73
	v_cvt_f32_f16_e32 v72, v65
	v_cvt_f32_f16_sdwa v73, v65 dst_sel:DWORD dst_unused:UNUSED_PAD src0_sel:WORD_1
	v_mov_b32_e32 v75, v52
	v_pk_mul_f32 v[68:69], v[152:153], v[68:69] op_sel_hi:[0,1]
	v_pk_fma_f32 v[68:69], v[150:151], v[74:75], v[68:69] op_sel_hi:[0,1,1]
	v_cvt_f32_f16_e32 v74, v70
	v_cvt_f32_f16_sdwa v75, v70 dst_sel:DWORD dst_unused:UNUSED_PAD src0_sel:WORD_1
	v_pk_mul_f32 v[68:69], v[68:69], v[72:73]
	v_mov_b32_e32 v72, v40
	v_cvt_pk_f16_f32 v65, v68, v69
	v_cvt_f32_f16_e32 v68, v66
	v_cvt_f32_f16_sdwa v69, v66 dst_sel:DWORD dst_unused:UNUSED_PAD src0_sel:WORD_1
	v_mov_b32_e32 v73, v44
	v_pk_mul_f32 v[74:75], v[152:153], v[74:75] op_sel_hi:[0,1]
	v_pk_fma_f32 v[72:73], v[150:151], v[72:73], v[74:75] op_sel_hi:[0,1,1]
	v_cvt_f32_f16_e32 v70, v71
	v_cvt_f32_f16_sdwa v71, v71 dst_sel:DWORD dst_unused:UNUSED_PAD src0_sel:WORD_1
	v_pk_mul_f32 v[68:69], v[72:73], v[68:69]
	v_mov_b32_e32 v72, v32
	v_cvt_pk_f16_f32 v66, v68, v69
	v_cvt_f32_f16_e32 v68, v67
	v_cvt_f32_f16_sdwa v69, v67 dst_sel:DWORD dst_unused:UNUSED_PAD src0_sel:WORD_1
	v_mov_b32_e32 v73, v36
	v_pk_mul_f32 v[70:71], v[152:153], v[70:71] op_sel_hi:[0,1]
	v_pk_fma_f32 v[70:71], v[150:151], v[72:73], v[70:71] op_sel_hi:[0,1,1]
	v_pk_mul_f32 v[68:69], v[70:71], v[68:69]
	v_mov_b32_e32 v52, v49
	v_cvt_pk_f16_f32 v67, v68, v69
	global_store_dwordx4 v[130:131], v[64:67], off offset:512
	global_load_dwordx4 v[64:67], v[134:135], off offset:528
	s_nop 0
	global_load_dwordx4 v[68:71], v[132:133], off offset:528
	v_mov_b32_e32 v44, v41
	v_mov_b32_e32 v36, v33
	v_mfma_f32_16x16x32_f16 v[4:7], v[178:181], v[162:165], v[240:243]
	s_waitcnt vmcnt(1)
; template <int MODE, int TB>
; DI void toeplitz_task(const Params& P, int layer, int set, int cg, int chunk, char* smem) {
;     ...
;       for (int v = 0; v < 4; ++v) {
;         const int t = t0 + 8 * v;
;         if (MODE == 0) {
;           const half8 x1 = *(const half8*)(hT + (size_t)(bb * 2048 + 512 + c) * L + t);
;           const half8 uu = *(const half8*)(Urow + t);
;           half8 o;
; #pragma unroll
;           for (int r = 0; r < 8; ++r) o[r] = (h16)((float)x1[r] * (acc[ta][r][v] * invs + (float)uu[r] * bias));
;           *(half8*)(z1T + (size_t)(bb * 512 + c) * L + t) = o;
	v_cvt_f32_f16_e32 v72, v64
	s_waitcnt vmcnt(0)
	v_cvt_f32_f16_e32 v56, v68
	v_cvt_f32_f16_sdwa v57, v68 dst_sel:DWORD dst_unused:UNUSED_PAD src0_sel:WORD_1
	v_cvt_f32_f16_sdwa v73, v64 dst_sel:DWORD dst_unused:UNUSED_PAD src0_sel:WORD_1
	v_cvt_f32_f16_e32 v48, v69
	v_cvt_f32_f16_sdwa v49, v69 dst_sel:DWORD dst_unused:UNUSED_PAD src0_sel:WORD_1
	v_pk_mul_f32 v[56:57], v[152:153], v[56:57] op_sel_hi:[0,1]
	v_pk_fma_f32 v[56:57], v[150:151], v[60:61], v[56:57] op_sel_hi:[0,1,1]
	v_pk_mul_f32 v[56:57], v[56:57], v[72:73]
	v_pk_mul_f32 v[48:49], v[152:153], v[48:49] op_sel_hi:[0,1]
	v_cvt_pk_f16_f32 v64, v56, v57
	v_cvt_f32_f16_e32 v56, v65
	v_cvt_f32_f16_sdwa v57, v65 dst_sel:DWORD dst_unused:UNUSED_PAD src0_sel:WORD_1
	v_pk_fma_f32 v[48:49], v[150:151], v[52:53], v[48:49] op_sel_hi:[0,1,1]
	v_cvt_f32_f16_e32 v40, v70
	v_cvt_f32_f16_sdwa v41, v70 dst_sel:DWORD dst_unused:UNUSED_PAD src0_sel:WORD_1
	v_pk_mul_f32 v[48:49], v[48:49], v[56:57]
	v_cvt_f32_f16_e32 v32, v71
	v_cvt_pk_f16_f32 v65, v48, v49
	v_cvt_f32_f16_e32 v48, v66
	v_cvt_f32_f16_sdwa v49, v66 dst_sel:DWORD dst_unused:UNUSED_PAD src0_sel:WORD_1
	v_pk_mul_f32 v[40:41], v[152:153], v[40:41] op_sel_hi:[0,1]
	v_pk_fma_f32 v[40:41], v[150:151], v[44:45], v[40:41] op_sel_hi:[0,1,1]
	v_cvt_f32_f16_sdwa v33, v71 dst_sel:DWORD dst_unused:UNUSED_PAD src0_sel:WORD_1
	v_pk_mul_f32 v[40:41], v[40:41], v[48:49]
	v_pk_mul_f32 v[32:33], v[152:153], v[32:33] op_sel_hi:[0,1]
	v_cvt_pk_f16_f32 v66, v40, v41
	v_cvt_f32_f16_e32 v40, v67
	v_cvt_f32_f16_sdwa v41, v67 dst_sel:DWORD dst_unused:UNUSED_PAD src0_sel:WORD_1
	v_pk_fma_f32 v[32:33], v[150:151], v[36:37], v[32:33] op_sel_hi:[0,1,1]
	v_mov_b32_e32 v36, v58
	v_mov_b32_e32 v37, v62
	v_pk_mul_f32 v[32:33], v[32:33], v[40:41]
	v_mov_b32_e32 v62, v59
	v_cvt_pk_f16_f32 v67, v32, v33
	global_store_dwordx4 v[130:131], v[64:67], off offset:528
	global_load_dwordx4 v[64:67], v[134:135], off offset:544
	s_nop 0
	global_load_dwordx4 v[68:71], v[132:133], off offset:544
	s_waitcnt vmcnt(1)
	v_cvt_f32_f16_e32 v32, v64
	s_waitcnt vmcnt(0)
	v_cvt_f32_f16_e32 v40, v68
	v_cvt_f32_f16_sdwa v41, v68 dst_sel:DWORD dst_unused:UNUSED_PAD src0_sel:WORD_1
	v_cvt_f32_f16_sdwa v33, v64 dst_sel:DWORD dst_unused:UNUSED_PAD src0_sel:WORD_1
	v_pk_mul_f32 v[40:41], v[152:153], v[40:41] op_sel_hi:[0,1]
	v_pk_fma_f32 v[36:37], v[150:151], v[36:37], v[40:41] op_sel_hi:[0,1,1]
	v_cvt_f32_f16_e32 v40, v69
	v_cvt_f32_f16_sdwa v41, v69 dst_sel:DWORD dst_unused:UNUSED_PAD src0_sel:WORD_1
	v_pk_mul_f32 v[32:33], v[36:37], v[32:33]
	v_mov_b32_e32 v36, v50
	v_cvt_pk_f16_f32 v64, v32, v33
	v_cvt_f32_f16_e32 v32, v65
	v_cvt_f32_f16_sdwa v33, v65 dst_sel:DWORD dst_unused:UNUSED_PAD src0_sel:WORD_1
	v_mov_b32_e32 v37, v54
	v_pk_mul_f32 v[40:41], v[152:153], v[40:41] op_sel_hi:[0,1]
	v_pk_fma_f32 v[36:37], v[150:151], v[36:37], v[40:41] op_sel_hi:[0,1,1]
	v_cvt_f32_f16_e32 v40, v70
	v_cvt_f32_f16_sdwa v41, v70 dst_sel:DWORD dst_unused:UNUSED_PAD src0_sel:WORD_1
	v_pk_mul_f32 v[32:33], v[36:37], v[32:33]
	v_mov_b32_e32 v36, v42
	v_cvt_pk_f16_f32 v65, v32, v33
	v_cvt_f32_f16_e32 v32, v66
	v_cvt_f32_f16_sdwa v33, v66 dst_sel:DWORD dst_unused:UNUSED_PAD src0_sel:WORD_1
	v_mov_b32_e32 v37, v46
	v_pk_mul_f32 v[40:41], v[152:153], v[40:41] op_sel_hi:[0,1]
	v_pk_fma_f32 v[36:37], v[150:151], v[36:37], v[40:41] op_sel_hi:[0,1,1]
	v_cvt_f32_f16_e32 v40, v71
	v_cvt_f32_f16_sdwa v41, v71 dst_sel:DWORD dst_unused:UNUSED_PAD src0_sel:WORD_1
	v_pk_mul_f32 v[32:33], v[36:37], v[32:33]
	v_mov_b32_e32 v36, v34
	v_cvt_pk_f16_f32 v66, v32, v33
	v_cvt_f32_f16_e32 v32, v67
	v_cvt_f32_f16_sdwa v33, v67 dst_sel:DWORD dst_unused:UNUSED_PAD src0_sel:WORD_1
	v_mov_b32_e32 v37, v38
	v_pk_mul_f32 v[40:41], v[152:153], v[40:41] op_sel_hi:[0,1]
	v_pk_fma_f32 v[36:37], v[150:151], v[36:37], v[40:41] op_sel_hi:[0,1,1]
	v_pk_mul_f32 v[32:33], v[36:37], v[32:33]
	v_mov_b32_e32 v54, v51
	v_cvt_pk_f16_f32 v67, v32, v33
	global_store_dwordx4 v[130:131], v[64:67], off offset:544
	global_load_dwordx4 v[64:67], v[134:135], off offset:560
	s_nop 0
	global_load_dwordx4 v[68:71], v[132:133], off offset:560
	v_mov_b32_e32 v46, v43
	v_mov_b32_e32 v38, v35
	v_mov_b32_e32 v42, v28
	v_mov_b32_e32 v43, v24
	v_mov_b32_e32 v24, v29
	s_waitcnt vmcnt(1)
	v_cvt_f32_f16_e32 v32, v64
	s_waitcnt vmcnt(0)
	v_cvt_f32_f16_e32 v36, v68
	v_cvt_f32_f16_sdwa v37, v68 dst_sel:DWORD dst_unused:UNUSED_PAD src0_sel:WORD_1
	v_cvt_f32_f16_sdwa v33, v64 dst_sel:DWORD dst_unused:UNUSED_PAD src0_sel:WORD_1
	v_cvt_f32_f16_e32 v40, v69
	v_cvt_f32_f16_sdwa v41, v69 dst_sel:DWORD dst_unused:UNUSED_PAD src0_sel:WORD_1
	v_pk_mul_f32 v[36:37], v[152:153], v[36:37] op_sel_hi:[0,1]
	v_pk_fma_f32 v[36:37], v[150:151], v[62:63], v[36:37] op_sel_hi:[0,1,1]
	v_pk_mul_f32 v[32:33], v[36:37], v[32:33]
	v_cvt_f32_f16_e32 v36, v65
	v_cvt_f32_f16_sdwa v37, v65 dst_sel:DWORD dst_unused:UNUSED_PAD src0_sel:WORD_1
	v_pk_mul_f32 v[40:41], v[152:153], v[40:41] op_sel_hi:[0,1]
	v_pk_fma_f32 v[40:41], v[150:151], v[54:55], v[40:41] op_sel_hi:[0,1,1]
	v_cvt_pk_f16_f32 v32, v32, v33
	v_pk_mul_f32 v[36:37], v[40:41], v[36:37]
	v_cvt_f32_f16_e32 v40, v70
	v_cvt_f32_f16_sdwa v41, v70 dst_sel:DWORD dst_unused:UNUSED_PAD src0_sel:WORD_1
	v_cvt_pk_f16_f32 v33, v36, v37
	v_cvt_f32_f16_e32 v36, v66
	v_cvt_f32_f16_sdwa v37, v66 dst_sel:DWORD dst_unused:UNUSED_PAD src0_sel:WORD_1
	v_pk_mul_f32 v[40:41], v[152:153], v[40:41] op_sel_hi:[0,1]
	v_pk_fma_f32 v[40:41], v[150:151], v[46:47], v[40:41] op_sel_hi:[0,1,1]
	v_pk_mul_f32 v[36:37], v[40:41], v[36:37]
	v_cvt_f32_f16_e32 v40, v71
	v_cvt_f32_f16_sdwa v41, v71 dst_sel:DWORD dst_unused:UNUSED_PAD src0_sel:WORD_1
	v_cvt_pk_f16_f32 v34, v36, v37
	v_cvt_f32_f16_e32 v36, v67
	v_cvt_f32_f16_sdwa v37, v67 dst_sel:DWORD dst_unused:UNUSED_PAD src0_sel:WORD_1
	v_pk_mul_f32 v[40:41], v[152:153], v[40:41] op_sel_hi:[0,1]
	v_pk_fma_f32 v[38:39], v[150:151], v[38:39], v[40:41] op_sel_hi:[0,1,1]
	v_pk_mul_f32 v[36:37], v[38:39], v[36:37]
	s_nop 0
	v_cvt_pk_f16_f32 v35, v36, v37
	global_store_dwordx4 v[130:131], v[32:35], off offset:560
	global_load_dwordx4 v[32:35], v[134:135], off offset:768
	s_nop 0
	global_load_dwordx4 v[36:39], v[132:133], off offset:768
	s_waitcnt vmcnt(1)
; template <int MODE, int TB>
; DI void toeplitz_task(const Params& P, int layer, int set, int cg, int chunk, char* smem) {
;     ...
;       for (int v = 0; v < 4; ++v) {
;         const int t = t0 + 8 * v;
;         if (MODE == 0) {
;           const half8 x1 = *(const half8*)(hT + (size_t)(bb * 2048 + 512 + c) * L + t);
;           const half8 uu = *(const half8*)(Urow + t);
;           half8 o;
; #pragma unroll
;           for (int r = 0; r < 8; ++r) o[r] = (h16)((float)x1[r] * (acc[ta][r][v] * invs + (float)uu[r] * bias));
;           *(half8*)(z1T + (size_t)(bb * 512 + c) * L + t) = o;
	v_cvt_f32_f16_e32 v40, v32
	s_waitcnt vmcnt(0)
	v_cvt_f32_f16_e32 v44, v36
	v_cvt_f32_f16_sdwa v45, v36 dst_sel:DWORD dst_unused:UNUSED_PAD src0_sel:WORD_1
	v_cvt_f32_f16_sdwa v41, v32 dst_sel:DWORD dst_unused:UNUSED_PAD src0_sel:WORD_1
	v_cvt_f32_f16_e32 v36, v37
	v_cvt_f32_f16_sdwa v37, v37 dst_sel:DWORD dst_unused:UNUSED_PAD src0_sel:WORD_1
	v_pk_mul_f32 v[44:45], v[152:153], v[44:45] op_sel_hi:[0,1]
	v_pk_fma_f32 v[42:43], v[150:151], v[42:43], v[44:45] op_sel_hi:[0,1,1]
	v_pk_mul_f32 v[40:41], v[42:43], v[40:41]
	v_mov_b32_e32 v42, v20
	v_cvt_pk_f16_f32 v32, v40, v41
	v_cvt_f32_f16_e32 v40, v33
	v_cvt_f32_f16_sdwa v41, v33 dst_sel:DWORD dst_unused:UNUSED_PAD src0_sel:WORD_1
	v_mov_b32_e32 v43, v16
	v_pk_mul_f32 v[36:37], v[152:153], v[36:37] op_sel_hi:[0,1]
	v_pk_fma_f32 v[36:37], v[150:151], v[42:43], v[36:37] op_sel_hi:[0,1,1]
	v_cvt_f32_f16_e32 v42, v38
	v_cvt_f32_f16_sdwa v43, v38 dst_sel:DWORD dst_unused:UNUSED_PAD src0_sel:WORD_1
	v_pk_mul_f32 v[36:37], v[36:37], v[40:41]
	v_mov_b32_e32 v40, v12
	v_cvt_pk_f16_f32 v33, v36, v37
	v_cvt_f32_f16_e32 v36, v34
	v_cvt_f32_f16_sdwa v37, v34 dst_sel:DWORD dst_unused:UNUSED_PAD src0_sel:WORD_1
	v_mov_b32_e32 v41, v8
	v_pk_mul_f32 v[42:43], v[152:153], v[42:43] op_sel_hi:[0,1]
	v_pk_fma_f32 v[40:41], v[150:151], v[40:41], v[42:43] op_sel_hi:[0,1,1]
	v_cvt_f32_f16_e32 v38, v39
	v_cvt_f32_f16_sdwa v39, v39 dst_sel:DWORD dst_unused:UNUSED_PAD src0_sel:WORD_1
	v_pk_mul_f32 v[36:37], v[40:41], v[36:37]
	v_mov_b32_e32 v40, v4
	v_cvt_pk_f16_f32 v34, v36, v37
	v_cvt_f32_f16_e32 v36, v35
	v_cvt_f32_f16_sdwa v37, v35 dst_sel:DWORD dst_unused:UNUSED_PAD src0_sel:WORD_1
	v_mov_b32_e32 v41, v0
	v_pk_mul_f32 v[38:39], v[152:153], v[38:39] op_sel_hi:[0,1]
	v_pk_fma_f32 v[38:39], v[150:151], v[40:41], v[38:39] op_sel_hi:[0,1,1]
	v_pk_mul_f32 v[36:37], v[38:39], v[36:37]
	v_mov_b32_e32 v16, v21
	v_cvt_pk_f16_f32 v35, v36, v37
	global_store_dwordx4 v[130:131], v[32:35], off offset:768
	global_load_dwordx4 v[32:35], v[134:135], off offset:784
	s_nop 0
	global_load_dwordx4 v[36:39], v[132:133], off offset:784
	v_mov_b32_e32 v8, v13
	v_mov_b32_e32 v0, v5
	s_waitcnt vmcnt(1)
	v_cvt_f32_f16_e32 v40, v32
	s_waitcnt vmcnt(0)
	v_cvt_f32_f16_e32 v28, v36
	v_cvt_f32_f16_sdwa v29, v36 dst_sel:DWORD dst_unused:UNUSED_PAD src0_sel:WORD_1
	v_cvt_f32_f16_sdwa v41, v32 dst_sel:DWORD dst_unused:UNUSED_PAD src0_sel:WORD_1
	v_cvt_f32_f16_e32 v20, v37
	v_cvt_f32_f16_sdwa v21, v37 dst_sel:DWORD dst_unused:UNUSED_PAD src0_sel:WORD_1
	v_pk_mul_f32 v[28:29], v[152:153], v[28:29] op_sel_hi:[0,1]
	v_pk_fma_f32 v[24:25], v[150:151], v[24:25], v[28:29] op_sel_hi:[0,1,1]
	v_pk_mul_f32 v[24:25], v[24:25], v[40:41]
	v_pk_mul_f32 v[20:21], v[152:153], v[20:21] op_sel_hi:[0,1]
	v_cvt_pk_f16_f32 v32, v24, v25
	v_cvt_f32_f16_e32 v24, v33
	v_cvt_f32_f16_sdwa v25, v33 dst_sel:DWORD dst_unused:UNUSED_PAD src0_sel:WORD_1
	v_pk_fma_f32 v[16:17], v[150:151], v[16:17], v[20:21] op_sel_hi:[0,1,1]
	v_cvt_f32_f16_e32 v12, v38
	v_cvt_f32_f16_sdwa v13, v38 dst_sel:DWORD dst_unused:UNUSED_PAD src0_sel:WORD_1
	v_pk_mul_f32 v[16:17], v[16:17], v[24:25]
	v_cvt_f32_f16_e32 v4, v39
	v_cvt_pk_f16_f32 v33, v16, v17
	v_cvt_f32_f16_e32 v16, v34
	v_cvt_f32_f16_sdwa v17, v34 dst_sel:DWORD dst_unused:UNUSED_PAD src0_sel:WORD_1
	v_pk_mul_f32 v[12:13], v[152:153], v[12:13] op_sel_hi:[0,1]
	v_pk_fma_f32 v[8:9], v[150:151], v[8:9], v[12:13] op_sel_hi:[0,1,1]
	v_cvt_f32_f16_sdwa v5, v39 dst_sel:DWORD dst_unused:UNUSED_PAD src0_sel:WORD_1
	v_pk_mul_f32 v[8:9], v[8:9], v[16:17]
	v_pk_mul_f32 v[4:5], v[152:153], v[4:5] op_sel_hi:[0,1]
	v_cvt_pk_f16_f32 v34, v8, v9
	v_cvt_f32_f16_e32 v8, v35
	v_cvt_f32_f16_sdwa v9, v35 dst_sel:DWORD dst_unused:UNUSED_PAD src0_sel:WORD_1
	v_pk_fma_f32 v[0:1], v[150:151], v[0:1], v[4:5] op_sel_hi:[0,1,1]
	v_mov_b32_e32 v4, v30
	v_mov_b32_e32 v5, v26
	v_pk_mul_f32 v[0:1], v[0:1], v[8:9]
	v_mov_b32_e32 v26, v31
	v_cvt_pk_f16_f32 v35, v0, v1
	global_store_dwordx4 v[130:131], v[32:35], off offset:784
	global_load_dwordx4 v[32:35], v[134:135], off offset:800
	s_nop 0
	global_load_dwordx4 v[36:39], v[132:133], off offset:800
	s_waitcnt vmcnt(1)
; template <int MODE, int TB>
; DI void toeplitz_task(const Params& P, int layer, int set, int cg, int chunk, char* smem) {
;     ...
;       for (int v = 0; v < 4; ++v) {
;         const int t = t0 + 8 * v;
;         if (MODE == 0) {
;           const half8 x1 = *(const half8*)(hT + (size_t)(bb * 2048 + 512 + c) * L + t);
;           const half8 uu = *(const half8*)(Urow + t);
;           half8 o;
; #pragma unroll
;           for (int r = 0; r < 8; ++r) o[r] = (h16)((float)x1[r] * (acc[ta][r][v] * invs + (float)uu[r] * bias));
;           *(half8*)(z1T + (size_t)(bb * 512 + c) * L + t) = o;
;     ...
;   __syncthreads();
	v_cvt_f32_f16_e32 v0, v32
	s_waitcnt vmcnt(0)
	v_cvt_f32_f16_e32 v8, v36
	v_cvt_f32_f16_sdwa v9, v36 dst_sel:DWORD dst_unused:UNUSED_PAD src0_sel:WORD_1
	v_cvt_f32_f16_sdwa v1, v32 dst_sel:DWORD dst_unused:UNUSED_PAD src0_sel:WORD_1
	v_pk_mul_f32 v[8:9], v[152:153], v[8:9] op_sel_hi:[0,1]
	v_pk_fma_f32 v[4:5], v[150:151], v[4:5], v[8:9] op_sel_hi:[0,1,1]
	v_cvt_f32_f16_e32 v8, v37
	v_cvt_f32_f16_sdwa v9, v37 dst_sel:DWORD dst_unused:UNUSED_PAD src0_sel:WORD_1
	v_pk_mul_f32 v[0:1], v[4:5], v[0:1]
	v_mov_b32_e32 v4, v22
	v_cvt_pk_f16_f32 v32, v0, v1
	v_cvt_f32_f16_e32 v0, v33
	v_cvt_f32_f16_sdwa v1, v33 dst_sel:DWORD dst_unused:UNUSED_PAD src0_sel:WORD_1
	v_mov_b32_e32 v5, v18
	v_pk_mul_f32 v[8:9], v[152:153], v[8:9] op_sel_hi:[0,1]
	v_pk_fma_f32 v[4:5], v[150:151], v[4:5], v[8:9] op_sel_hi:[0,1,1]
	v_cvt_f32_f16_e32 v8, v38
	v_cvt_f32_f16_sdwa v9, v38 dst_sel:DWORD dst_unused:UNUSED_PAD src0_sel:WORD_1
	v_pk_mul_f32 v[0:1], v[4:5], v[0:1]
	v_mov_b32_e32 v4, v14
	v_cvt_pk_f16_f32 v33, v0, v1
	v_cvt_f32_f16_e32 v0, v34
	v_cvt_f32_f16_sdwa v1, v34 dst_sel:DWORD dst_unused:UNUSED_PAD src0_sel:WORD_1
	v_mov_b32_e32 v5, v10
	v_pk_mul_f32 v[8:9], v[152:153], v[8:9] op_sel_hi:[0,1]
	v_pk_fma_f32 v[4:5], v[150:151], v[4:5], v[8:9] op_sel_hi:[0,1,1]
	v_cvt_f32_f16_e32 v8, v39
	v_cvt_f32_f16_sdwa v9, v39 dst_sel:DWORD dst_unused:UNUSED_PAD src0_sel:WORD_1
	v_pk_mul_f32 v[0:1], v[4:5], v[0:1]
	v_mov_b32_e32 v4, v6
	v_cvt_pk_f16_f32 v34, v0, v1
	v_cvt_f32_f16_e32 v0, v35
	v_cvt_f32_f16_sdwa v1, v35 dst_sel:DWORD dst_unused:UNUSED_PAD src0_sel:WORD_1
	v_mov_b32_e32 v5, v2
	v_pk_mul_f32 v[8:9], v[152:153], v[8:9] op_sel_hi:[0,1]
	v_pk_fma_f32 v[4:5], v[150:151], v[4:5], v[8:9] op_sel_hi:[0,1,1]
	v_pk_mul_f32 v[0:1], v[4:5], v[0:1]
	v_mov_b32_e32 v18, v23
	v_cvt_pk_f16_f32 v35, v0, v1
	global_store_dwordx4 v[130:131], v[32:35], off offset:800
	global_load_dwordx4 v[32:35], v[134:135], off offset:816
	s_nop 0
	global_load_dwordx4 v[36:39], v[132:133], off offset:816
	v_mov_b32_e32 v10, v15
	v_mov_b32_e32 v2, v7
	s_waitcnt vmcnt(1)
	v_cvt_f32_f16_e32 v0, v32
	s_waitcnt vmcnt(0)
	v_cvt_f32_f16_e32 v4, v36
	v_cvt_f32_f16_sdwa v5, v36 dst_sel:DWORD dst_unused:UNUSED_PAD src0_sel:WORD_1
	v_cvt_f32_f16_sdwa v1, v32 dst_sel:DWORD dst_unused:UNUSED_PAD src0_sel:WORD_1
	v_cvt_f32_f16_e32 v8, v37
	v_cvt_f32_f16_sdwa v9, v37 dst_sel:DWORD dst_unused:UNUSED_PAD src0_sel:WORD_1
	v_pk_mul_f32 v[4:5], v[152:153], v[4:5] op_sel_hi:[0,1]
	v_pk_fma_f32 v[4:5], v[150:151], v[26:27], v[4:5] op_sel_hi:[0,1,1]
	v_pk_mul_f32 v[0:1], v[4:5], v[0:1]
	v_pk_mul_f32 v[8:9], v[152:153], v[8:9] op_sel_hi:[0,1]
	v_cvt_pk_f16_f32 v4, v0, v1
	v_cvt_f32_f16_e32 v0, v33
	v_cvt_f32_f16_sdwa v1, v33 dst_sel:DWORD dst_unused:UNUSED_PAD src0_sel:WORD_1
	v_pk_fma_f32 v[8:9], v[150:151], v[18:19], v[8:9] op_sel_hi:[0,1,1]
	v_pk_mul_f32 v[0:1], v[8:9], v[0:1]
	v_cvt_f32_f16_e32 v8, v38
	v_cvt_f32_f16_sdwa v9, v38 dst_sel:DWORD dst_unused:UNUSED_PAD src0_sel:WORD_1
	v_cvt_pk_f16_f32 v5, v0, v1
	v_cvt_f32_f16_e32 v0, v34
	v_cvt_f32_f16_sdwa v1, v34 dst_sel:DWORD dst_unused:UNUSED_PAD src0_sel:WORD_1
	v_pk_mul_f32 v[8:9], v[152:153], v[8:9] op_sel_hi:[0,1]
	v_pk_fma_f32 v[8:9], v[150:151], v[10:11], v[8:9] op_sel_hi:[0,1,1]
	v_pk_mul_f32 v[0:1], v[8:9], v[0:1]
	v_cvt_f32_f16_e32 v8, v39
	v_cvt_f32_f16_sdwa v9, v39 dst_sel:DWORD dst_unused:UNUSED_PAD src0_sel:WORD_1
	v_cvt_pk_f16_f32 v6, v0, v1
	v_cvt_f32_f16_e32 v0, v35
	v_cvt_f32_f16_sdwa v1, v35 dst_sel:DWORD dst_unused:UNUSED_PAD src0_sel:WORD_1
	v_pk_mul_f32 v[8:9], v[152:153], v[8:9] op_sel_hi:[0,1]
	v_pk_fma_f32 v[2:3], v[150:151], v[2:3], v[8:9] op_sel_hi:[0,1,1]
	v_pk_mul_f32 v[0:1], v[2:3], v[0:1]
	s_nop 0
	v_cvt_pk_f16_f32 v7, v0, v1
	global_store_dwordx4 v[130:131], v[4:7], off offset:816
	s_barrier
	s_branch .LBB0_412
